# MoE weight conversion items: the read-once f32 weight loads marked nt (streaming) so they do not displace the GEMM working set in L2
# speedup vs baseline: 1.0059x; 1.0054x over previous
.LBB0_128:
	s_ashr_i32 s4, s45, 10
	s_bfe_u32 s47, s45, 0x10009
	s_and_b32 s46, s10, 0x3e0
	s_cmp_eq_u32 s47, 0
	s_cselect_b32 s5, s11, 0xd0
	s_add_u32 s48, s0, s5
	s_addc_u32 s49, s1, 0
	s_load_dwordx2 s[48:49], s[48:49], 0x0
	s_ashr_i32 s5, s4, 31
	s_lshl_b64 s[50:51], s[4:5], 22
	v_mov_b32_e32 v2, v1
	s_waitcnt lgkmcnt(0)
	s_add_u32 s33, s48, s50
	s_addc_u32 s48, s49, s51
	s_lshl_b64 s[4:5], s[4:5], 21
	s_add_u32 s49, s7, s4
	s_addc_u32 s50, s8, s5
	s_lshl_b32 s4, s10, 1
	s_lshl_b32 s5, s47, 7
	s_and_b32 s4, s4, 0x700
	s_and_b32 s47, s10, 0x60
	s_or_b32 s4, s4, s5
	v_ashrrev_i32_e32 v12, 5, v2
	v_lshlrev_b32_e32 v13, 2, v2
	s_and_b32 s51, s9, 0x3c0
	s_lshl_b32 s46, s46, 2
	s_or_b32 s5, s4, s47
	v_lshlrev_b32_e32 v17, 3, v2
	v_ashrrev_i32_e32 v14, 3, v2
	v_and_b32_e32 v2, 0x7c, v13
	v_mul_lo_u32 v13, v12, s44
	v_add_u32_e32 v12, s51, v12
	s_add_u32 s4, s33, s46
	v_lshlrev_b32_e32 v84, 2, v14
	v_add3_u32 v85, s3, v2, v13
	v_ashrrev_i32_e32 v13, 31, v12
	v_add_u32_e32 v14, s5, v14
	s_addc_u32 s5, s48, 0
	v_lshlrev_b64 v[12:13], 12, v[12:13]
	v_lshl_add_u64 v[22:23], s[4:5], 0, v[2:3]
	v_lshl_add_u64 v[12:13], v[22:23], 0, v[12:13]
	v_add_co_u32_e32 v22, vcc, s6, v12
	v_add_u32_e32 v86, 0x400, v85
	s_nop 0
	v_addc_co_u32_e32 v23, vcc, 0, v13, vcc
	v_add_co_u32_e32 v24, vcc, s12, v12
	v_add_u32_e32 v87, 0x800, v85
	s_nop 0
	v_addc_co_u32_e32 v25, vcc, 0, v13, vcc
	v_add_co_u32_e32 v26, vcc, s13, v12
	v_add_u32_e32 v88, 0xc00, v85
	s_nop 0
	v_addc_co_u32_e32 v27, vcc, 0, v13, vcc
	v_add_co_u32_e32 v28, vcc, s14, v12
	v_add_u32_e32 v89, 0x1000, v85
	s_nop 0
	v_addc_co_u32_e32 v29, vcc, 0, v13, vcc
	v_add_co_u32_e32 v30, vcc, s15, v12
	v_add_u32_e32 v90, 0x1400, v85
	s_nop 0
	v_addc_co_u32_e32 v31, vcc, 0, v13, vcc
	v_add_co_u32_e32 v32, vcc, s16, v12
	v_add_u32_e32 v91, 0x1800, v85
	s_nop 0
	v_addc_co_u32_e32 v33, vcc, 0, v13, vcc
	v_add_co_u32_e32 v34, vcc, s17, v12
	v_add_u32_e32 v92, 0x1c00, v85
	s_nop 0
	v_addc_co_u32_e32 v35, vcc, 0, v13, vcc
	v_add_co_u32_e32 v36, vcc, s18, v12
	v_add_u32_e32 v16, 8, v14
	s_nop 0
	v_addc_co_u32_e32 v37, vcc, 0, v13, vcc
	v_add_co_u32_e32 v38, vcc, s19, v12
	v_add_u32_e32 v18, 16, v14
	s_nop 0
	v_addc_co_u32_e32 v39, vcc, 0, v13, vcc
	v_add_co_u32_e32 v40, vcc, s20, v12
	v_add_u32_e32 v20, 24, v14
	s_nop 0
	v_addc_co_u32_e32 v41, vcc, 0, v13, vcc
	v_add_co_u32_e32 v42, vcc, s21, v12
	v_and_b32_e32 v2, 56, v17
	s_nop 0
	v_addc_co_u32_e32 v43, vcc, 0, v13, vcc
	v_add_co_u32_e32 v44, vcc, s22, v12
	s_add_u32 s4, s49, s51
	s_nop 0
	v_addc_co_u32_e32 v45, vcc, 0, v13, vcc
	v_add_co_u32_e32 v46, vcc, s23, v12
	v_ashrrev_i32_e32 v15, 31, v14
	s_nop 0
	v_addc_co_u32_e32 v47, vcc, 0, v13, vcc
	v_add_co_u32_e32 v48, vcc, s24, v12
	v_ashrrev_i32_e32 v17, 31, v16
	s_nop 0
	v_addc_co_u32_e32 v49, vcc, 0, v13, vcc
	v_add_co_u32_e32 v50, vcc, s25, v12
	v_ashrrev_i32_e32 v19, 31, v18
	s_nop 0
	v_addc_co_u32_e32 v51, vcc, 0, v13, vcc
	v_add_co_u32_e32 v52, vcc, s26, v12
	v_ashrrev_i32_e32 v21, 31, v20
	s_nop 0
	v_addc_co_u32_e32 v53, vcc, 0, v13, vcc
	v_add_co_u32_e32 v54, vcc, s27, v12
	v_mul_u32_u24_e32 v93, 0x84, v2
	s_nop 0
	v_addc_co_u32_e32 v55, vcc, 0, v13, vcc
	v_add_co_u32_e32 v56, vcc, s28, v12
	s_addc_u32 s5, s50, 0
	s_nop 0
	v_addc_co_u32_e32 v57, vcc, 0, v13, vcc
	v_add_co_u32_e32 v58, vcc, s29, v12
	v_lshlrev_b64 v[14:15], 10, v[14:15]
	s_nop 0
	v_addc_co_u32_e32 v59, vcc, 0, v13, vcc
	v_add_co_u32_e32 v60, vcc, s30, v12
	v_mov_b32_e32 v4, v3
	s_nop 0
	v_addc_co_u32_e32 v61, vcc, 0, v13, vcc
	v_add_co_u32_e32 v62, vcc, s31, v12
	v_mov_b32_e32 v5, v3
	s_nop 0
	v_addc_co_u32_e32 v63, vcc, 0, v13, vcc
	v_add_co_u32_e32 v64, vcc, s34, v12
	v_mov_b32_e32 v6, v3
	s_nop 0
	v_addc_co_u32_e32 v65, vcc, 0, v13, vcc
	v_add_co_u32_e32 v66, vcc, s35, v12
	v_mov_b32_e32 v7, v3
	s_nop 0
	v_addc_co_u32_e32 v67, vcc, 0, v13, vcc
	v_add_co_u32_e32 v68, vcc, s36, v12
	v_mov_b32_e32 v8, v3
	s_nop 0
	v_addc_co_u32_e32 v69, vcc, 0, v13, vcc
	v_add_co_u32_e32 v70, vcc, s37, v12
	v_mov_b32_e32 v9, v3
	s_nop 0
	v_addc_co_u32_e32 v71, vcc, 0, v13, vcc
	v_add_co_u32_e32 v72, vcc, s38, v12
	v_mov_b32_e32 v10, v3
	s_nop 0
	v_addc_co_u32_e32 v73, vcc, 0, v13, vcc
	v_add_co_u32_e32 v74, vcc, s39, v12
	v_mov_b32_e32 v11, v3
	s_nop 0
	v_addc_co_u32_e32 v75, vcc, 0, v13, vcc
	v_add_co_u32_e32 v76, vcc, s40, v12
	s_add_i32 s33, s45, 0x800
	s_nop 0
	v_addc_co_u32_e32 v77, vcc, 0, v13, vcc
	v_add_co_u32_e32 v78, vcc, s41, v12
	s_addk_i32 s9, 0x1000
	s_nop 0
	v_addc_co_u32_e32 v79, vcc, 0, v13, vcc
	v_add_co_u32_e32 v80, vcc, s42, v12
	s_add_i32 s10, s10, 0x10000
	s_nop 0
	v_addc_co_u32_e32 v81, vcc, 0, v13, vcc
	v_add_co_u32_e32 v82, vcc, s43, v12
	s_cmpk_lt_i32 s45, 0x1800
	s_nop 0
	v_addc_co_u32_e32 v83, vcc, 0, v13, vcc
	global_load_dword v94, v[12:13], off nt
	s_nop 0
	global_load_dword v22, v[22:23], off nt
	s_nop 0
	global_load_dword v23, v[24:25], off nt
	s_nop 0
	global_load_dword v24, v[26:27], off nt
	global_load_dword v25, v[28:29], off nt
	s_nop 0
	global_load_dword v26, v[30:31], off nt
	global_load_dword v27, v[32:33], off nt
	global_load_dword v28, v[34:35], off nt
	global_load_dword v29, v[36:37], off nt
	s_nop 0
	global_load_dword v30, v[38:39], off nt
	global_load_dword v31, v[40:41], off nt
	global_load_dword v32, v[42:43], off nt
	global_load_dword v33, v[44:45], off nt
	global_load_dword v34, v[46:47], off nt
	global_load_dword v35, v[48:49], off nt
	global_load_dword v36, v[50:51], off nt
	global_load_dword v37, v[52:53], off nt
	global_load_dword v38, v[54:55], off nt
	global_load_dword v39, v[56:57], off nt
	global_load_dword v40, v[58:59], off nt
	global_load_dword v41, v[60:61], off nt
	global_load_dword v42, v[62:63], off nt
	global_load_dword v43, v[64:65], off nt
	global_load_dword v44, v[66:67], off nt
	global_load_dword v45, v[68:69], off nt
	global_load_dword v46, v[70:71], off nt
	global_load_dword v47, v[72:73], off nt
	global_load_dword v48, v[74:75], off nt
	global_load_dword v49, v[76:77], off nt
	global_load_dword v50, v[78:79], off nt
	global_load_dword v51, v[80:81], off nt
	global_load_dword v52, v[82:83], off nt
	s_waitcnt vmcnt(30)
	ds_write2_b32 v85, v94, v22 offset1:66
	s_waitcnt vmcnt(28)
	ds_write2_b32 v85, v23, v24 offset0:132 offset1:198
	s_waitcnt vmcnt(26)
	ds_write2_b32 v86, v25, v26 offset0:8 offset1:74
	s_waitcnt vmcnt(24)
	ds_write2_b32 v86, v27, v28 offset0:140 offset1:206
	s_waitcnt vmcnt(22)
	ds_write2_b32 v87, v29, v30 offset0:16 offset1:82
	s_waitcnt vmcnt(20)
	ds_write2_b32 v87, v31, v32 offset0:148 offset1:214
	s_waitcnt vmcnt(18)
	ds_write2_b32 v88, v33, v34 offset0:24 offset1:90
	s_waitcnt vmcnt(16)
	ds_write2_b32 v88, v35, v36 offset0:156 offset1:222
	s_waitcnt vmcnt(14)
	ds_write2_b32 v89, v37, v38 offset0:32 offset1:98
	s_waitcnt vmcnt(12)
	ds_write2_b32 v89, v39, v40 offset0:164 offset1:230
	s_waitcnt vmcnt(10)
	ds_write2_b32 v90, v41, v42 offset0:40 offset1:106
	s_waitcnt vmcnt(8)
	ds_write2_b32 v90, v43, v44 offset0:172 offset1:238
	s_waitcnt vmcnt(6)
	ds_write2_b32 v91, v45, v46 offset0:48 offset1:114
	s_waitcnt vmcnt(4)
	ds_write2_b32 v91, v47, v48 offset0:180 offset1:246
	s_waitcnt vmcnt(2)
	ds_write2_b32 v92, v49, v50 offset0:56 offset1:122
	s_waitcnt vmcnt(0)
	ds_write2_b32 v92, v51, v52 offset0:188 offset1:254
	s_waitcnt lgkmcnt(0)
	v_lshlrev_b64 v[12:13], 10, v[16:17]
	v_lshlrev_b64 v[16:17], 10, v[18:19]
	v_lshlrev_b64 v[18:19], 10, v[20:21]
	v_lshl_add_u64 v[20:21], s[4:5], 0, v[2:3]
	v_add3_u32 v2, s3, v93, v84
	v_lshl_add_u64 v[14:15], v[20:21], 0, v[14:15]
	v_lshl_add_u64 v[12:13], v[20:21], 0, v[12:13]
	v_lshl_add_u64 v[16:17], v[20:21], 0, v[16:17]
	v_lshl_add_u64 v[18:19], v[20:21], 0, v[18:19]
	ds_read2_b32 v[20:21], v2 offset1:8
	ds_read2_b32 v[22:23], v2 offset0:33 offset1:41
	ds_read2_b32 v[24:25], v2 offset0:66 offset1:74
	ds_read2_b32 v[26:27], v2 offset0:99 offset1:107
	ds_read2_b32 v[28:29], v2 offset0:132 offset1:140
	ds_read2_b32 v[30:31], v2 offset0:165 offset1:173
	ds_read2_b32 v[32:33], v2 offset0:198 offset1:206
	ds_read2_b32 v[34:35], v2 offset0:231 offset1:239
	ds_read2_b32 v[36:37], v2 offset0:16 offset1:24
	ds_read2_b32 v[38:39], v2 offset0:49 offset1:57
	ds_read2_b32 v[40:41], v2 offset0:82 offset1:90
	ds_read2_b32 v[42:43], v2 offset0:115 offset1:123
	ds_read2_b32 v[44:45], v2 offset0:148 offset1:156
	ds_read2_b32 v[46:47], v2 offset0:181 offset1:189
	ds_read2_b32 v[48:49], v2 offset0:214 offset1:222
	ds_read2_b32 v[50:51], v2 offset0:247 offset1:255
	s_waitcnt lgkmcnt(14)
	v_mul_f32_e32 v2, 0x42000000, v20
	v_mul_f32_e32 v20, 0x42000000, v22
	s_waitcnt lgkmcnt(13)
	v_mul_f32_e32 v22, 0x42000000, v24
	s_waitcnt lgkmcnt(12)
	v_mul_f32_e32 v24, 0x42000000, v26
	s_waitcnt lgkmcnt(11)
	v_mul_f32_e32 v26, 0x42000000, v28
	s_waitcnt lgkmcnt(10)
	v_mul_f32_e32 v28, 0x42000000, v30
	v_mul_f32_e32 v21, 0x42000000, v21
	v_mul_f32_e32 v23, 0x42000000, v23
	v_mul_f32_e32 v29, 0x42000000, v29
	v_mul_f32_e32 v31, 0x42000000, v31
	v_cvt_pk_fp8_f32 v4, v2, v20
	v_cvt_pk_fp8_f32 v5, v26, v28
	s_waitcnt lgkmcnt(9)
	v_mul_f32_e32 v30, 0x42000000, v32
	s_waitcnt lgkmcnt(8)
	v_mul_f32_e32 v32, 0x42000000, v34
	v_mul_f32_e32 v34, 0x42000000, v35
	s_waitcnt lgkmcnt(7)
	v_mul_f32_e32 v35, 0x42000000, v36
	s_waitcnt lgkmcnt(6)
	v_mul_f32_e32 v36, 0x42000000, v38
	s_waitcnt lgkmcnt(5)
	v_mul_f32_e32 v38, 0x42000000, v40
	s_waitcnt lgkmcnt(4)
	v_mul_f32_e32 v40, 0x42000000, v42
	s_waitcnt lgkmcnt(3)
	v_mul_f32_e32 v42, 0x42000000, v44
	s_waitcnt lgkmcnt(2)
	v_mul_f32_e32 v44, 0x42000000, v46
	v_cvt_pk_fp8_f32 v6, v21, v23
	v_cvt_pk_fp8_f32 v7, v29, v31
	v_mul_f32_e32 v37, 0x42000000, v37
	v_mul_f32_e32 v39, 0x42000000, v39
	v_mul_f32_e32 v45, 0x42000000, v45
	v_mul_f32_e32 v47, 0x42000000, v47
	v_cvt_pk_fp8_f32 v8, v35, v36
	v_cvt_pk_fp8_f32 v9, v42, v44
	v_cvt_pk_fp8_f32 v10, v37, v39
	v_cvt_pk_fp8_f32 v11, v45, v47
	v_mul_f32_e32 v25, 0x42000000, v25
	v_mul_f32_e32 v27, 0x42000000, v27
	v_mul_f32_e32 v33, 0x42000000, v33
	v_cvt_pk_fp8_f32 v4, v22, v24 op_sel:[0,0,1]
	v_cvt_pk_fp8_f32 v5, v30, v32 op_sel:[0,0,1]
	s_waitcnt lgkmcnt(1)
	v_mul_f32_e32 v46, 0x42000000, v48
	s_waitcnt lgkmcnt(0)
	v_mul_f32_e32 v48, 0x42000000, v50
	v_cvt_pk_fp8_f32 v6, v25, v27 op_sel:[0,0,1]
	v_cvt_pk_fp8_f32 v7, v33, v34 op_sel:[0,0,1]
	v_mul_f32_e32 v41, 0x42000000, v41
	v_mul_f32_e32 v43, 0x42000000, v43
	v_mul_f32_e32 v49, 0x42000000, v49
	v_mul_f32_e32 v50, 0x42000000, v51
	v_cvt_pk_fp8_f32 v8, v38, v40 op_sel:[0,0,1]
	v_cvt_pk_fp8_f32 v9, v46, v48 op_sel:[0,0,1]
	v_cvt_pk_fp8_f32 v10, v41, v43 op_sel:[0,0,1]
	v_cvt_pk_fp8_f32 v11, v49, v50 op_sel:[0,0,1]
	global_store_dwordx2 v[14:15], v[4:5], off
	global_store_dwordx2 v[12:13], v[6:7], off
	global_store_dwordx2 v[16:17], v[8:9], off
	global_store_dwordx2 v[18:19], v[10:11], off
	s_waitcnt lgkmcnt(0)
	s_mov_b32 s45, s33
	s_cbranch_scc1 .LBB0_128

.LBB0_284:
	s_addk_i32 s9, 0x500
	s_and_b32 s4, s11, 0x3e0
	s_ashr_i32 s50, s9, 10
	s_bfe_u32 s5, s9, 0x10009
	s_cmp_eq_u32 s5, 0
	s_cselect_b32 s33, s12, 0xd0
	s_add_u32 s58, s0, s33
	s_addc_u32 s59, s1, 0
	s_load_dwordx2 s[58:59], s[58:59], 0x0
	s_ashr_i32 s51, s50, 31
	s_lshl_b64 s[72:73], s[50:51], 22
	v_mov_b32_e32 v2, v1
	s_waitcnt lgkmcnt(0)
	s_add_u32 s33, s58, s72
	s_addc_u32 s49, s59, s73
	s_lshl_b64 s[50:51], s[50:51], 21
	s_add_u32 s50, s3, s50
	s_addc_u32 s51, s6, s51
	s_lshl_b32 s58, s11, 1
	s_lshl_b32 s5, s5, 7
	s_and_b32 s58, s58, 0x700
	s_and_b32 s59, s11, 0x60
	s_or_b32 s5, s58, s5
	v_ashrrev_i32_e32 v12, 5, v2
	v_lshlrev_b32_e32 v13, 2, v2
	s_and_b32 s57, s10, 0x3c0
	s_lshl_b32 s4, s4, 2
	s_or_b32 s5, s5, s59
	v_ashrrev_i32_e32 v14, 3, v2
	v_lshlrev_b32_e32 v17, 3, v2
	v_and_b32_e32 v2, 0x7c, v13
	v_mul_lo_u32 v13, v12, s47
	v_add_u32_e32 v12, s57, v12
	s_add_u32 s4, s33, s4
	v_lshlrev_b32_e32 v84, 2, v14
	v_add3_u32 v85, s8, v2, v13
	v_ashrrev_i32_e32 v13, 31, v12
	v_add_u32_e32 v14, s5, v14
	s_addc_u32 s5, s49, 0
	v_lshlrev_b64 v[12:13], 12, v[12:13]
	v_lshl_add_u64 v[22:23], s[4:5], 0, v[2:3]
	v_lshl_add_u64 v[12:13], v[22:23], 0, v[12:13]
	v_add_co_u32_e32 v22, vcc, s13, v12
	v_add_u32_e32 v86, 0x400, v85
	s_nop 0
	v_addc_co_u32_e32 v23, vcc, 0, v13, vcc
	v_add_co_u32_e32 v24, vcc, s14, v12
	v_add_u32_e32 v87, 0x800, v85
	s_nop 0
	v_addc_co_u32_e32 v25, vcc, 0, v13, vcc
	v_add_co_u32_e32 v26, vcc, s15, v12
	v_add_u32_e32 v88, 0xc00, v85
	s_nop 0
	v_addc_co_u32_e32 v27, vcc, 0, v13, vcc
	v_add_co_u32_e32 v28, vcc, s16, v12
	v_add_u32_e32 v89, 0x1000, v85
	s_nop 0
	v_addc_co_u32_e32 v29, vcc, 0, v13, vcc
	v_add_co_u32_e32 v30, vcc, s17, v12
	v_add_u32_e32 v90, 0x1400, v85
	s_nop 0
	v_addc_co_u32_e32 v31, vcc, 0, v13, vcc
	v_add_co_u32_e32 v32, vcc, s18, v12
	v_add_u32_e32 v91, 0x1800, v85
	s_nop 0
	v_addc_co_u32_e32 v33, vcc, 0, v13, vcc
	v_add_co_u32_e32 v34, vcc, s19, v12
	v_add_u32_e32 v92, 0x1c00, v85
	s_nop 0
	v_addc_co_u32_e32 v35, vcc, 0, v13, vcc
	v_add_co_u32_e32 v36, vcc, s7, v12
	v_add_u32_e32 v16, 8, v14
	s_nop 0
	v_addc_co_u32_e32 v37, vcc, 0, v13, vcc
	v_add_co_u32_e32 v38, vcc, s20, v12
	v_add_u32_e32 v18, 16, v14
	s_nop 0
	v_addc_co_u32_e32 v39, vcc, 0, v13, vcc
	v_add_co_u32_e32 v40, vcc, s21, v12
	v_add_u32_e32 v20, 24, v14
	s_nop 0
	v_addc_co_u32_e32 v41, vcc, 0, v13, vcc
	v_add_co_u32_e32 v42, vcc, s22, v12
	v_and_b32_e32 v2, 56, v17
	s_nop 0
	v_addc_co_u32_e32 v43, vcc, 0, v13, vcc
	v_add_co_u32_e32 v44, vcc, s23, v12
	s_add_u32 s4, s50, s57
	s_nop 0
	v_addc_co_u32_e32 v45, vcc, 0, v13, vcc
	v_add_co_u32_e32 v46, vcc, s24, v12
	v_ashrrev_i32_e32 v15, 31, v14
	s_nop 0
	v_addc_co_u32_e32 v47, vcc, 0, v13, vcc
	v_add_co_u32_e32 v48, vcc, s25, v12
	v_ashrrev_i32_e32 v17, 31, v16
	s_nop 0
	v_addc_co_u32_e32 v49, vcc, 0, v13, vcc
	v_add_co_u32_e32 v50, vcc, s26, v12
	v_ashrrev_i32_e32 v19, 31, v18
	s_nop 0
	v_addc_co_u32_e32 v51, vcc, 0, v13, vcc
	v_add_co_u32_e32 v52, vcc, s27, v12
	v_ashrrev_i32_e32 v21, 31, v20
	s_nop 0
	v_addc_co_u32_e32 v53, vcc, 0, v13, vcc
	v_add_co_u32_e32 v54, vcc, s28, v12
	v_mul_u32_u24_e32 v93, 0x84, v2
	s_nop 0
	v_addc_co_u32_e32 v55, vcc, 0, v13, vcc
	v_add_co_u32_e32 v56, vcc, s29, v12
	s_addc_u32 s5, s51, 0
	s_nop 0
	v_addc_co_u32_e32 v57, vcc, 0, v13, vcc
	v_add_co_u32_e32 v58, vcc, s30, v12
	v_lshlrev_b64 v[14:15], 10, v[14:15]
	s_nop 0
	v_addc_co_u32_e32 v59, vcc, 0, v13, vcc
	v_add_co_u32_e32 v60, vcc, s31, v12
	v_mov_b32_e32 v4, v3
	s_nop 0
	v_addc_co_u32_e32 v61, vcc, 0, v13, vcc
	v_add_co_u32_e32 v62, vcc, s34, v12
	v_mov_b32_e32 v5, v3
	s_nop 0
	v_addc_co_u32_e32 v63, vcc, 0, v13, vcc
	v_add_co_u32_e32 v64, vcc, s35, v12
	v_mov_b32_e32 v6, v3
	s_nop 0
	v_addc_co_u32_e32 v65, vcc, 0, v13, vcc
	v_add_co_u32_e32 v66, vcc, s36, v12
	v_mov_b32_e32 v7, v3
	s_nop 0
	v_addc_co_u32_e32 v67, vcc, 0, v13, vcc
	v_add_co_u32_e32 v68, vcc, s37, v12
	v_mov_b32_e32 v8, v3
	s_nop 0
	v_addc_co_u32_e32 v69, vcc, 0, v13, vcc
	v_add_co_u32_e32 v70, vcc, s38, v12
	v_mov_b32_e32 v9, v3
	s_nop 0
	v_addc_co_u32_e32 v71, vcc, 0, v13, vcc
	v_add_co_u32_e32 v72, vcc, s39, v12
	v_mov_b32_e32 v10, v3
	s_nop 0
	v_addc_co_u32_e32 v73, vcc, 0, v13, vcc
	v_add_co_u32_e32 v74, vcc, s41, v12
	v_mov_b32_e32 v11, v3
	s_nop 0
	v_addc_co_u32_e32 v75, vcc, 0, v13, vcc
	v_add_co_u32_e32 v76, vcc, s42, v12
	s_addk_i32 s10, 0xa00
	s_nop 0
	v_addc_co_u32_e32 v77, vcc, 0, v13, vcc
	v_add_co_u32_e32 v78, vcc, s43, v12
	s_add_i32 s11, s11, 0xa000
	s_nop 0
	v_addc_co_u32_e32 v79, vcc, 0, v13, vcc
	v_add_co_u32_e32 v80, vcc, s45, v12
	s_cmpk_lt_i32 s9, 0x3b00
	s_nop 0
	v_addc_co_u32_e32 v81, vcc, 0, v13, vcc
	v_add_co_u32_e32 v82, vcc, s46, v12
	s_nop 1
	v_addc_co_u32_e32 v83, vcc, 0, v13, vcc
	global_load_dword v94, v[12:13], off nt
	s_nop 0
	global_load_dword v22, v[22:23], off nt
	s_nop 0
	global_load_dword v23, v[24:25], off nt
	s_nop 0
	global_load_dword v24, v[26:27], off nt
	global_load_dword v25, v[28:29], off nt
	s_nop 0
	global_load_dword v26, v[30:31], off nt
	global_load_dword v27, v[32:33], off nt
	global_load_dword v28, v[34:35], off nt
	global_load_dword v29, v[36:37], off nt
	s_nop 0
	global_load_dword v30, v[38:39], off nt
	global_load_dword v31, v[40:41], off nt
	global_load_dword v32, v[42:43], off nt
	global_load_dword v33, v[44:45], off nt
	global_load_dword v34, v[46:47], off nt
	global_load_dword v35, v[48:49], off nt
	global_load_dword v36, v[50:51], off nt
	global_load_dword v37, v[52:53], off nt
	global_load_dword v38, v[54:55], off nt
	global_load_dword v39, v[56:57], off nt
	global_load_dword v40, v[58:59], off nt
	global_load_dword v41, v[60:61], off nt
	global_load_dword v42, v[62:63], off nt
	global_load_dword v43, v[64:65], off nt
	global_load_dword v44, v[66:67], off nt
	global_load_dword v45, v[68:69], off nt
	global_load_dword v46, v[70:71], off nt
	global_load_dword v47, v[72:73], off nt
	global_load_dword v48, v[74:75], off nt
	global_load_dword v49, v[76:77], off nt
	global_load_dword v50, v[78:79], off nt
	global_load_dword v51, v[80:81], off nt
	global_load_dword v52, v[82:83], off nt
	s_waitcnt vmcnt(30)
	ds_write2_b32 v85, v94, v22 offset1:66
	s_waitcnt vmcnt(28)
	ds_write2_b32 v85, v23, v24 offset0:132 offset1:198
	s_waitcnt vmcnt(26)
	ds_write2_b32 v86, v25, v26 offset0:8 offset1:74
	s_waitcnt vmcnt(24)
	ds_write2_b32 v86, v27, v28 offset0:140 offset1:206
	s_waitcnt vmcnt(22)
	ds_write2_b32 v87, v29, v30 offset0:16 offset1:82
	s_waitcnt vmcnt(20)
	ds_write2_b32 v87, v31, v32 offset0:148 offset1:214
	s_waitcnt vmcnt(18)
	ds_write2_b32 v88, v33, v34 offset0:24 offset1:90
	s_waitcnt vmcnt(16)
	ds_write2_b32 v88, v35, v36 offset0:156 offset1:222
	s_waitcnt vmcnt(14)
	ds_write2_b32 v89, v37, v38 offset0:32 offset1:98
	s_waitcnt vmcnt(12)
	ds_write2_b32 v89, v39, v40 offset0:164 offset1:230
	s_waitcnt vmcnt(10)
	ds_write2_b32 v90, v41, v42 offset0:40 offset1:106
	s_waitcnt vmcnt(8)
	ds_write2_b32 v90, v43, v44 offset0:172 offset1:238
	s_waitcnt vmcnt(6)
	ds_write2_b32 v91, v45, v46 offset0:48 offset1:114
	s_waitcnt vmcnt(4)
	ds_write2_b32 v91, v47, v48 offset0:180 offset1:246
	s_waitcnt vmcnt(2)
	ds_write2_b32 v92, v49, v50 offset0:56 offset1:122
	s_waitcnt vmcnt(0)
	ds_write2_b32 v92, v51, v52 offset0:188 offset1:254
	s_waitcnt lgkmcnt(0)
	v_lshlrev_b64 v[12:13], 10, v[16:17]
	v_lshlrev_b64 v[16:17], 10, v[18:19]
	v_lshlrev_b64 v[18:19], 10, v[20:21]
	v_lshl_add_u64 v[20:21], s[4:5], 0, v[2:3]
	v_add3_u32 v2, s8, v93, v84
	v_lshl_add_u64 v[14:15], v[20:21], 0, v[14:15]
	v_lshl_add_u64 v[12:13], v[20:21], 0, v[12:13]
	v_lshl_add_u64 v[16:17], v[20:21], 0, v[16:17]
	v_lshl_add_u64 v[18:19], v[20:21], 0, v[18:19]
	ds_read2_b32 v[20:21], v2 offset1:8
	ds_read2_b32 v[22:23], v2 offset0:33 offset1:41
	ds_read2_b32 v[24:25], v2 offset0:66 offset1:74
	ds_read2_b32 v[26:27], v2 offset0:99 offset1:107
	ds_read2_b32 v[28:29], v2 offset0:132 offset1:140
	ds_read2_b32 v[30:31], v2 offset0:165 offset1:173
	ds_read2_b32 v[32:33], v2 offset0:198 offset1:206
	ds_read2_b32 v[34:35], v2 offset0:231 offset1:239
	ds_read2_b32 v[36:37], v2 offset0:16 offset1:24
	ds_read2_b32 v[38:39], v2 offset0:49 offset1:57
	ds_read2_b32 v[40:41], v2 offset0:82 offset1:90
	ds_read2_b32 v[42:43], v2 offset0:115 offset1:123
	ds_read2_b32 v[44:45], v2 offset0:148 offset1:156
	ds_read2_b32 v[46:47], v2 offset0:181 offset1:189
	ds_read2_b32 v[48:49], v2 offset0:214 offset1:222
	ds_read2_b32 v[50:51], v2 offset0:247 offset1:255
	s_waitcnt lgkmcnt(14)
	v_mul_f32_e32 v2, 0x42000000, v20
	v_mul_f32_e32 v20, 0x42000000, v22
	s_waitcnt lgkmcnt(13)
	v_mul_f32_e32 v22, 0x42000000, v24
	s_waitcnt lgkmcnt(12)
	v_mul_f32_e32 v24, 0x42000000, v26
	s_waitcnt lgkmcnt(11)
	v_mul_f32_e32 v26, 0x42000000, v28
	s_waitcnt lgkmcnt(10)
	v_mul_f32_e32 v28, 0x42000000, v30
	v_mul_f32_e32 v21, 0x42000000, v21
	v_mul_f32_e32 v23, 0x42000000, v23
	v_mul_f32_e32 v29, 0x42000000, v29
	v_mul_f32_e32 v31, 0x42000000, v31
	v_cvt_pk_fp8_f32 v4, v2, v20
	v_cvt_pk_fp8_f32 v5, v26, v28
	s_waitcnt lgkmcnt(9)
	v_mul_f32_e32 v30, 0x42000000, v32
	s_waitcnt lgkmcnt(8)
	v_mul_f32_e32 v32, 0x42000000, v34
	v_mul_f32_e32 v34, 0x42000000, v35
	s_waitcnt lgkmcnt(7)
	v_mul_f32_e32 v35, 0x42000000, v36
	s_waitcnt lgkmcnt(6)
	v_mul_f32_e32 v36, 0x42000000, v38
	s_waitcnt lgkmcnt(5)
	v_mul_f32_e32 v38, 0x42000000, v40
	s_waitcnt lgkmcnt(4)
	v_mul_f32_e32 v40, 0x42000000, v42
	s_waitcnt lgkmcnt(3)
	v_mul_f32_e32 v42, 0x42000000, v44
	s_waitcnt lgkmcnt(2)
	v_mul_f32_e32 v44, 0x42000000, v46
	v_cvt_pk_fp8_f32 v6, v21, v23
	v_cvt_pk_fp8_f32 v7, v29, v31
	v_mul_f32_e32 v37, 0x42000000, v37
	v_mul_f32_e32 v39, 0x42000000, v39
	v_mul_f32_e32 v45, 0x42000000, v45
	v_mul_f32_e32 v47, 0x42000000, v47
	v_cvt_pk_fp8_f32 v8, v35, v36
	v_cvt_pk_fp8_f32 v9, v42, v44
	v_cvt_pk_fp8_f32 v10, v37, v39
	v_cvt_pk_fp8_f32 v11, v45, v47
	v_mul_f32_e32 v25, 0x42000000, v25
	v_mul_f32_e32 v27, 0x42000000, v27
	v_mul_f32_e32 v33, 0x42000000, v33
	v_cvt_pk_fp8_f32 v4, v22, v24 op_sel:[0,0,1]
	v_cvt_pk_fp8_f32 v5, v30, v32 op_sel:[0,0,1]
	s_waitcnt lgkmcnt(1)
	v_mul_f32_e32 v46, 0x42000000, v48
	s_waitcnt lgkmcnt(0)
	v_mul_f32_e32 v48, 0x42000000, v50
	v_cvt_pk_fp8_f32 v6, v25, v27 op_sel:[0,0,1]
	v_cvt_pk_fp8_f32 v7, v33, v34 op_sel:[0,0,1]
	v_mul_f32_e32 v41, 0x42000000, v41
	v_mul_f32_e32 v43, 0x42000000, v43
	v_mul_f32_e32 v49, 0x42000000, v49
	v_mul_f32_e32 v50, 0x42000000, v51
	v_cvt_pk_fp8_f32 v8, v38, v40 op_sel:[0,0,1]
	v_cvt_pk_fp8_f32 v9, v46, v48 op_sel:[0,0,1]
	v_cvt_pk_fp8_f32 v10, v41, v43 op_sel:[0,0,1]
	v_cvt_pk_fp8_f32 v11, v49, v50 op_sel:[0,0,1]
	global_store_dwordx2 v[14:15], v[4:5], off
	global_store_dwordx2 v[12:13], v[6:7], off
	global_store_dwordx2 v[16:17], v[8:9], off
	global_store_dwordx2 v[18:19], v[10:11], off
	s_waitcnt lgkmcnt(0)
	s_cbranch_scc1 .LBB0_284

.LBB0_706:
	s_cmp_ge_u32 s87, s3
	s_cbranch_scc1 .LBB0_705
	s_cmpk_gt_i32 s87, 0x5fff
	s_cselect_b64 s[14:15], -1, 0
	s_and_b64 s[16:17], s[14:15], exec
	s_cselect_b32 s90, 0xffffa000, 0
	s_add_i32 s90, s90, s87
	s_cmpk_gt_i32 s90, 0x3fff
	s_mov_b64 s[16:17], -1
	s_cbranch_scc0 .LBB0_709
	s_and_b64 s[16:17], s[14:15], exec
	s_mov_b32 s8, 0x7b00000
	s_cselect_b32 s8, s8, 0x6b00000
	s_add_u32 s33, s52, s8
	s_addc_u32 s76, s53, 0
	s_add_i32 s8, s90, 0xffffc000
	s_lshr_b32 s16, s8, 9
	s_load_dwordx2 s[92:93], s[0:1], 0xd8
	s_and_b64 s[94:95], s[14:15], exec
	s_cselect_b32 s8, 16, 0
	s_add_i32 s8, s16, s8
	s_lshl_b64 s[94:95], s[8:9], 22
	s_waitcnt lgkmcnt(0)
	s_add_u32 s77, s92, s94
	s_mov_b32 s17, s9
	s_addc_u32 s80, s93, s95
	s_lshl_b64 s[16:17], s[16:17], 20
	s_add_u32 s16, s33, s16
	s_addc_u32 s17, s76, s17
	s_and_b32 s8, s88, 0x3e0
	v_mov_b32_e32 v8, v1
	s_and_b32 s91, s89, 0x3c0
	s_lshl_b32 s33, s8, 2
	v_ashrrev_i32_e32 v9, 5, v8
	v_add_u32_e32 v4, s91, v9
	s_add_u32 s92, s77, s33
	v_lshlrev_b32_e32 v2, 2, v8
	s_addc_u32 s93, s80, 0
	v_and_b32_e32 v2, 0x7c, v2
	v_ashrrev_i32_e32 v5, 31, v4
	v_lshl_add_u64 v[6:7], s[92:93], 0, v[2:3]
	v_lshlrev_b64 v[4:5], 12, v[4:5]
	v_lshl_add_u64 v[4:5], v[6:7], 0, v[4:5]
	v_add_co_u32_e32 v6, vcc, s25, v4
	global_load_dword v10, v[4:5], off nt
	s_nop 0
	v_addc_co_u32_e32 v7, vcc, 0, v5, vcc
	global_load_dword v11, v[6:7], off nt
	v_add_co_u32_e32 v6, vcc, s26, v4
	s_add_u32 s16, s16, s91
	s_nop 0
	v_addc_co_u32_e32 v7, vcc, 0, v5, vcc
	global_load_dword v12, v[6:7], off nt
	v_add_co_u32_e32 v6, vcc, s19, v4
	s_addc_u32 s17, s17, 0
	s_nop 0
	v_addc_co_u32_e32 v7, vcc, 0, v5, vcc
	global_load_dword v13, v[6:7], off nt
	v_add_co_u32_e32 v6, vcc, s27, v4
	s_nop 1
	v_addc_co_u32_e32 v7, vcc, 0, v5, vcc
	global_load_dword v14, v[6:7], off nt
	v_add_co_u32_e32 v6, vcc, s28, v4
	s_nop 1
	v_addc_co_u32_e32 v7, vcc, 0, v5, vcc
	global_load_dword v15, v[6:7], off nt
	v_add_co_u32_e32 v6, vcc, s29, v4
	s_nop 1
	v_addc_co_u32_e32 v7, vcc, 0, v5, vcc
	global_load_dword v16, v[6:7], off nt
	v_add_co_u32_e32 v6, vcc, s30, v4
	s_nop 1
	v_addc_co_u32_e32 v7, vcc, 0, v5, vcc
	global_load_dword v17, v[6:7], off nt
	v_add_co_u32_e32 v6, vcc, s23, v4
	s_nop 1
	v_addc_co_u32_e32 v7, vcc, 0, v5, vcc
	global_load_dword v18, v[6:7], off nt
	v_add_co_u32_e32 v6, vcc, s31, v4
	s_nop 1
	v_addc_co_u32_e32 v7, vcc, 0, v5, vcc
	global_load_dword v19, v[6:7], off nt
	v_add_co_u32_e32 v6, vcc, s34, v4
	s_nop 1
	v_addc_co_u32_e32 v7, vcc, 0, v5, vcc
	global_load_dword v20, v[6:7], off nt
	v_add_co_u32_e32 v6, vcc, s35, v4
	s_nop 1
	v_addc_co_u32_e32 v7, vcc, 0, v5, vcc
	global_load_dword v21, v[6:7], off nt
	v_add_co_u32_e32 v6, vcc, s36, v4
	s_nop 1
	v_addc_co_u32_e32 v7, vcc, 0, v5, vcc
	global_load_dword v22, v[6:7], off nt
	v_add_co_u32_e32 v6, vcc, s37, v4
	s_nop 1
	v_addc_co_u32_e32 v7, vcc, 0, v5, vcc
	global_load_dword v23, v[6:7], off nt
	v_add_co_u32_e32 v6, vcc, s38, v4
	s_nop 1
	v_addc_co_u32_e32 v7, vcc, 0, v5, vcc
	global_load_dword v24, v[6:7], off nt
	v_add_co_u32_e32 v6, vcc, s39, v4
	s_nop 1
	v_addc_co_u32_e32 v7, vcc, 0, v5, vcc
	global_load_dword v25, v[6:7], off nt
	v_add_co_u32_e32 v6, vcc, s41, v4
	s_nop 1
	v_addc_co_u32_e32 v7, vcc, 0, v5, vcc
	global_load_dword v26, v[6:7], off nt
	v_add_co_u32_e32 v6, vcc, s42, v4
	s_nop 1
	v_addc_co_u32_e32 v7, vcc, 0, v5, vcc
	global_load_dword v27, v[6:7], off nt
	v_add_co_u32_e32 v6, vcc, s43, v4
	s_nop 1
	v_addc_co_u32_e32 v7, vcc, 0, v5, vcc
	global_load_dword v28, v[6:7], off nt
	v_add_co_u32_e32 v6, vcc, s45, v4
	s_nop 1
	v_addc_co_u32_e32 v7, vcc, 0, v5, vcc
	global_load_dword v29, v[6:7], off nt
	v_add_co_u32_e32 v6, vcc, s46, v4
	s_nop 1
	v_addc_co_u32_e32 v7, vcc, 0, v5, vcc
	global_load_dword v30, v[6:7], off nt
	v_add_co_u32_e32 v6, vcc, s47, v4
	s_nop 1
	v_addc_co_u32_e32 v7, vcc, 0, v5, vcc
	global_load_dword v31, v[6:7], off nt
	v_add_co_u32_e32 v6, vcc, s49, v4
	s_nop 1
	v_addc_co_u32_e32 v7, vcc, 0, v5, vcc
	global_load_dword v32, v[6:7], off nt
	v_add_co_u32_e32 v6, vcc, s50, v4
	s_nop 1
	v_addc_co_u32_e32 v7, vcc, 0, v5, vcc
	global_load_dword v33, v[6:7], off nt
	v_add_co_u32_e32 v6, vcc, s51, v4
	s_nop 1
	v_addc_co_u32_e32 v7, vcc, 0, v5, vcc
	global_load_dword v34, v[6:7], off nt
	v_add_co_u32_e32 v6, vcc, s57, v4
	s_nop 1
	v_addc_co_u32_e32 v7, vcc, 0, v5, vcc
	global_load_dword v35, v[6:7], off nt
	v_add_co_u32_e32 v6, vcc, s58, v4
	s_nop 1
	v_addc_co_u32_e32 v7, vcc, 0, v5, vcc
	global_load_dword v36, v[6:7], off nt
	v_add_co_u32_e32 v6, vcc, s59, v4
	s_nop 1
	v_addc_co_u32_e32 v7, vcc, 0, v5, vcc
	global_load_dword v37, v[6:7], off nt
	v_add_co_u32_e32 v6, vcc, s72, v4
	s_nop 1
	v_addc_co_u32_e32 v7, vcc, 0, v5, vcc
	global_load_dword v38, v[6:7], off nt
	v_add_co_u32_e32 v6, vcc, s73, v4
	s_nop 1
	v_addc_co_u32_e32 v7, vcc, 0, v5, vcc
	global_load_dword v39, v[6:7], off nt
	v_add_co_u32_e32 v6, vcc, s78, v4
	s_nop 1
	v_addc_co_u32_e32 v7, vcc, 0, v5, vcc
	v_add_co_u32_e32 v4, vcc, s79, v4
	global_load_dword v6, v[6:7], off nt
	s_nop 0
	v_addc_co_u32_e32 v5, vcc, 0, v5, vcc
	global_load_dword v4, v[4:5], off nt
	v_mul_lo_u32 v5, v9, s86
	v_add3_u32 v2, s24, v2, v5
	v_add_u32_e32 v5, 0x400, v2
	s_waitcnt vmcnt(30)
	ds_write2_b32 v2, v10, v11 offset1:66
	s_waitcnt vmcnt(28)
	ds_write2_b32 v2, v12, v13 offset0:132 offset1:198
	s_waitcnt vmcnt(26)
	ds_write2_b32 v5, v14, v15 offset0:8 offset1:74
	s_waitcnt vmcnt(24)
	ds_write2_b32 v5, v16, v17 offset0:140 offset1:206
	v_add_u32_e32 v5, 0x800, v2
	s_waitcnt vmcnt(22)
	ds_write2_b32 v5, v18, v19 offset0:16 offset1:82
	s_waitcnt vmcnt(20)
	ds_write2_b32 v5, v20, v21 offset0:148 offset1:214
	v_add_u32_e32 v5, 0xc00, v2
	s_waitcnt vmcnt(18)
	ds_write2_b32 v5, v22, v23 offset0:24 offset1:90
	s_waitcnt vmcnt(16)
	ds_write2_b32 v5, v24, v25 offset0:156 offset1:222
	v_add_u32_e32 v5, 0x1000, v2
	s_waitcnt vmcnt(14)
	ds_write2_b32 v5, v26, v27 offset0:32 offset1:98
	s_waitcnt vmcnt(12)
	ds_write2_b32 v5, v28, v29 offset0:164 offset1:230
	v_add_u32_e32 v5, 0x1400, v2
	s_waitcnt vmcnt(10)
	ds_write2_b32 v5, v30, v31 offset0:40 offset1:106
	s_waitcnt vmcnt(8)
	ds_write2_b32 v5, v32, v33 offset0:172 offset1:238
	v_add_u32_e32 v5, 0x1800, v2
	v_add_u32_e32 v2, 0x1c00, v2
	s_waitcnt vmcnt(6)
	ds_write2_b32 v5, v34, v35 offset0:48 offset1:114
	s_waitcnt vmcnt(4)
	ds_write2_b32 v5, v36, v37 offset0:180 offset1:246
	s_waitcnt vmcnt(2)
	ds_write2_b32 v2, v38, v39 offset0:56 offset1:122
	s_waitcnt vmcnt(0)
	ds_write2_b32 v2, v6, v4 offset0:188 offset1:254
	v_lshlrev_b32_e32 v2, 3, v8
	v_ashrrev_i32_e32 v24, 3, v8
	v_and_b32_e32 v2, 56, v2
	s_waitcnt lgkmcnt(0)
	v_mul_u32_u24_e32 v6, 0x84, v2
	v_lshl_add_u64 v[4:5], s[16:17], 0, v[2:3]
	v_lshlrev_b32_e32 v2, 2, v24
	v_add3_u32 v2, s24, v6, v2
	ds_read2_b32 v[6:7], v2 offset1:8
	ds_read2_b32 v[8:9], v2 offset0:33 offset1:41
	ds_read2_b32 v[16:17], v2 offset0:132 offset1:140
	ds_read2_b32 v[18:19], v2 offset0:165 offset1:173
	ds_read2_b32 v[10:11], v2 offset0:66 offset1:74
	ds_read2_b32 v[12:13], v2 offset0:99 offset1:107
	s_waitcnt lgkmcnt(5)
	v_mul_f32_e32 v6, 0x42000000, v6
	s_waitcnt lgkmcnt(4)
	v_mul_f32_e32 v8, 0x42000000, v8
	v_mov_b32_e32 v14, v3
	ds_read2_b32 v[20:21], v2 offset0:198 offset1:206
	ds_read2_b32 v[22:23], v2 offset0:231 offset1:239
	v_cvt_pk_fp8_f32 v14, v6, v8
	s_waitcnt lgkmcnt(5)
	v_mul_f32_e32 v6, 0x42000000, v16
	s_waitcnt lgkmcnt(4)
	v_mul_f32_e32 v8, 0x42000000, v18
	v_mov_b32_e32 v15, v3
	v_cvt_pk_fp8_f32 v15, v6, v8
	v_mul_f32_e32 v7, 0x42000000, v7
	v_mul_f32_e32 v8, 0x42000000, v9
	v_mov_b32_e32 v6, v3
	v_cvt_pk_fp8_f32 v6, v7, v8
	s_waitcnt lgkmcnt(3)
	v_mul_f32_e32 v10, 0x42000000, v10
	s_waitcnt lgkmcnt(2)
	v_mul_f32_e32 v12, 0x42000000, v12
	v_cvt_pk_fp8_f32 v14, v10, v12 op_sel:[0,0,1]
	s_waitcnt lgkmcnt(1)
	v_mul_f32_e32 v10, 0x42000000, v20
	s_waitcnt lgkmcnt(0)
	v_mul_f32_e32 v12, 0x42000000, v22
	v_cvt_pk_fp8_f32 v15, v10, v12 op_sel:[0,0,1]
	v_mul_f32_e32 v9, 0x42000000, v11
	v_mul_f32_e32 v10, 0x42000000, v13
	v_cvt_pk_fp8_f32 v6, v9, v10 op_sel:[0,0,1]
	v_mul_f32_e32 v8, 0x42000000, v17
	v_mul_f32_e32 v9, 0x42000000, v19
	v_mov_b32_e32 v7, v3
	v_cvt_pk_fp8_f32 v7, v8, v9
	v_add_u32_e32 v24, s8, v24
	v_mul_f32_e32 v10, 0x42000000, v21
	v_mul_f32_e32 v11, 0x42000000, v23
	v_cvt_pk_fp8_f32 v7, v10, v11 op_sel:[0,0,1]
	v_add_u32_e32 v8, 8, v24
	v_ashrrev_i32_e32 v9, 31, v8
	v_lshlrev_b64 v[8:9], 10, v[8:9]
	v_lshl_add_u64 v[8:9], v[4:5], 0, v[8:9]
	global_store_dwordx2 v[8:9], v[6:7], off
	ds_read2_b32 v[6:7], v2 offset0:16 offset1:24
	ds_read2_b32 v[8:9], v2 offset0:49 offset1:57
	ds_read2_b32 v[16:17], v2 offset0:148 offset1:156
	ds_read2_b32 v[18:19], v2 offset0:181 offset1:189
	v_ashrrev_i32_e32 v25, 31, v24
	v_lshlrev_b64 v[26:27], 10, v[24:25]
	v_lshl_add_u64 v[26:27], v[4:5], 0, v[26:27]
	ds_read2_b32 v[10:11], v2 offset0:82 offset1:90
	ds_read2_b32 v[12:13], v2 offset0:115 offset1:123
	global_store_dwordx2 v[26:27], v[14:15], off
	s_waitcnt lgkmcnt(5)
	v_mul_f32_e32 v6, 0x42000000, v6
	s_waitcnt lgkmcnt(4)
	v_mul_f32_e32 v8, 0x42000000, v8
	v_mov_b32_e32 v14, v3
	ds_read2_b32 v[20:21], v2 offset0:214 offset1:222
	ds_read2_b32 v[22:23], v2 offset0:247 offset1:255
	v_cvt_pk_fp8_f32 v14, v6, v8
	s_waitcnt lgkmcnt(5)
	v_mul_f32_e32 v6, 0x42000000, v16
	s_waitcnt lgkmcnt(4)
	v_mul_f32_e32 v8, 0x42000000, v18
	v_mov_b32_e32 v15, v3
	v_cvt_pk_fp8_f32 v15, v6, v8
	s_waitcnt lgkmcnt(3)
	v_mul_f32_e32 v10, 0x42000000, v10
	s_waitcnt lgkmcnt(2)
	v_mul_f32_e32 v12, 0x42000000, v12
	v_cvt_pk_fp8_f32 v14, v10, v12 op_sel:[0,0,1]
	s_waitcnt lgkmcnt(1)
	v_mul_f32_e32 v10, 0x42000000, v20
	s_waitcnt lgkmcnt(0)
	v_mul_f32_e32 v2, 0x42000000, v22
	v_cvt_pk_fp8_f32 v15, v10, v2 op_sel:[0,0,1]
	v_mul_f32_e32 v2, 0x42000000, v7
	v_mul_f32_e32 v7, 0x42000000, v9
	v_mov_b32_e32 v6, v3
	v_cvt_pk_fp8_f32 v6, v2, v7
	v_mul_f32_e32 v8, 0x42000000, v11
	v_mul_f32_e32 v9, 0x42000000, v13
	v_mul_f32_e32 v2, 0x42000000, v17
	v_cvt_pk_fp8_f32 v6, v8, v9 op_sel:[0,0,1]
	v_mul_f32_e32 v8, 0x42000000, v19
	v_mov_b32_e32 v7, v3
	v_cvt_pk_fp8_f32 v7, v2, v8
	v_mul_f32_e32 v9, 0x42000000, v21
	v_mul_f32_e32 v10, 0x42000000, v23
	v_add_u32_e32 v26, 16, v24
	v_cvt_pk_fp8_f32 v7, v9, v10 op_sel:[0,0,1]
	v_add_u32_e32 v8, 24, v24
	v_ashrrev_i32_e32 v27, 31, v26
	v_ashrrev_i32_e32 v9, 31, v8
	v_lshlrev_b64 v[26:27], 10, v[26:27]
	v_lshlrev_b64 v[8:9], 10, v[8:9]
	v_lshl_add_u64 v[26:27], v[4:5], 0, v[26:27]
	v_lshl_add_u64 v[4:5], v[4:5], 0, v[8:9]
	global_store_dwordx2 v[26:27], v[14:15], off
	global_store_dwordx2 v[4:5], v[6:7], off
	s_waitcnt lgkmcnt(0)
	s_mov_b64 s[16:17], 0
.LBB0_709:
	s_andn2_b64 vcc, exec, s[16:17]
	s_cbranch_vccnz .LBB0_705
	s_and_b64 s[16:17], s[14:15], exec
	s_mov_b32 s8, 0x4b00000
	s_cselect_b32 s8, s8, 0x2b00000
	s_add_u32 s8, s52, s8
	s_addc_u32 s33, s53, 0
	s_ashr_i32 s16, s90, 10
	s_bfe_u32 s76, s87, 0x10009
	s_and_b32 s77, s88, 0x3e0
	s_cmp_eq_u32 s76, 0
	s_movk_i32 s17, 0xc8
	s_cselect_b32 s17, s17, 0xd0
	s_add_u32 s90, s0, s17
	s_addc_u32 s91, s1, 0
	s_load_dwordx2 s[90:91], s[90:91], 0x0
	s_and_b64 s[14:15], s[14:15], exec
	s_cselect_b32 s14, 16, 0
	s_add_i32 s14, s16, s14
	s_ashr_i32 s15, s14, 31
	s_lshl_b64 s[14:15], s[14:15], 22
	s_waitcnt lgkmcnt(0)
	s_add_u32 s80, s90, s14
	s_addc_u32 s81, s91, s15
	s_ashr_i32 s17, s16, 31
	s_lshl_b64 s[14:15], s[16:17], 21
	s_add_u32 s14, s8, s14
	s_addc_u32 s15, s33, s15
	s_lshl_b32 s8, s88, 1
	s_and_b32 s8, s8, 0x700
	s_lshl_b32 s17, s76, 7
	s_or_b32 s8, s8, s17
	s_and_b32 s17, s88, 0x60
	v_mov_b32_e32 v8, v1
	s_and_b32 s16, s89, 0x3c0
	s_or_b32 s8, s8, s17
	s_lshl_b32 s17, s77, 2
	v_ashrrev_i32_e32 v9, 5, v8
	v_add_u32_e32 v4, s16, v9
	s_add_u32 s90, s80, s17
	v_lshlrev_b32_e32 v2, 2, v8
	s_addc_u32 s91, s81, 0
	v_and_b32_e32 v2, 0x7c, v2
	v_ashrrev_i32_e32 v5, 31, v4
	v_lshl_add_u64 v[6:7], s[90:91], 0, v[2:3]
	v_lshlrev_b64 v[4:5], 12, v[4:5]
	v_lshl_add_u64 v[4:5], v[6:7], 0, v[4:5]
	v_add_co_u32_e32 v6, vcc, s25, v4
	global_load_dword v10, v[4:5], off nt
	s_nop 0
	v_addc_co_u32_e32 v7, vcc, 0, v5, vcc
	global_load_dword v11, v[6:7], off nt
	v_add_co_u32_e32 v6, vcc, s26, v4
	s_add_u32 s14, s14, s16
	s_nop 0
	v_addc_co_u32_e32 v7, vcc, 0, v5, vcc
	global_load_dword v12, v[6:7], off nt
	v_add_co_u32_e32 v6, vcc, s19, v4
	s_addc_u32 s15, s15, 0
	s_nop 0
	v_addc_co_u32_e32 v7, vcc, 0, v5, vcc
	global_load_dword v13, v[6:7], off nt
	v_add_co_u32_e32 v6, vcc, s27, v4
	s_nop 1
	v_addc_co_u32_e32 v7, vcc, 0, v5, vcc
	global_load_dword v14, v[6:7], off nt
	v_add_co_u32_e32 v6, vcc, s28, v4
	s_nop 1
	v_addc_co_u32_e32 v7, vcc, 0, v5, vcc
	global_load_dword v15, v[6:7], off nt
	v_add_co_u32_e32 v6, vcc, s29, v4
	s_nop 1
	v_addc_co_u32_e32 v7, vcc, 0, v5, vcc
	global_load_dword v16, v[6:7], off nt
	v_add_co_u32_e32 v6, vcc, s30, v4
	s_nop 1
	v_addc_co_u32_e32 v7, vcc, 0, v5, vcc
	global_load_dword v17, v[6:7], off nt
	v_add_co_u32_e32 v6, vcc, s23, v4
	s_nop 1
	v_addc_co_u32_e32 v7, vcc, 0, v5, vcc
	global_load_dword v18, v[6:7], off nt
	v_add_co_u32_e32 v6, vcc, s31, v4
	s_nop 1
	v_addc_co_u32_e32 v7, vcc, 0, v5, vcc
	global_load_dword v19, v[6:7], off nt
	v_add_co_u32_e32 v6, vcc, s34, v4
	s_nop 1
	v_addc_co_u32_e32 v7, vcc, 0, v5, vcc
	global_load_dword v20, v[6:7], off nt
	v_add_co_u32_e32 v6, vcc, s35, v4
	s_nop 1
	v_addc_co_u32_e32 v7, vcc, 0, v5, vcc
	global_load_dword v21, v[6:7], off nt
	v_add_co_u32_e32 v6, vcc, s36, v4
	s_nop 1
	v_addc_co_u32_e32 v7, vcc, 0, v5, vcc
	global_load_dword v22, v[6:7], off nt
	v_add_co_u32_e32 v6, vcc, s37, v4
	s_nop 1
	v_addc_co_u32_e32 v7, vcc, 0, v5, vcc
	global_load_dword v23, v[6:7], off nt
	v_add_co_u32_e32 v6, vcc, s38, v4
	s_nop 1
	v_addc_co_u32_e32 v7, vcc, 0, v5, vcc
	global_load_dword v24, v[6:7], off nt
	v_add_co_u32_e32 v6, vcc, s39, v4
	s_nop 1
	v_addc_co_u32_e32 v7, vcc, 0, v5, vcc
	global_load_dword v25, v[6:7], off nt
	v_add_co_u32_e32 v6, vcc, s41, v4
	s_nop 1
	v_addc_co_u32_e32 v7, vcc, 0, v5, vcc
	global_load_dword v26, v[6:7], off nt
	v_add_co_u32_e32 v6, vcc, s42, v4
	s_nop 1
	v_addc_co_u32_e32 v7, vcc, 0, v5, vcc
	global_load_dword v27, v[6:7], off nt
	v_add_co_u32_e32 v6, vcc, s43, v4
	s_nop 1
	v_addc_co_u32_e32 v7, vcc, 0, v5, vcc
	global_load_dword v28, v[6:7], off nt
	v_add_co_u32_e32 v6, vcc, s45, v4
	s_nop 1
	v_addc_co_u32_e32 v7, vcc, 0, v5, vcc
	global_load_dword v29, v[6:7], off nt
	v_add_co_u32_e32 v6, vcc, s46, v4
	s_nop 1
	v_addc_co_u32_e32 v7, vcc, 0, v5, vcc
	global_load_dword v30, v[6:7], off nt
	v_add_co_u32_e32 v6, vcc, s47, v4
	s_nop 1
	v_addc_co_u32_e32 v7, vcc, 0, v5, vcc
	global_load_dword v31, v[6:7], off nt
	v_add_co_u32_e32 v6, vcc, s49, v4
	s_nop 1
	v_addc_co_u32_e32 v7, vcc, 0, v5, vcc
	global_load_dword v32, v[6:7], off nt
	v_add_co_u32_e32 v6, vcc, s50, v4
	s_nop 1
	v_addc_co_u32_e32 v7, vcc, 0, v5, vcc
	global_load_dword v33, v[6:7], off nt
	v_add_co_u32_e32 v6, vcc, s51, v4
	s_nop 1
	v_addc_co_u32_e32 v7, vcc, 0, v5, vcc
	global_load_dword v34, v[6:7], off nt
	v_add_co_u32_e32 v6, vcc, s57, v4
	s_nop 1
	v_addc_co_u32_e32 v7, vcc, 0, v5, vcc
	global_load_dword v35, v[6:7], off nt
	v_add_co_u32_e32 v6, vcc, s58, v4
	s_nop 1
	v_addc_co_u32_e32 v7, vcc, 0, v5, vcc
	global_load_dword v36, v[6:7], off nt
	v_add_co_u32_e32 v6, vcc, s59, v4
	s_nop 1
	v_addc_co_u32_e32 v7, vcc, 0, v5, vcc
	global_load_dword v37, v[6:7], off nt
	v_add_co_u32_e32 v6, vcc, s72, v4
	s_nop 1
	v_addc_co_u32_e32 v7, vcc, 0, v5, vcc
	global_load_dword v38, v[6:7], off nt
	v_add_co_u32_e32 v6, vcc, s73, v4
	s_nop 1
	v_addc_co_u32_e32 v7, vcc, 0, v5, vcc
	global_load_dword v39, v[6:7], off nt
	v_add_co_u32_e32 v6, vcc, s78, v4
	s_nop 1
	v_addc_co_u32_e32 v7, vcc, 0, v5, vcc
	v_add_co_u32_e32 v4, vcc, s79, v4
	global_load_dword v6, v[6:7], off nt
	s_nop 0
	v_addc_co_u32_e32 v5, vcc, 0, v5, vcc
	global_load_dword v4, v[4:5], off nt
	v_mul_lo_u32 v5, v9, s86
	v_add3_u32 v2, s24, v2, v5
	v_add_u32_e32 v5, 0x400, v2
	s_waitcnt vmcnt(30)
	ds_write2_b32 v2, v10, v11 offset1:66
	s_waitcnt vmcnt(28)
	ds_write2_b32 v2, v12, v13 offset0:132 offset1:198
	s_waitcnt vmcnt(26)
	ds_write2_b32 v5, v14, v15 offset0:8 offset1:74
	s_waitcnt vmcnt(24)
	ds_write2_b32 v5, v16, v17 offset0:140 offset1:206
	v_add_u32_e32 v5, 0x800, v2
	s_waitcnt vmcnt(22)
	ds_write2_b32 v5, v18, v19 offset0:16 offset1:82
	s_waitcnt vmcnt(20)
	ds_write2_b32 v5, v20, v21 offset0:148 offset1:214
	v_add_u32_e32 v5, 0xc00, v2
	s_waitcnt vmcnt(18)
	ds_write2_b32 v5, v22, v23 offset0:24 offset1:90
	s_waitcnt vmcnt(16)
	ds_write2_b32 v5, v24, v25 offset0:156 offset1:222
	v_add_u32_e32 v5, 0x1000, v2
	s_waitcnt vmcnt(14)
	ds_write2_b32 v5, v26, v27 offset0:32 offset1:98
	s_waitcnt vmcnt(12)
	ds_write2_b32 v5, v28, v29 offset0:164 offset1:230
	v_add_u32_e32 v5, 0x1400, v2
	s_waitcnt vmcnt(10)
	ds_write2_b32 v5, v30, v31 offset0:40 offset1:106
	s_waitcnt vmcnt(8)
	ds_write2_b32 v5, v32, v33 offset0:172 offset1:238
	v_add_u32_e32 v5, 0x1800, v2
	v_add_u32_e32 v2, 0x1c00, v2
	s_waitcnt vmcnt(6)
	ds_write2_b32 v5, v34, v35 offset0:48 offset1:114
	s_waitcnt vmcnt(4)
	ds_write2_b32 v5, v36, v37 offset0:180 offset1:246
	s_waitcnt vmcnt(2)
	ds_write2_b32 v2, v38, v39 offset0:56 offset1:122
	s_waitcnt vmcnt(0)
	ds_write2_b32 v2, v6, v4 offset0:188 offset1:254
	v_lshlrev_b32_e32 v2, 3, v8
	v_ashrrev_i32_e32 v24, 3, v8
	v_and_b32_e32 v2, 56, v2
	s_waitcnt lgkmcnt(0)
	v_mul_u32_u24_e32 v6, 0x84, v2
	v_lshl_add_u64 v[4:5], s[14:15], 0, v[2:3]
	v_lshlrev_b32_e32 v2, 2, v24
	v_add3_u32 v2, s24, v6, v2
	ds_read2_b32 v[6:7], v2 offset1:8
	ds_read2_b32 v[8:9], v2 offset0:33 offset1:41
	ds_read2_b32 v[16:17], v2 offset0:132 offset1:140
	ds_read2_b32 v[18:19], v2 offset0:165 offset1:173
	ds_read2_b32 v[10:11], v2 offset0:66 offset1:74
	ds_read2_b32 v[12:13], v2 offset0:99 offset1:107
	s_waitcnt lgkmcnt(5)
	v_mul_f32_e32 v6, 0x42000000, v6
	s_waitcnt lgkmcnt(4)
	v_mul_f32_e32 v8, 0x42000000, v8
	v_mov_b32_e32 v14, v3
	ds_read2_b32 v[20:21], v2 offset0:198 offset1:206
	ds_read2_b32 v[22:23], v2 offset0:231 offset1:239
	v_cvt_pk_fp8_f32 v14, v6, v8
	s_waitcnt lgkmcnt(5)
	v_mul_f32_e32 v6, 0x42000000, v16
	s_waitcnt lgkmcnt(4)
	v_mul_f32_e32 v8, 0x42000000, v18
	v_mov_b32_e32 v15, v3
	v_cvt_pk_fp8_f32 v15, v6, v8
	v_mul_f32_e32 v7, 0x42000000, v7
	v_mul_f32_e32 v8, 0x42000000, v9
	v_mov_b32_e32 v6, v3
	v_cvt_pk_fp8_f32 v6, v7, v8
	s_waitcnt lgkmcnt(3)
	v_mul_f32_e32 v10, 0x42000000, v10
	s_waitcnt lgkmcnt(2)
	v_mul_f32_e32 v12, 0x42000000, v12
	v_cvt_pk_fp8_f32 v14, v10, v12 op_sel:[0,0,1]
	s_waitcnt lgkmcnt(1)
	v_mul_f32_e32 v10, 0x42000000, v20
	s_waitcnt lgkmcnt(0)
	v_mul_f32_e32 v12, 0x42000000, v22
	v_cvt_pk_fp8_f32 v15, v10, v12 op_sel:[0,0,1]
	v_mul_f32_e32 v9, 0x42000000, v11
	v_mul_f32_e32 v10, 0x42000000, v13
	v_cvt_pk_fp8_f32 v6, v9, v10 op_sel:[0,0,1]
	v_mul_f32_e32 v8, 0x42000000, v17
	v_mul_f32_e32 v9, 0x42000000, v19
	v_mov_b32_e32 v7, v3
	v_cvt_pk_fp8_f32 v7, v8, v9
	v_add_u32_e32 v24, s8, v24
	v_mul_f32_e32 v10, 0x42000000, v21
	v_mul_f32_e32 v11, 0x42000000, v23
	v_cvt_pk_fp8_f32 v7, v10, v11 op_sel:[0,0,1]
	v_add_u32_e32 v8, 8, v24
	v_ashrrev_i32_e32 v9, 31, v8
	v_lshlrev_b64 v[8:9], 10, v[8:9]
	v_lshl_add_u64 v[8:9], v[4:5], 0, v[8:9]
	global_store_dwordx2 v[8:9], v[6:7], off
	ds_read2_b32 v[6:7], v2 offset0:16 offset1:24
	ds_read2_b32 v[8:9], v2 offset0:49 offset1:57
	ds_read2_b32 v[16:17], v2 offset0:148 offset1:156
	ds_read2_b32 v[18:19], v2 offset0:181 offset1:189
	v_ashrrev_i32_e32 v25, 31, v24
	v_lshlrev_b64 v[26:27], 10, v[24:25]
	v_lshl_add_u64 v[26:27], v[4:5], 0, v[26:27]
	ds_read2_b32 v[10:11], v2 offset0:82 offset1:90
	ds_read2_b32 v[12:13], v2 offset0:115 offset1:123
	global_store_dwordx2 v[26:27], v[14:15], off
	s_waitcnt lgkmcnt(5)
	v_mul_f32_e32 v6, 0x42000000, v6
	s_waitcnt lgkmcnt(4)
	v_mul_f32_e32 v8, 0x42000000, v8
	v_mov_b32_e32 v14, v3
	ds_read2_b32 v[20:21], v2 offset0:214 offset1:222
	ds_read2_b32 v[22:23], v2 offset0:247 offset1:255
	v_cvt_pk_fp8_f32 v14, v6, v8
	s_waitcnt lgkmcnt(5)
	v_mul_f32_e32 v6, 0x42000000, v16
	s_waitcnt lgkmcnt(4)
	v_mul_f32_e32 v8, 0x42000000, v18
	v_mov_b32_e32 v15, v3
	v_cvt_pk_fp8_f32 v15, v6, v8
	s_waitcnt lgkmcnt(3)
	v_mul_f32_e32 v10, 0x42000000, v10
	s_waitcnt lgkmcnt(2)
	v_mul_f32_e32 v12, 0x42000000, v12
	v_cvt_pk_fp8_f32 v14, v10, v12 op_sel:[0,0,1]
	s_waitcnt lgkmcnt(1)
	v_mul_f32_e32 v10, 0x42000000, v20
	s_waitcnt lgkmcnt(0)
	v_mul_f32_e32 v2, 0x42000000, v22
	v_cvt_pk_fp8_f32 v15, v10, v2 op_sel:[0,0,1]
	v_mul_f32_e32 v2, 0x42000000, v7
	v_mul_f32_e32 v7, 0x42000000, v9
	v_mov_b32_e32 v6, v3
	v_cvt_pk_fp8_f32 v6, v2, v7
	v_mul_f32_e32 v8, 0x42000000, v11
	v_mul_f32_e32 v9, 0x42000000, v13
	v_mul_f32_e32 v2, 0x42000000, v17
	v_cvt_pk_fp8_f32 v6, v8, v9 op_sel:[0,0,1]
	v_mul_f32_e32 v8, 0x42000000, v19
	v_mov_b32_e32 v7, v3
	v_cvt_pk_fp8_f32 v7, v2, v8
	v_mul_f32_e32 v9, 0x42000000, v21
	v_mul_f32_e32 v10, 0x42000000, v23
	v_add_u32_e32 v26, 16, v24
	v_cvt_pk_fp8_f32 v7, v9, v10 op_sel:[0,0,1]
	v_add_u32_e32 v8, 24, v24
	v_ashrrev_i32_e32 v27, 31, v26
	v_ashrrev_i32_e32 v9, 31, v8
	v_lshlrev_b64 v[26:27], 10, v[26:27]
	v_lshlrev_b64 v[8:9], 10, v[8:9]
	v_lshl_add_u64 v[26:27], v[4:5], 0, v[26:27]
	v_lshl_add_u64 v[4:5], v[4:5], 0, v[8:9]
	global_store_dwordx2 v[26:27], v[14:15], off
	global_store_dwordx2 v[4:5], v[6:7], off
	s_waitcnt lgkmcnt(0)
	s_branch .LBB0_705

.LBB0_1007:
	s_cmpk_gt_i32 s3, 0x5fff
	s_cselect_b64 s[6:7], -1, 0
	s_and_b64 s[8:9], s[6:7], exec
	s_cselect_b32 s58, 0xffffa000, 0
	s_add_i32 s58, s58, s3
	s_cmpk_gt_i32 s58, 0x3fff
	s_mov_b64 s[8:9], -1
	s_cbranch_scc0 .LBB0_1009
	s_and_b64 s[8:9], s[6:7], exec
	s_cselect_b32 s4, s14, 0x6b00000
	s_add_u32 s33, s52, s4
	s_addc_u32 s59, s53, 0
	s_add_i32 s4, s58, 0xffffc000
	s_lshr_b32 s8, s4, 9
	s_load_dwordx2 s[72:73], s[0:1], 0xd8
	s_and_b64 s[78:79], s[6:7], exec
	s_cselect_b32 s4, 16, 0
	s_add_i32 s4, s8, s4
	s_lshl_b64 s[78:79], s[4:5], 22
	s_waitcnt lgkmcnt(0)
	s_add_u32 s76, s72, s78
	s_mov_b32 s9, s5
	s_addc_u32 s77, s73, s79
	s_lshl_b64 s[72:73], s[8:9], 20
	s_add_u32 s9, s33, s72
	s_addc_u32 s8, s59, s73
	s_and_b32 s4, s13, 0x3e0
	v_mov_b32_e32 v22, v1
	s_and_b32 s59, s12, 0x3c0
	s_lshl_b32 s33, s4, 2
	v_ashrrev_i32_e32 v23, 5, v22
	v_add_u32_e32 v4, s59, v23
	s_add_u32 s72, s76, s33
	v_lshlrev_b32_e32 v2, 2, v22
	s_addc_u32 s73, s77, 0
	v_and_b32_e32 v2, 0x7c, v2
	v_ashrrev_i32_e32 v5, 31, v4
	v_lshl_add_u64 v[6:7], s[72:73], 0, v[2:3]
	v_lshlrev_b64 v[4:5], 12, v[4:5]
	v_lshl_add_u64 v[4:5], v[6:7], 0, v[4:5]
	v_add_co_u32_e32 v6, vcc, s15, v4
	s_add_u32 s72, s9, s59
	s_nop 0
	v_addc_co_u32_e32 v7, vcc, 0, v5, vcc
	v_add_co_u32_e32 v8, vcc, s16, v4
	s_addc_u32 s73, s8, 0
	s_nop 0
	v_addc_co_u32_e32 v9, vcc, 0, v5, vcc
	v_add_co_u32_e32 v10, vcc, s17, v4
	s_mov_b64 s[8:9], 0
	s_nop 0
	v_addc_co_u32_e32 v11, vcc, 0, v5, vcc
	v_add_co_u32_e32 v12, vcc, s18, v4
	s_nop 1
	v_addc_co_u32_e32 v13, vcc, 0, v5, vcc
	v_add_co_u32_e32 v14, vcc, s19, v4
	s_nop 1
	v_addc_co_u32_e32 v15, vcc, 0, v5, vcc
	v_add_co_u32_e32 v16, vcc, s20, v4
	s_nop 1
	v_addc_co_u32_e32 v17, vcc, 0, v5, vcc
	v_add_co_u32_e32 v18, vcc, s21, v4
	s_nop 1
	v_addc_co_u32_e32 v19, vcc, 0, v5, vcc
	global_load_dword v24, v[4:5], off nt
	global_load_dword v25, v[6:7], off nt
	global_load_dword v26, v[8:9], off nt
	global_load_dword v27, v[10:11], off nt
	global_load_dword v28, v[12:13], off nt
	global_load_dword v29, v[14:15], off nt
	global_load_dword v30, v[16:17], off nt
	global_load_dword v31, v[18:19], off nt
	v_add_co_u32_e32 v6, vcc, s10, v4
	s_nop 1
	v_addc_co_u32_e32 v7, vcc, 0, v5, vcc
	v_add_co_u32_e32 v8, vcc, s22, v4
	s_nop 1
	v_addc_co_u32_e32 v9, vcc, 0, v5, vcc
	v_add_co_u32_e32 v10, vcc, s23, v4
	s_nop 1
	v_addc_co_u32_e32 v11, vcc, 0, v5, vcc
	v_add_co_u32_e32 v12, vcc, s24, v4
	s_nop 1
	v_addc_co_u32_e32 v13, vcc, 0, v5, vcc
	v_add_co_u32_e32 v14, vcc, s25, v4
	s_nop 1
	v_addc_co_u32_e32 v15, vcc, 0, v5, vcc
	v_add_co_u32_e32 v16, vcc, s26, v4
	s_nop 1
	v_addc_co_u32_e32 v17, vcc, 0, v5, vcc
	v_add_co_u32_e32 v18, vcc, s27, v4
	s_nop 1
	v_addc_co_u32_e32 v19, vcc, 0, v5, vcc
	v_add_co_u32_e32 v20, vcc, s28, v4
	s_nop 1
	v_addc_co_u32_e32 v21, vcc, 0, v5, vcc
	global_load_dword v32, v[6:7], off nt
	global_load_dword v33, v[8:9], off nt
	global_load_dword v34, v[10:11], off nt
	global_load_dword v35, v[12:13], off nt
	global_load_dword v36, v[14:15], off nt
	global_load_dword v37, v[16:17], off nt
	global_load_dword v38, v[18:19], off nt
	global_load_dword v39, v[20:21], off nt
	v_add_co_u32_e32 v6, vcc, s29, v4
	s_nop 1
	v_addc_co_u32_e32 v7, vcc, 0, v5, vcc
	v_add_co_u32_e32 v8, vcc, s30, v4
	s_nop 1
	v_addc_co_u32_e32 v9, vcc, 0, v5, vcc
	v_add_co_u32_e32 v10, vcc, s31, v4
	s_nop 1
	v_addc_co_u32_e32 v11, vcc, 0, v5, vcc
	v_add_co_u32_e32 v12, vcc, s34, v4
	s_nop 1
	v_addc_co_u32_e32 v13, vcc, 0, v5, vcc
	v_add_co_u32_e32 v14, vcc, s35, v4
	s_nop 1
	v_addc_co_u32_e32 v15, vcc, 0, v5, vcc
	v_add_co_u32_e32 v16, vcc, s36, v4
	s_nop 1
	v_addc_co_u32_e32 v17, vcc, 0, v5, vcc
	v_add_co_u32_e32 v18, vcc, s37, v4
	s_nop 1
	v_addc_co_u32_e32 v19, vcc, 0, v5, vcc
	v_add_co_u32_e32 v20, vcc, s38, v4
	s_nop 1
	v_addc_co_u32_e32 v21, vcc, 0, v5, vcc
	global_load_dword v40, v[6:7], off nt
	global_load_dword v41, v[8:9], off nt
	global_load_dword v42, v[10:11], off nt
	global_load_dword v43, v[12:13], off nt
	global_load_dword v44, v[14:15], off nt
	global_load_dword v45, v[16:17], off nt
	global_load_dword v46, v[18:19], off nt
	s_nop 0
	global_load_dword v20, v[20:21], off nt
	v_add_co_u32_e32 v6, vcc, s39, v4
	s_nop 1
	v_addc_co_u32_e32 v7, vcc, 0, v5, vcc
	v_add_co_u32_e32 v8, vcc, s41, v4
	s_nop 1
	v_addc_co_u32_e32 v9, vcc, 0, v5, vcc
	v_add_co_u32_e32 v10, vcc, s42, v4
	s_nop 1
	v_addc_co_u32_e32 v11, vcc, 0, v5, vcc
	v_add_co_u32_e32 v12, vcc, s43, v4
	s_nop 1
	v_addc_co_u32_e32 v13, vcc, 0, v5, vcc
	v_add_co_u32_e32 v14, vcc, s45, v4
	s_nop 1
	v_addc_co_u32_e32 v15, vcc, 0, v5, vcc
	v_add_co_u32_e32 v16, vcc, s46, v4
	s_nop 1
	v_addc_co_u32_e32 v17, vcc, 0, v5, vcc
	v_add_co_u32_e32 v18, vcc, s47, v4
	s_nop 1
	v_addc_co_u32_e32 v19, vcc, 0, v5, vcc
	v_add_co_u32_e32 v4, vcc, s49, v4
	s_nop 1
	v_addc_co_u32_e32 v5, vcc, 0, v5, vcc
	global_load_dword v6, v[6:7], off nt
	s_nop 0
	global_load_dword v7, v[8:9], off nt
	s_nop 0
	global_load_dword v8, v[10:11], off nt
	global_load_dword v9, v[12:13], off nt
	s_nop 0
	global_load_dword v10, v[14:15], off nt
	global_load_dword v11, v[16:17], off nt
	global_load_dword v12, v[18:19], off nt
	s_nop 0
	global_load_dword v4, v[4:5], off nt
	v_mul_lo_u32 v5, v23, s50
	v_add3_u32 v2, s11, v2, v5
	v_add_u32_e32 v5, 0x400, v2
	s_waitcnt vmcnt(30)
	ds_write2_b32 v2, v24, v25 offset1:66
	s_waitcnt vmcnt(28)
	ds_write2_b32 v2, v26, v27 offset0:132 offset1:198
	s_waitcnt vmcnt(26)
	ds_write2_b32 v5, v28, v29 offset0:8 offset1:74
	s_waitcnt vmcnt(24)
	ds_write2_b32 v5, v30, v31 offset0:140 offset1:206
	v_add_u32_e32 v5, 0x800, v2
	s_waitcnt vmcnt(22)
	ds_write2_b32 v5, v32, v33 offset0:16 offset1:82
	s_waitcnt vmcnt(20)
	ds_write2_b32 v5, v34, v35 offset0:148 offset1:214
	v_add_u32_e32 v5, 0xc00, v2
	s_waitcnt vmcnt(18)
	ds_write2_b32 v5, v36, v37 offset0:24 offset1:90
	s_waitcnt vmcnt(16)
	ds_write2_b32 v5, v38, v39 offset0:156 offset1:222
	v_add_u32_e32 v5, 0x1000, v2
	s_waitcnt vmcnt(14)
	ds_write2_b32 v5, v40, v41 offset0:32 offset1:98
	s_waitcnt vmcnt(12)
	ds_write2_b32 v5, v42, v43 offset0:164 offset1:230
	v_add_u32_e32 v5, 0x1400, v2
	s_waitcnt vmcnt(10)
	ds_write2_b32 v5, v44, v45 offset0:40 offset1:106
	s_waitcnt vmcnt(8)
	ds_write2_b32 v5, v46, v20 offset0:172 offset1:238
	v_add_u32_e32 v5, 0x1800, v2
	v_add_u32_e32 v2, 0x1c00, v2
	s_waitcnt vmcnt(6)
	ds_write2_b32 v5, v6, v7 offset0:48 offset1:114
	s_waitcnt vmcnt(4)
	ds_write2_b32 v5, v8, v9 offset0:180 offset1:246
	s_waitcnt vmcnt(2)
	ds_write2_b32 v2, v10, v11 offset0:56 offset1:122
	s_waitcnt vmcnt(0)
	ds_write2_b32 v2, v12, v4 offset0:188 offset1:254
	v_lshlrev_b32_e32 v2, 3, v22
	v_ashrrev_i32_e32 v24, 3, v22
	v_and_b32_e32 v2, 56, v2
	s_waitcnt lgkmcnt(0)
	v_mul_u32_u24_e32 v4, 0x84, v2
	v_lshlrev_b32_e32 v5, 2, v24
	v_add3_u32 v28, s11, v4, v5
	ds_read2_b32 v[4:5], v28 offset1:8
	ds_read2_b32 v[6:7], v28 offset0:33 offset1:41
	ds_read2_b32 v[8:9], v28 offset0:66 offset1:74
	ds_read2_b32 v[12:13], v28 offset0:99 offset1:107
	ds_read2_b32 v[14:15], v28 offset0:132 offset1:140
	ds_read2_b32 v[16:17], v28 offset0:165 offset1:173
	v_lshl_add_u64 v[10:11], s[72:73], 0, v[2:3]
	s_waitcnt lgkmcnt(5)
	v_mul_f32_e32 v2, 0x42000000, v4
	s_waitcnt lgkmcnt(4)
	v_mul_f32_e32 v4, 0x42000000, v6
	v_mov_b32_e32 v18, v3
	ds_read2_b32 v[20:21], v28 offset0:198 offset1:206
	ds_read2_b32 v[22:23], v28 offset0:231 offset1:239
	v_cvt_pk_fp8_f32 v18, v2, v4
	s_waitcnt lgkmcnt(3)
	v_mul_f32_e32 v2, 0x42000000, v14
	s_waitcnt lgkmcnt(2)
	v_mul_f32_e32 v4, 0x42000000, v16
	v_mov_b32_e32 v19, v3
	v_cvt_pk_fp8_f32 v19, v2, v4
	s_waitcnt lgkmcnt(1)
	v_mul_f32_e32 v2, 0x42000000, v20
	s_waitcnt lgkmcnt(0)
	v_mul_f32_e32 v4, 0x42000000, v22
	v_mul_f32_e32 v6, 0x42000000, v8
	v_mul_f32_e32 v8, 0x42000000, v12
	v_cvt_pk_fp8_f32 v19, v2, v4 op_sel:[0,0,1]
	v_mul_f32_e32 v2, 0x42000000, v5
	v_mul_f32_e32 v5, 0x42000000, v7
	v_mov_b32_e32 v4, v3
	v_cvt_pk_fp8_f32 v18, v6, v8 op_sel:[0,0,1]
	v_cvt_pk_fp8_f32 v4, v2, v5
	v_mul_f32_e32 v2, 0x42000000, v15
	v_mul_f32_e32 v8, 0x42000000, v17
	v_mov_b32_e32 v5, v3
	v_cvt_pk_fp8_f32 v5, v2, v8
	v_mul_f32_e32 v6, 0x42000000, v9
	v_mul_f32_e32 v7, 0x42000000, v13
	v_add_u32_e32 v24, s4, v24
	v_cvt_pk_fp8_f32 v4, v6, v7 op_sel:[0,0,1]
	v_mul_f32_e32 v2, 0x42000000, v21
	v_mul_f32_e32 v6, 0x42000000, v23
	v_ashrrev_i32_e32 v25, 31, v24
	v_cvt_pk_fp8_f32 v5, v2, v6 op_sel:[0,0,1]
	v_add_u32_e32 v6, 8, v24
	v_lshlrev_b64 v[26:27], 10, v[24:25]
	v_ashrrev_i32_e32 v7, 31, v6
	v_lshl_add_u64 v[26:27], v[10:11], 0, v[26:27]
	v_lshlrev_b64 v[6:7], 10, v[6:7]
	global_store_dwordx2 v[26:27], v[18:19], off
	v_lshl_add_u64 v[6:7], v[10:11], 0, v[6:7]
	ds_read2_b32 v[8:9], v28 offset0:16 offset1:24
	ds_read2_b32 v[12:13], v28 offset0:49 offset1:57
	ds_read2_b32 v[14:15], v28 offset0:82 offset1:90
	global_store_dwordx2 v[6:7], v[4:5], off
	ds_read2_b32 v[4:5], v28 offset0:115 offset1:123
	ds_read2_b32 v[6:7], v28 offset0:148 offset1:156
	ds_read2_b32 v[16:17], v28 offset0:181 offset1:189
	s_waitcnt lgkmcnt(5)
	v_mul_f32_e32 v2, 0x42000000, v8
	s_waitcnt lgkmcnt(4)
	v_mul_f32_e32 v8, 0x42000000, v12
	v_mov_b32_e32 v18, v3
	ds_read2_b32 v[20:21], v28 offset0:214 offset1:222
	ds_read2_b32 v[22:23], v28 offset0:247 offset1:255
	v_cvt_pk_fp8_f32 v18, v2, v8
	s_waitcnt lgkmcnt(3)
	v_mul_f32_e32 v2, 0x42000000, v6
	s_waitcnt lgkmcnt(2)
	v_mul_f32_e32 v6, 0x42000000, v16
	v_mov_b32_e32 v19, v3
	v_cvt_pk_fp8_f32 v19, v2, v6
	v_mul_f32_e32 v12, 0x42000000, v14
	v_mul_f32_e32 v4, 0x42000000, v4
	v_cvt_pk_fp8_f32 v18, v12, v4 op_sel:[0,0,1]
	s_waitcnt lgkmcnt(1)
	v_mul_f32_e32 v2, 0x42000000, v20
	s_waitcnt lgkmcnt(0)
	v_mul_f32_e32 v4, 0x42000000, v22
	v_cvt_pk_fp8_f32 v19, v2, v4 op_sel:[0,0,1]
	v_mul_f32_e32 v2, 0x42000000, v9
	v_mul_f32_e32 v6, 0x42000000, v13
	v_mov_b32_e32 v4, v3
	v_mul_f32_e32 v9, 0x42000000, v5
	v_cvt_pk_fp8_f32 v4, v2, v6
	v_mul_f32_e32 v2, 0x42000000, v7
	v_mul_f32_e32 v6, 0x42000000, v17
	v_mov_b32_e32 v5, v3
	v_cvt_pk_fp8_f32 v5, v2, v6
	v_mul_f32_e32 v8, 0x42000000, v15
	v_mul_f32_e32 v2, 0x42000000, v21
	v_mul_f32_e32 v6, 0x42000000, v23
	v_add_u32_e32 v26, 16, v24
	v_cvt_pk_fp8_f32 v4, v8, v9 op_sel:[0,0,1]
	v_cvt_pk_fp8_f32 v5, v2, v6 op_sel:[0,0,1]
	v_add_u32_e32 v6, 24, v24
	v_ashrrev_i32_e32 v27, 31, v26
	v_ashrrev_i32_e32 v7, 31, v6
	v_lshlrev_b64 v[26:27], 10, v[26:27]
	v_lshlrev_b64 v[6:7], 10, v[6:7]
	v_lshl_add_u64 v[26:27], v[10:11], 0, v[26:27]
	v_lshl_add_u64 v[6:7], v[10:11], 0, v[6:7]
	global_store_dwordx2 v[26:27], v[18:19], off
	global_store_dwordx2 v[6:7], v[4:5], off
	s_waitcnt lgkmcnt(0)
.LBB0_1009:
	s_andn2_b64 vcc, exec, s[8:9]
	s_cbranch_vccnz .LBB0_1006
	s_and_b64 s[8:9], s[6:7], exec
	s_cselect_b32 s4, s51, 0x2b00000
	s_add_u32 s4, s52, s4
	s_addc_u32 s33, s53, 0
	s_ashr_i32 s8, s58, 10
	s_bfe_u32 s72, s3, 0x10009
	s_and_b32 s73, s13, 0x3e0
	s_cmp_eq_u32 s72, 0
	s_cselect_b32 s9, s57, 0xd0
	s_add_u32 s58, s0, s9
	s_addc_u32 s59, s1, 0
	s_load_dwordx2 s[58:59], s[58:59], 0x0
	s_and_b64 s[6:7], s[6:7], exec
	s_cselect_b32 s6, 16, 0
	s_add_i32 s6, s8, s6
	s_ashr_i32 s7, s6, 31
	s_lshl_b64 s[6:7], s[6:7], 22
	s_waitcnt lgkmcnt(0)
	s_add_u32 s58, s58, s6
	s_addc_u32 s59, s59, s7
	s_ashr_i32 s9, s8, 31
	s_lshl_b64 s[8:9], s[8:9], 21
	s_add_u32 s7, s4, s8
	s_addc_u32 s6, s33, s9
	s_lshl_b32 s4, s13, 1
	s_and_b32 s4, s4, 0x700
	s_lshl_b32 s9, s72, 7
	s_or_b32 s4, s4, s9
	s_and_b32 s9, s13, 0x60
	v_mov_b32_e32 v22, v1
	s_and_b32 s8, s12, 0x3c0
	s_or_b32 s4, s4, s9
	s_lshl_b32 s9, s73, 2
	v_ashrrev_i32_e32 v23, 5, v22
	v_add_u32_e32 v4, s8, v23
	s_add_u32 s58, s58, s9
	v_lshlrev_b32_e32 v2, 2, v22
	s_addc_u32 s59, s59, 0
	v_and_b32_e32 v2, 0x7c, v2
	v_ashrrev_i32_e32 v5, 31, v4
	v_lshl_add_u64 v[6:7], s[58:59], 0, v[2:3]
	v_lshlrev_b64 v[4:5], 12, v[4:5]
	v_lshl_add_u64 v[4:5], v[6:7], 0, v[4:5]
	v_add_co_u32_e32 v6, vcc, s15, v4
	s_add_u32 s8, s7, s8
	s_nop 0
	v_addc_co_u32_e32 v7, vcc, 0, v5, vcc
	v_add_co_u32_e32 v8, vcc, s16, v4
	s_addc_u32 s9, s6, 0
	s_nop 0
	v_addc_co_u32_e32 v9, vcc, 0, v5, vcc
	v_add_co_u32_e32 v10, vcc, s17, v4
	s_nop 1
	v_addc_co_u32_e32 v11, vcc, 0, v5, vcc
	v_add_co_u32_e32 v12, vcc, s18, v4
	s_nop 1
	v_addc_co_u32_e32 v13, vcc, 0, v5, vcc
	v_add_co_u32_e32 v14, vcc, s19, v4
	s_nop 1
	v_addc_co_u32_e32 v15, vcc, 0, v5, vcc
	v_add_co_u32_e32 v16, vcc, s20, v4
	s_nop 1
	v_addc_co_u32_e32 v17, vcc, 0, v5, vcc
	v_add_co_u32_e32 v18, vcc, s21, v4
	s_nop 1
	v_addc_co_u32_e32 v19, vcc, 0, v5, vcc
	global_load_dword v24, v[4:5], off nt
	global_load_dword v25, v[6:7], off nt
	global_load_dword v26, v[8:9], off nt
	global_load_dword v27, v[10:11], off nt
	global_load_dword v28, v[12:13], off nt
	global_load_dword v29, v[14:15], off nt
	global_load_dword v30, v[16:17], off nt
	global_load_dword v31, v[18:19], off nt
	v_add_co_u32_e32 v6, vcc, s10, v4
	s_nop 1
	v_addc_co_u32_e32 v7, vcc, 0, v5, vcc
	v_add_co_u32_e32 v8, vcc, s22, v4
	s_nop 1
	v_addc_co_u32_e32 v9, vcc, 0, v5, vcc
	v_add_co_u32_e32 v10, vcc, s23, v4
	s_nop 1
	v_addc_co_u32_e32 v11, vcc, 0, v5, vcc
	v_add_co_u32_e32 v12, vcc, s24, v4
	s_nop 1
	v_addc_co_u32_e32 v13, vcc, 0, v5, vcc
	v_add_co_u32_e32 v14, vcc, s25, v4
	s_nop 1
	v_addc_co_u32_e32 v15, vcc, 0, v5, vcc
	v_add_co_u32_e32 v16, vcc, s26, v4
	s_nop 1
	v_addc_co_u32_e32 v17, vcc, 0, v5, vcc
	v_add_co_u32_e32 v18, vcc, s27, v4
	s_nop 1
	v_addc_co_u32_e32 v19, vcc, 0, v5, vcc
	v_add_co_u32_e32 v20, vcc, s28, v4
	s_nop 1
	v_addc_co_u32_e32 v21, vcc, 0, v5, vcc
	global_load_dword v32, v[6:7], off nt
	global_load_dword v33, v[8:9], off nt
	global_load_dword v34, v[10:11], off nt
	global_load_dword v35, v[12:13], off nt
	global_load_dword v36, v[14:15], off nt
	global_load_dword v37, v[16:17], off nt
	global_load_dword v38, v[18:19], off nt
	global_load_dword v39, v[20:21], off nt
	v_add_co_u32_e32 v6, vcc, s29, v4
	s_nop 1
	v_addc_co_u32_e32 v7, vcc, 0, v5, vcc
	v_add_co_u32_e32 v8, vcc, s30, v4
	s_nop 1
	v_addc_co_u32_e32 v9, vcc, 0, v5, vcc
	v_add_co_u32_e32 v10, vcc, s31, v4
	s_nop 1
	v_addc_co_u32_e32 v11, vcc, 0, v5, vcc
	v_add_co_u32_e32 v12, vcc, s34, v4
	s_nop 1
	v_addc_co_u32_e32 v13, vcc, 0, v5, vcc
	v_add_co_u32_e32 v14, vcc, s35, v4
	s_nop 1
	v_addc_co_u32_e32 v15, vcc, 0, v5, vcc
	v_add_co_u32_e32 v16, vcc, s36, v4
	s_nop 1
	v_addc_co_u32_e32 v17, vcc, 0, v5, vcc
	v_add_co_u32_e32 v18, vcc, s37, v4
	s_nop 1
	v_addc_co_u32_e32 v19, vcc, 0, v5, vcc
	v_add_co_u32_e32 v20, vcc, s38, v4
	s_nop 1
	v_addc_co_u32_e32 v21, vcc, 0, v5, vcc
	global_load_dword v40, v[6:7], off nt
	global_load_dword v41, v[8:9], off nt
	global_load_dword v42, v[10:11], off nt
	global_load_dword v43, v[12:13], off nt
	global_load_dword v44, v[14:15], off nt
	global_load_dword v45, v[16:17], off nt
	global_load_dword v46, v[18:19], off nt
	s_nop 0
	global_load_dword v20, v[20:21], off nt
	v_add_co_u32_e32 v6, vcc, s39, v4
	s_nop 1
	v_addc_co_u32_e32 v7, vcc, 0, v5, vcc
	v_add_co_u32_e32 v8, vcc, s41, v4
	s_nop 1
	v_addc_co_u32_e32 v9, vcc, 0, v5, vcc
	v_add_co_u32_e32 v10, vcc, s42, v4
	s_nop 1
	v_addc_co_u32_e32 v11, vcc, 0, v5, vcc
	v_add_co_u32_e32 v12, vcc, s43, v4
	s_nop 1
	v_addc_co_u32_e32 v13, vcc, 0, v5, vcc
	v_add_co_u32_e32 v14, vcc, s45, v4
	s_nop 1
	v_addc_co_u32_e32 v15, vcc, 0, v5, vcc
	v_add_co_u32_e32 v16, vcc, s46, v4
	s_nop 1
	v_addc_co_u32_e32 v17, vcc, 0, v5, vcc
	v_add_co_u32_e32 v18, vcc, s47, v4
	s_nop 1
	v_addc_co_u32_e32 v19, vcc, 0, v5, vcc
	v_add_co_u32_e32 v4, vcc, s49, v4
	s_nop 1
	v_addc_co_u32_e32 v5, vcc, 0, v5, vcc
	global_load_dword v6, v[6:7], off nt
	s_nop 0
	global_load_dword v7, v[8:9], off nt
	s_nop 0
	global_load_dword v8, v[10:11], off nt
	global_load_dword v9, v[12:13], off nt
	s_nop 0
	global_load_dword v10, v[14:15], off nt
	global_load_dword v11, v[16:17], off nt
	global_load_dword v12, v[18:19], off nt
	s_nop 0
	global_load_dword v4, v[4:5], off nt
	v_mul_lo_u32 v5, v23, s50
	v_add3_u32 v2, s11, v2, v5
	v_add_u32_e32 v5, 0x400, v2
	s_waitcnt vmcnt(30)
	ds_write2_b32 v2, v24, v25 offset1:66
	s_waitcnt vmcnt(28)
	ds_write2_b32 v2, v26, v27 offset0:132 offset1:198
	s_waitcnt vmcnt(26)
	ds_write2_b32 v5, v28, v29 offset0:8 offset1:74
	s_waitcnt vmcnt(24)
	ds_write2_b32 v5, v30, v31 offset0:140 offset1:206
	v_add_u32_e32 v5, 0x800, v2
	s_waitcnt vmcnt(22)
	ds_write2_b32 v5, v32, v33 offset0:16 offset1:82
	s_waitcnt vmcnt(20)
	ds_write2_b32 v5, v34, v35 offset0:148 offset1:214
	v_add_u32_e32 v5, 0xc00, v2
	s_waitcnt vmcnt(18)
	ds_write2_b32 v5, v36, v37 offset0:24 offset1:90
	s_waitcnt vmcnt(16)
	ds_write2_b32 v5, v38, v39 offset0:156 offset1:222
	v_add_u32_e32 v5, 0x1000, v2
	s_waitcnt vmcnt(14)
	ds_write2_b32 v5, v40, v41 offset0:32 offset1:98
	s_waitcnt vmcnt(12)
	ds_write2_b32 v5, v42, v43 offset0:164 offset1:230
	v_add_u32_e32 v5, 0x1400, v2
	s_waitcnt vmcnt(10)
	ds_write2_b32 v5, v44, v45 offset0:40 offset1:106
	s_waitcnt vmcnt(8)
	ds_write2_b32 v5, v46, v20 offset0:172 offset1:238
	v_add_u32_e32 v5, 0x1800, v2
	v_add_u32_e32 v2, 0x1c00, v2
	s_waitcnt vmcnt(6)
	ds_write2_b32 v5, v6, v7 offset0:48 offset1:114
	s_waitcnt vmcnt(4)
	ds_write2_b32 v5, v8, v9 offset0:180 offset1:246
	s_waitcnt vmcnt(2)
	ds_write2_b32 v2, v10, v11 offset0:56 offset1:122
	s_waitcnt vmcnt(0)
	ds_write2_b32 v2, v12, v4 offset0:188 offset1:254
	v_lshlrev_b32_e32 v2, 3, v22
	v_ashrrev_i32_e32 v24, 3, v22
	v_and_b32_e32 v2, 56, v2
	s_waitcnt lgkmcnt(0)
	v_mul_u32_u24_e32 v4, 0x84, v2
	v_lshlrev_b32_e32 v5, 2, v24
	v_add3_u32 v28, s11, v4, v5
	ds_read2_b32 v[4:5], v28 offset1:8
	ds_read2_b32 v[6:7], v28 offset0:33 offset1:41
	ds_read2_b32 v[8:9], v28 offset0:66 offset1:74
	ds_read2_b32 v[12:13], v28 offset0:99 offset1:107
	ds_read2_b32 v[14:15], v28 offset0:132 offset1:140
	ds_read2_b32 v[16:17], v28 offset0:165 offset1:173
	v_lshl_add_u64 v[10:11], s[8:9], 0, v[2:3]
	s_waitcnt lgkmcnt(5)
	v_mul_f32_e32 v2, 0x42000000, v4
	s_waitcnt lgkmcnt(4)
	v_mul_f32_e32 v4, 0x42000000, v6
	v_mov_b32_e32 v18, v3
	ds_read2_b32 v[20:21], v28 offset0:198 offset1:206
	ds_read2_b32 v[22:23], v28 offset0:231 offset1:239
	v_cvt_pk_fp8_f32 v18, v2, v4
	s_waitcnt lgkmcnt(3)
	v_mul_f32_e32 v2, 0x42000000, v14
	s_waitcnt lgkmcnt(2)
	v_mul_f32_e32 v4, 0x42000000, v16
	v_mov_b32_e32 v19, v3
	v_cvt_pk_fp8_f32 v19, v2, v4
	s_waitcnt lgkmcnt(1)
	v_mul_f32_e32 v2, 0x42000000, v20
	s_waitcnt lgkmcnt(0)
	v_mul_f32_e32 v4, 0x42000000, v22
	v_mul_f32_e32 v6, 0x42000000, v8
	v_mul_f32_e32 v8, 0x42000000, v12
	v_cvt_pk_fp8_f32 v19, v2, v4 op_sel:[0,0,1]
	v_mul_f32_e32 v2, 0x42000000, v5
	v_mul_f32_e32 v5, 0x42000000, v7
	v_mov_b32_e32 v4, v3
	v_cvt_pk_fp8_f32 v18, v6, v8 op_sel:[0,0,1]
	v_cvt_pk_fp8_f32 v4, v2, v5
	v_mul_f32_e32 v2, 0x42000000, v15
	v_mul_f32_e32 v8, 0x42000000, v17
	v_mov_b32_e32 v5, v3
	v_cvt_pk_fp8_f32 v5, v2, v8
	v_mul_f32_e32 v6, 0x42000000, v9
	v_mul_f32_e32 v7, 0x42000000, v13
	v_add_u32_e32 v24, s4, v24
	v_cvt_pk_fp8_f32 v4, v6, v7 op_sel:[0,0,1]
	v_mul_f32_e32 v2, 0x42000000, v21
	v_mul_f32_e32 v6, 0x42000000, v23
	v_ashrrev_i32_e32 v25, 31, v24
	v_cvt_pk_fp8_f32 v5, v2, v6 op_sel:[0,0,1]
	v_add_u32_e32 v6, 8, v24
	v_lshlrev_b64 v[26:27], 10, v[24:25]
	v_ashrrev_i32_e32 v7, 31, v6
	v_lshl_add_u64 v[26:27], v[10:11], 0, v[26:27]
	v_lshlrev_b64 v[6:7], 10, v[6:7]
	global_store_dwordx2 v[26:27], v[18:19], off
	v_lshl_add_u64 v[6:7], v[10:11], 0, v[6:7]
	ds_read2_b32 v[8:9], v28 offset0:16 offset1:24
	ds_read2_b32 v[12:13], v28 offset0:49 offset1:57
	ds_read2_b32 v[14:15], v28 offset0:82 offset1:90
	global_store_dwordx2 v[6:7], v[4:5], off
	ds_read2_b32 v[4:5], v28 offset0:115 offset1:123
	ds_read2_b32 v[6:7], v28 offset0:148 offset1:156
	ds_read2_b32 v[16:17], v28 offset0:181 offset1:189
	s_waitcnt lgkmcnt(5)
	v_mul_f32_e32 v2, 0x42000000, v8
	s_waitcnt lgkmcnt(4)
	v_mul_f32_e32 v8, 0x42000000, v12
	v_mov_b32_e32 v18, v3
	ds_read2_b32 v[20:21], v28 offset0:214 offset1:222
	ds_read2_b32 v[22:23], v28 offset0:247 offset1:255
	v_cvt_pk_fp8_f32 v18, v2, v8
	s_waitcnt lgkmcnt(3)
	v_mul_f32_e32 v2, 0x42000000, v6
	s_waitcnt lgkmcnt(2)
	v_mul_f32_e32 v6, 0x42000000, v16
	v_mov_b32_e32 v19, v3
	v_cvt_pk_fp8_f32 v19, v2, v6
	v_mul_f32_e32 v12, 0x42000000, v14
	v_mul_f32_e32 v4, 0x42000000, v4
	v_cvt_pk_fp8_f32 v18, v12, v4 op_sel:[0,0,1]
	s_waitcnt lgkmcnt(1)
	v_mul_f32_e32 v2, 0x42000000, v20
	s_waitcnt lgkmcnt(0)
	v_mul_f32_e32 v4, 0x42000000, v22
	v_cvt_pk_fp8_f32 v19, v2, v4 op_sel:[0,0,1]
	v_mul_f32_e32 v2, 0x42000000, v9
	v_mul_f32_e32 v6, 0x42000000, v13
	v_mov_b32_e32 v4, v3
	v_mul_f32_e32 v9, 0x42000000, v5
	v_cvt_pk_fp8_f32 v4, v2, v6
	v_mul_f32_e32 v2, 0x42000000, v7
	v_mul_f32_e32 v6, 0x42000000, v17
	v_mov_b32_e32 v5, v3
	v_cvt_pk_fp8_f32 v5, v2, v6
	v_mul_f32_e32 v8, 0x42000000, v15
	v_mul_f32_e32 v2, 0x42000000, v21
	v_mul_f32_e32 v6, 0x42000000, v23
	v_add_u32_e32 v26, 16, v24
	v_cvt_pk_fp8_f32 v4, v8, v9 op_sel:[0,0,1]
	v_cvt_pk_fp8_f32 v5, v2, v6 op_sel:[0,0,1]
	v_add_u32_e32 v6, 24, v24
	v_ashrrev_i32_e32 v27, 31, v26
	v_ashrrev_i32_e32 v7, 31, v6
	v_lshlrev_b64 v[26:27], 10, v[26:27]
	v_lshlrev_b64 v[6:7], 10, v[6:7]
	v_lshl_add_u64 v[26:27], v[10:11], 0, v[26:27]
	v_lshl_add_u64 v[6:7], v[10:11], 0, v[6:7]
	global_store_dwordx2 v[26:27], v[18:19], off
	global_store_dwordx2 v[6:7], v[4:5], off
	s_waitcnt lgkmcnt(0)
	s_branch .LBB0_1006

.LBB0_1319:
	s_cmpk_gt_i32 s3, 0x5fff
	s_cselect_b64 s[6:7], -1, 0
	s_and_b64 s[8:9], s[6:7], exec
	s_cselect_b32 s58, 0xffffa000, 0
	s_add_i32 s58, s58, s3
	s_cmpk_gt_i32 s58, 0x3fff
	s_mov_b64 s[8:9], -1
	s_cbranch_scc0 .LBB0_1321
	s_and_b64 s[8:9], s[6:7], exec
	s_cselect_b32 s4, s14, 0x6b00000
	s_add_u32 s33, s52, s4
	s_addc_u32 s59, s53, 0
	s_add_i32 s4, s58, 0xffffc000
	s_lshr_b32 s8, s4, 9
	s_load_dwordx2 s[72:73], s[0:1], 0xd8
	s_and_b64 s[76:77], s[6:7], exec
	s_cselect_b32 s4, 16, 0
	s_add_i32 s4, s8, s4
	s_lshl_b64 s[76:77], s[4:5], 22
	s_waitcnt lgkmcnt(0)
	s_add_u32 s76, s72, s76
	s_mov_b32 s9, s5
	s_addc_u32 s77, s73, s77
	s_lshl_b64 s[72:73], s[8:9], 20
	s_add_u32 s9, s33, s72
	s_addc_u32 s8, s59, s73
	s_and_b32 s4, s13, 0x3e0
	v_mov_b32_e32 v22, v1
	s_and_b32 s59, s12, 0x3c0
	s_lshl_b32 s33, s4, 2
	v_ashrrev_i32_e32 v23, 5, v22
	v_add_u32_e32 v4, s59, v23
	s_add_u32 s72, s76, s33
	v_lshlrev_b32_e32 v2, 2, v22
	s_addc_u32 s73, s77, 0
	v_and_b32_e32 v2, 0x7c, v2
	v_ashrrev_i32_e32 v5, 31, v4
	v_lshl_add_u64 v[6:7], s[72:73], 0, v[2:3]
	v_lshlrev_b64 v[4:5], 12, v[4:5]
	v_lshl_add_u64 v[4:5], v[6:7], 0, v[4:5]
	v_add_co_u32_e32 v6, vcc, s15, v4
	s_add_u32 s72, s9, s59
	s_nop 0
	v_addc_co_u32_e32 v7, vcc, 0, v5, vcc
	v_add_co_u32_e32 v8, vcc, s16, v4
	s_addc_u32 s73, s8, 0
	s_nop 0
	v_addc_co_u32_e32 v9, vcc, 0, v5, vcc
	v_add_co_u32_e32 v10, vcc, s17, v4
	s_mov_b64 s[8:9], 0
	s_nop 0
	v_addc_co_u32_e32 v11, vcc, 0, v5, vcc
	v_add_co_u32_e32 v12, vcc, s18, v4
	s_nop 1
	v_addc_co_u32_e32 v13, vcc, 0, v5, vcc
	v_add_co_u32_e32 v14, vcc, s19, v4
	s_nop 1
	v_addc_co_u32_e32 v15, vcc, 0, v5, vcc
	v_add_co_u32_e32 v16, vcc, s20, v4
	s_nop 1
	v_addc_co_u32_e32 v17, vcc, 0, v5, vcc
	v_add_co_u32_e32 v18, vcc, s21, v4
	s_nop 1
	v_addc_co_u32_e32 v19, vcc, 0, v5, vcc
	global_load_dword v24, v[4:5], off nt
	global_load_dword v25, v[6:7], off nt
	global_load_dword v26, v[8:9], off nt
	global_load_dword v27, v[10:11], off nt
	global_load_dword v28, v[12:13], off nt
	global_load_dword v29, v[14:15], off nt
	global_load_dword v30, v[16:17], off nt
	global_load_dword v31, v[18:19], off nt
	v_add_co_u32_e32 v6, vcc, s10, v4
	s_nop 1
	v_addc_co_u32_e32 v7, vcc, 0, v5, vcc
	v_add_co_u32_e32 v8, vcc, s22, v4
	s_nop 1
	v_addc_co_u32_e32 v9, vcc, 0, v5, vcc
	v_add_co_u32_e32 v10, vcc, s23, v4
	s_nop 1
	v_addc_co_u32_e32 v11, vcc, 0, v5, vcc
	v_add_co_u32_e32 v12, vcc, s24, v4
	s_nop 1
	v_addc_co_u32_e32 v13, vcc, 0, v5, vcc
	v_add_co_u32_e32 v14, vcc, s25, v4
	s_nop 1
	v_addc_co_u32_e32 v15, vcc, 0, v5, vcc
	v_add_co_u32_e32 v16, vcc, s26, v4
	s_nop 1
	v_addc_co_u32_e32 v17, vcc, 0, v5, vcc
	v_add_co_u32_e32 v18, vcc, s27, v4
	s_nop 1
	v_addc_co_u32_e32 v19, vcc, 0, v5, vcc
	v_add_co_u32_e32 v20, vcc, s28, v4
	s_nop 1
	v_addc_co_u32_e32 v21, vcc, 0, v5, vcc
	global_load_dword v32, v[6:7], off nt
	global_load_dword v33, v[8:9], off nt
	global_load_dword v34, v[10:11], off nt
	global_load_dword v35, v[12:13], off nt
	global_load_dword v36, v[14:15], off nt
	global_load_dword v37, v[16:17], off nt
	global_load_dword v38, v[18:19], off nt
	global_load_dword v39, v[20:21], off nt
	v_add_co_u32_e32 v6, vcc, s29, v4
	s_nop 1
	v_addc_co_u32_e32 v7, vcc, 0, v5, vcc
	v_add_co_u32_e32 v8, vcc, s30, v4
	s_nop 1
	v_addc_co_u32_e32 v9, vcc, 0, v5, vcc
	v_add_co_u32_e32 v10, vcc, s31, v4
	s_nop 1
	v_addc_co_u32_e32 v11, vcc, 0, v5, vcc
	v_add_co_u32_e32 v12, vcc, s34, v4
	s_nop 1
	v_addc_co_u32_e32 v13, vcc, 0, v5, vcc
	v_add_co_u32_e32 v14, vcc, s35, v4
	s_nop 1
	v_addc_co_u32_e32 v15, vcc, 0, v5, vcc
	v_add_co_u32_e32 v16, vcc, s36, v4
	s_nop 1
	v_addc_co_u32_e32 v17, vcc, 0, v5, vcc
	v_add_co_u32_e32 v18, vcc, s37, v4
	s_nop 1
	v_addc_co_u32_e32 v19, vcc, 0, v5, vcc
	v_add_co_u32_e32 v20, vcc, s38, v4
	s_nop 1
	v_addc_co_u32_e32 v21, vcc, 0, v5, vcc
	global_load_dword v40, v[6:7], off nt
	global_load_dword v41, v[8:9], off nt
	global_load_dword v42, v[10:11], off nt
	global_load_dword v43, v[12:13], off nt
	global_load_dword v44, v[14:15], off nt
	global_load_dword v45, v[16:17], off nt
	global_load_dword v46, v[18:19], off nt
	s_nop 0
	global_load_dword v20, v[20:21], off nt
	v_add_co_u32_e32 v6, vcc, s39, v4
	s_nop 1
	v_addc_co_u32_e32 v7, vcc, 0, v5, vcc
	v_add_co_u32_e32 v8, vcc, s41, v4
	s_nop 1
	v_addc_co_u32_e32 v9, vcc, 0, v5, vcc
	v_add_co_u32_e32 v10, vcc, s42, v4
	s_nop 1
	v_addc_co_u32_e32 v11, vcc, 0, v5, vcc
	v_add_co_u32_e32 v12, vcc, s43, v4
	s_nop 1
	v_addc_co_u32_e32 v13, vcc, 0, v5, vcc
	v_add_co_u32_e32 v14, vcc, s45, v4
	s_nop 1
	v_addc_co_u32_e32 v15, vcc, 0, v5, vcc
	v_add_co_u32_e32 v16, vcc, s46, v4
	s_nop 1
	v_addc_co_u32_e32 v17, vcc, 0, v5, vcc
	v_add_co_u32_e32 v18, vcc, s47, v4
	s_nop 1
	v_addc_co_u32_e32 v19, vcc, 0, v5, vcc
	v_add_co_u32_e32 v4, vcc, s49, v4
	s_nop 1
	v_addc_co_u32_e32 v5, vcc, 0, v5, vcc
	global_load_dword v6, v[6:7], off nt
	s_nop 0
	global_load_dword v7, v[8:9], off nt
	s_nop 0
	global_load_dword v8, v[10:11], off nt
	global_load_dword v9, v[12:13], off nt
	s_nop 0
	global_load_dword v10, v[14:15], off nt
	global_load_dword v11, v[16:17], off nt
	global_load_dword v12, v[18:19], off nt
	s_nop 0
	global_load_dword v4, v[4:5], off nt
	v_mul_lo_u32 v5, v23, s50
	v_add3_u32 v2, s11, v2, v5
	v_add_u32_e32 v5, 0x400, v2
	s_waitcnt vmcnt(30)
	ds_write2_b32 v2, v24, v25 offset1:66
	s_waitcnt vmcnt(28)
	ds_write2_b32 v2, v26, v27 offset0:132 offset1:198
	s_waitcnt vmcnt(26)
	ds_write2_b32 v5, v28, v29 offset0:8 offset1:74
	s_waitcnt vmcnt(24)
	ds_write2_b32 v5, v30, v31 offset0:140 offset1:206
	v_add_u32_e32 v5, 0x800, v2
	s_waitcnt vmcnt(22)
	ds_write2_b32 v5, v32, v33 offset0:16 offset1:82
	s_waitcnt vmcnt(20)
	ds_write2_b32 v5, v34, v35 offset0:148 offset1:214
	v_add_u32_e32 v5, 0xc00, v2
	s_waitcnt vmcnt(18)
	ds_write2_b32 v5, v36, v37 offset0:24 offset1:90
	s_waitcnt vmcnt(16)
	ds_write2_b32 v5, v38, v39 offset0:156 offset1:222
	v_add_u32_e32 v5, 0x1000, v2
	s_waitcnt vmcnt(14)
	ds_write2_b32 v5, v40, v41 offset0:32 offset1:98
	s_waitcnt vmcnt(12)
	ds_write2_b32 v5, v42, v43 offset0:164 offset1:230
	v_add_u32_e32 v5, 0x1400, v2
	s_waitcnt vmcnt(10)
	ds_write2_b32 v5, v44, v45 offset0:40 offset1:106
	s_waitcnt vmcnt(8)
	ds_write2_b32 v5, v46, v20 offset0:172 offset1:238
	v_add_u32_e32 v5, 0x1800, v2
	v_add_u32_e32 v2, 0x1c00, v2
	s_waitcnt vmcnt(6)
	ds_write2_b32 v5, v6, v7 offset0:48 offset1:114
	s_waitcnt vmcnt(4)
	ds_write2_b32 v5, v8, v9 offset0:180 offset1:246
	s_waitcnt vmcnt(2)
	ds_write2_b32 v2, v10, v11 offset0:56 offset1:122
	s_waitcnt vmcnt(0)
	ds_write2_b32 v2, v12, v4 offset0:188 offset1:254
	v_lshlrev_b32_e32 v2, 3, v22
	v_ashrrev_i32_e32 v24, 3, v22
	v_and_b32_e32 v2, 56, v2
	s_waitcnt lgkmcnt(0)
	v_mul_u32_u24_e32 v4, 0x84, v2
	v_lshlrev_b32_e32 v5, 2, v24
	v_add3_u32 v28, s11, v4, v5
	ds_read2_b32 v[4:5], v28 offset1:8
	ds_read2_b32 v[6:7], v28 offset0:33 offset1:41
	ds_read2_b32 v[8:9], v28 offset0:66 offset1:74
	ds_read2_b32 v[12:13], v28 offset0:99 offset1:107
	ds_read2_b32 v[14:15], v28 offset0:132 offset1:140
	ds_read2_b32 v[16:17], v28 offset0:165 offset1:173
	v_lshl_add_u64 v[10:11], s[72:73], 0, v[2:3]
	s_waitcnt lgkmcnt(5)
	v_mul_f32_e32 v2, 0x42000000, v4
	s_waitcnt lgkmcnt(4)
	v_mul_f32_e32 v4, 0x42000000, v6
	v_mov_b32_e32 v18, v3
	ds_read2_b32 v[20:21], v28 offset0:198 offset1:206
	ds_read2_b32 v[22:23], v28 offset0:231 offset1:239
	v_cvt_pk_fp8_f32 v18, v2, v4
	s_waitcnt lgkmcnt(3)
	v_mul_f32_e32 v2, 0x42000000, v14
	s_waitcnt lgkmcnt(2)
	v_mul_f32_e32 v4, 0x42000000, v16
	v_mov_b32_e32 v19, v3
	v_cvt_pk_fp8_f32 v19, v2, v4
	s_waitcnt lgkmcnt(1)
	v_mul_f32_e32 v2, 0x42000000, v20
	s_waitcnt lgkmcnt(0)
	v_mul_f32_e32 v4, 0x42000000, v22
	v_mul_f32_e32 v6, 0x42000000, v8
	v_mul_f32_e32 v8, 0x42000000, v12
	v_cvt_pk_fp8_f32 v19, v2, v4 op_sel:[0,0,1]
	v_mul_f32_e32 v2, 0x42000000, v5
	v_mul_f32_e32 v5, 0x42000000, v7
	v_mov_b32_e32 v4, v3
	v_cvt_pk_fp8_f32 v18, v6, v8 op_sel:[0,0,1]
	v_cvt_pk_fp8_f32 v4, v2, v5
	v_mul_f32_e32 v2, 0x42000000, v15
	v_mul_f32_e32 v8, 0x42000000, v17
	v_mov_b32_e32 v5, v3
	v_cvt_pk_fp8_f32 v5, v2, v8
	v_mul_f32_e32 v6, 0x42000000, v9
	v_mul_f32_e32 v7, 0x42000000, v13
	v_add_u32_e32 v24, s4, v24
	v_cvt_pk_fp8_f32 v4, v6, v7 op_sel:[0,0,1]
	v_mul_f32_e32 v2, 0x42000000, v21
	v_mul_f32_e32 v6, 0x42000000, v23
	v_ashrrev_i32_e32 v25, 31, v24
	v_cvt_pk_fp8_f32 v5, v2, v6 op_sel:[0,0,1]
	v_add_u32_e32 v6, 8, v24
	v_lshlrev_b64 v[26:27], 10, v[24:25]
	v_ashrrev_i32_e32 v7, 31, v6
	v_lshl_add_u64 v[26:27], v[10:11], 0, v[26:27]
	v_lshlrev_b64 v[6:7], 10, v[6:7]
	global_store_dwordx2 v[26:27], v[18:19], off
	v_lshl_add_u64 v[6:7], v[10:11], 0, v[6:7]
	ds_read2_b32 v[8:9], v28 offset0:16 offset1:24
	ds_read2_b32 v[12:13], v28 offset0:49 offset1:57
	ds_read2_b32 v[14:15], v28 offset0:82 offset1:90
	global_store_dwordx2 v[6:7], v[4:5], off
	ds_read2_b32 v[4:5], v28 offset0:115 offset1:123
	ds_read2_b32 v[6:7], v28 offset0:148 offset1:156
	ds_read2_b32 v[16:17], v28 offset0:181 offset1:189
	s_waitcnt lgkmcnt(5)
	v_mul_f32_e32 v2, 0x42000000, v8
	s_waitcnt lgkmcnt(4)
	v_mul_f32_e32 v8, 0x42000000, v12
	v_mov_b32_e32 v18, v3
	ds_read2_b32 v[20:21], v28 offset0:214 offset1:222
	ds_read2_b32 v[22:23], v28 offset0:247 offset1:255
	v_cvt_pk_fp8_f32 v18, v2, v8
	s_waitcnt lgkmcnt(3)
	v_mul_f32_e32 v2, 0x42000000, v6
	s_waitcnt lgkmcnt(2)
	v_mul_f32_e32 v6, 0x42000000, v16
	v_mov_b32_e32 v19, v3
	v_cvt_pk_fp8_f32 v19, v2, v6
	v_mul_f32_e32 v12, 0x42000000, v14
	v_mul_f32_e32 v4, 0x42000000, v4
	v_cvt_pk_fp8_f32 v18, v12, v4 op_sel:[0,0,1]
	s_waitcnt lgkmcnt(1)
	v_mul_f32_e32 v2, 0x42000000, v20
	s_waitcnt lgkmcnt(0)
	v_mul_f32_e32 v4, 0x42000000, v22
	v_cvt_pk_fp8_f32 v19, v2, v4 op_sel:[0,0,1]
	v_mul_f32_e32 v2, 0x42000000, v9
	v_mul_f32_e32 v6, 0x42000000, v13
	v_mov_b32_e32 v4, v3
	v_mul_f32_e32 v9, 0x42000000, v5
	v_cvt_pk_fp8_f32 v4, v2, v6
	v_mul_f32_e32 v2, 0x42000000, v7
	v_mul_f32_e32 v6, 0x42000000, v17
	v_mov_b32_e32 v5, v3
	v_cvt_pk_fp8_f32 v5, v2, v6
	v_mul_f32_e32 v8, 0x42000000, v15
	v_mul_f32_e32 v2, 0x42000000, v21
	v_mul_f32_e32 v6, 0x42000000, v23
	v_add_u32_e32 v26, 16, v24
	v_cvt_pk_fp8_f32 v4, v8, v9 op_sel:[0,0,1]
	v_cvt_pk_fp8_f32 v5, v2, v6 op_sel:[0,0,1]
	v_add_u32_e32 v6, 24, v24
	v_ashrrev_i32_e32 v27, 31, v26
	v_ashrrev_i32_e32 v7, 31, v6
	v_lshlrev_b64 v[26:27], 10, v[26:27]
	v_lshlrev_b64 v[6:7], 10, v[6:7]
	v_lshl_add_u64 v[26:27], v[10:11], 0, v[26:27]
	v_lshl_add_u64 v[6:7], v[10:11], 0, v[6:7]
	global_store_dwordx2 v[26:27], v[18:19], off
	global_store_dwordx2 v[6:7], v[4:5], off
	s_waitcnt lgkmcnt(0)

.LBB0_1590:
	s_cmp_ge_u32 s87, s19
	s_cbranch_scc1 .LBB0_1589
	s_cmpk_gt_i32 s87, 0x5fff
	s_cselect_b64 s[16:17], -1, 0
	s_cmp_gt_i32 s87, 0xbfff
	s_cselect_b64 s[14:15], -1, 0
	v_cndmask_b32_e64 v2, 0, 1, s[14:15]
	s_cmp_lg_u64 s[16:17], 0
	v_readfirstlane_b32 s8, v2
	s_addc_u32 s90, s8, 0
	s_mul_i32 s8, s90, 0xffffa000
	s_add_i32 s91, s87, s8
	s_cmpk_gt_i32 s91, 0x3fff
	s_mov_b64 s[16:17], -1
	s_cbranch_scc0 .LBB0_1593
	s_lshl_b32 s8, s90, 24
	s_add_i32 s8, s8, 0x6b00000
	s_and_b64 s[16:17], s[14:15], exec
	s_cselect_b32 s8, 0x3db00000, s8
	s_add_u32 s33, s52, s8
	s_load_dwordx2 s[76:77], s[0:1], 0xd8
	s_addc_u32 s92, s53, 0
	s_add_i32 s8, s91, 0xffffc000
	s_lshr_b32 s16, s8, 9
	s_lshl_b32 s8, s90, 4
	s_add_i32 s8, s16, s8
	s_lshl_b64 s[80:81], s[8:9], 22
	s_waitcnt lgkmcnt(0)
	s_add_u32 s76, s76, s80
	s_mov_b32 s17, s9
	s_addc_u32 s77, s77, s81
	s_lshl_b64 s[16:17], s[16:17], 20
	s_add_u32 s16, s33, s16
	s_addc_u32 s17, s92, s17
	s_and_b32 s8, s88, 0x3e0
	v_mov_b32_e32 v8, v1
	s_and_b32 s92, s89, 0x3c0
	s_lshl_b32 s33, s8, 2
	v_ashrrev_i32_e32 v9, 5, v8
	v_add_u32_e32 v4, s92, v9
	s_add_u32 s76, s76, s33
	v_lshlrev_b32_e32 v2, 2, v8
	s_addc_u32 s77, s77, 0
	v_and_b32_e32 v2, 0x7c, v2
	v_ashrrev_i32_e32 v5, 31, v4
	v_lshl_add_u64 v[6:7], s[76:77], 0, v[2:3]
	v_lshlrev_b64 v[4:5], 12, v[4:5]
	v_lshl_add_u64 v[4:5], v[6:7], 0, v[4:5]
	v_add_co_u32_e32 v6, vcc, s26, v4
	global_load_dword v10, v[4:5], off nt
	s_nop 0
	v_addc_co_u32_e32 v7, vcc, 0, v5, vcc
	global_load_dword v11, v[6:7], off nt
	v_add_co_u32_e32 v6, vcc, s27, v4
	s_add_u32 s16, s16, s92
	s_nop 0
	v_addc_co_u32_e32 v7, vcc, 0, v5, vcc
	global_load_dword v12, v[6:7], off nt
	v_add_co_u32_e32 v6, vcc, s3, v4
	s_addc_u32 s17, s17, 0
	s_nop 0
	v_addc_co_u32_e32 v7, vcc, 0, v5, vcc
	global_load_dword v13, v[6:7], off nt
	v_add_co_u32_e32 v6, vcc, s28, v4
	s_nop 1
	v_addc_co_u32_e32 v7, vcc, 0, v5, vcc
	global_load_dword v14, v[6:7], off nt
	v_add_co_u32_e32 v6, vcc, s29, v4
	s_nop 1
	v_addc_co_u32_e32 v7, vcc, 0, v5, vcc
	global_load_dword v15, v[6:7], off nt
	v_add_co_u32_e32 v6, vcc, s18, v4
	s_nop 1
	v_addc_co_u32_e32 v7, vcc, 0, v5, vcc
	global_load_dword v16, v[6:7], off nt
	v_add_co_u32_e32 v6, vcc, s30, v4
	s_nop 1
	v_addc_co_u32_e32 v7, vcc, 0, v5, vcc
	global_load_dword v17, v[6:7], off nt
	v_add_co_u32_e32 v6, vcc, s24, v4
	s_nop 1
	v_addc_co_u32_e32 v7, vcc, 0, v5, vcc
	global_load_dword v18, v[6:7], off nt
	v_add_co_u32_e32 v6, vcc, s31, v4
	s_nop 1
	v_addc_co_u32_e32 v7, vcc, 0, v5, vcc
	global_load_dword v19, v[6:7], off nt
	v_add_co_u32_e32 v6, vcc, s34, v4
	s_nop 1
	v_addc_co_u32_e32 v7, vcc, 0, v5, vcc
	global_load_dword v20, v[6:7], off nt
	v_add_co_u32_e32 v6, vcc, s35, v4
	s_nop 1
	v_addc_co_u32_e32 v7, vcc, 0, v5, vcc
	global_load_dword v21, v[6:7], off nt
	v_add_co_u32_e32 v6, vcc, s36, v4
	s_nop 1
	v_addc_co_u32_e32 v7, vcc, 0, v5, vcc
	global_load_dword v22, v[6:7], off nt
	v_add_co_u32_e32 v6, vcc, s37, v4
	s_nop 1
	v_addc_co_u32_e32 v7, vcc, 0, v5, vcc
	global_load_dword v23, v[6:7], off nt
	v_add_co_u32_e32 v6, vcc, s38, v4
	s_nop 1
	v_addc_co_u32_e32 v7, vcc, 0, v5, vcc
	global_load_dword v24, v[6:7], off nt
	v_add_co_u32_e32 v6, vcc, s39, v4
	s_nop 1
	v_addc_co_u32_e32 v7, vcc, 0, v5, vcc
	global_load_dword v25, v[6:7], off nt
	v_add_co_u32_e32 v6, vcc, s41, v4
	s_nop 1
	v_addc_co_u32_e32 v7, vcc, 0, v5, vcc
	global_load_dword v26, v[6:7], off nt
	v_add_co_u32_e32 v6, vcc, s42, v4
	s_nop 1
	v_addc_co_u32_e32 v7, vcc, 0, v5, vcc
	global_load_dword v27, v[6:7], off nt
	v_add_co_u32_e32 v6, vcc, s43, v4
	s_nop 1
	v_addc_co_u32_e32 v7, vcc, 0, v5, vcc
	global_load_dword v28, v[6:7], off nt
	v_add_co_u32_e32 v6, vcc, s45, v4
	s_nop 1
	v_addc_co_u32_e32 v7, vcc, 0, v5, vcc
	global_load_dword v29, v[6:7], off nt
	v_add_co_u32_e32 v6, vcc, s46, v4
	s_nop 1
	v_addc_co_u32_e32 v7, vcc, 0, v5, vcc
	global_load_dword v30, v[6:7], off nt
	v_add_co_u32_e32 v6, vcc, s47, v4
	s_nop 1
	v_addc_co_u32_e32 v7, vcc, 0, v5, vcc
	global_load_dword v31, v[6:7], off nt
	v_add_co_u32_e32 v6, vcc, s49, v4
	s_nop 1
	v_addc_co_u32_e32 v7, vcc, 0, v5, vcc
	global_load_dword v32, v[6:7], off nt
	v_add_co_u32_e32 v6, vcc, s57, v4
	s_nop 1
	v_addc_co_u32_e32 v7, vcc, 0, v5, vcc
	global_load_dword v33, v[6:7], off nt
	v_add_co_u32_e32 v6, vcc, s58, v4
	s_nop 1
	v_addc_co_u32_e32 v7, vcc, 0, v5, vcc
	global_load_dword v34, v[6:7], off nt
	v_add_co_u32_e32 v6, vcc, s59, v4
	s_nop 1
	v_addc_co_u32_e32 v7, vcc, 0, v5, vcc
	global_load_dword v35, v[6:7], off nt
	v_add_co_u32_e32 v6, vcc, s72, v4
	s_nop 1
	v_addc_co_u32_e32 v7, vcc, 0, v5, vcc
	global_load_dword v36, v[6:7], off nt
	v_add_co_u32_e32 v6, vcc, s73, v4
	s_nop 1
	v_addc_co_u32_e32 v7, vcc, 0, v5, vcc
	global_load_dword v37, v[6:7], off nt
	v_add_co_u32_e32 v6, vcc, s78, v4
	s_nop 1
	v_addc_co_u32_e32 v7, vcc, 0, v5, vcc
	global_load_dword v38, v[6:7], off nt
	v_add_co_u32_e32 v6, vcc, s79, v4
	s_nop 1
	v_addc_co_u32_e32 v7, vcc, 0, v5, vcc
	global_load_dword v39, v[6:7], off nt
	v_add_co_u32_e32 v6, vcc, s84, v4
	s_nop 1
	v_addc_co_u32_e32 v7, vcc, 0, v5, vcc
	v_add_co_u32_e32 v4, vcc, s85, v4
	global_load_dword v6, v[6:7], off nt
	s_nop 0
	v_addc_co_u32_e32 v5, vcc, 0, v5, vcc
	global_load_dword v4, v[4:5], off nt
	v_mul_lo_u32 v5, v9, s86
	v_add3_u32 v2, s25, v2, v5
	v_add_u32_e32 v5, 0x400, v2
	s_waitcnt vmcnt(30)
	ds_write2_b32 v2, v10, v11 offset1:66
	s_waitcnt vmcnt(28)
	ds_write2_b32 v2, v12, v13 offset0:132 offset1:198
	s_waitcnt vmcnt(26)
	ds_write2_b32 v5, v14, v15 offset0:8 offset1:74
	s_waitcnt vmcnt(24)
	ds_write2_b32 v5, v16, v17 offset0:140 offset1:206
	v_add_u32_e32 v5, 0x800, v2
	s_waitcnt vmcnt(22)
	ds_write2_b32 v5, v18, v19 offset0:16 offset1:82
	s_waitcnt vmcnt(20)
	ds_write2_b32 v5, v20, v21 offset0:148 offset1:214
	v_add_u32_e32 v5, 0xc00, v2
	s_waitcnt vmcnt(18)
	ds_write2_b32 v5, v22, v23 offset0:24 offset1:90
	s_waitcnt vmcnt(16)
	ds_write2_b32 v5, v24, v25 offset0:156 offset1:222
	v_add_u32_e32 v5, 0x1000, v2
	s_waitcnt vmcnt(14)
	ds_write2_b32 v5, v26, v27 offset0:32 offset1:98
	s_waitcnt vmcnt(12)
	ds_write2_b32 v5, v28, v29 offset0:164 offset1:230
	v_add_u32_e32 v5, 0x1400, v2
	s_waitcnt vmcnt(10)
	ds_write2_b32 v5, v30, v31 offset0:40 offset1:106
	s_waitcnt vmcnt(8)
	ds_write2_b32 v5, v32, v33 offset0:172 offset1:238
	v_add_u32_e32 v5, 0x1800, v2
	v_add_u32_e32 v2, 0x1c00, v2
	s_waitcnt vmcnt(6)
	ds_write2_b32 v5, v34, v35 offset0:48 offset1:114
	s_waitcnt vmcnt(4)
	ds_write2_b32 v5, v36, v37 offset0:180 offset1:246
	s_waitcnt vmcnt(2)
	ds_write2_b32 v2, v38, v39 offset0:56 offset1:122
	s_waitcnt vmcnt(0)
	ds_write2_b32 v2, v6, v4 offset0:188 offset1:254
	v_lshlrev_b32_e32 v2, 3, v8
	v_ashrrev_i32_e32 v24, 3, v8
	v_and_b32_e32 v2, 56, v2
	s_waitcnt lgkmcnt(0)
	v_mul_u32_u24_e32 v6, 0x84, v2
	v_lshl_add_u64 v[4:5], s[16:17], 0, v[2:3]
	v_lshlrev_b32_e32 v2, 2, v24
	v_add3_u32 v2, s25, v6, v2
	ds_read2_b32 v[6:7], v2 offset1:8
	ds_read2_b32 v[8:9], v2 offset0:33 offset1:41
	ds_read2_b32 v[16:17], v2 offset0:132 offset1:140
	ds_read2_b32 v[18:19], v2 offset0:165 offset1:173
	ds_read2_b32 v[10:11], v2 offset0:66 offset1:74
	ds_read2_b32 v[12:13], v2 offset0:99 offset1:107
	s_waitcnt lgkmcnt(5)
	v_mul_f32_e32 v6, 0x42000000, v6
	s_waitcnt lgkmcnt(4)
	v_mul_f32_e32 v8, 0x42000000, v8
	v_mov_b32_e32 v14, v3
	ds_read2_b32 v[20:21], v2 offset0:198 offset1:206
	ds_read2_b32 v[22:23], v2 offset0:231 offset1:239
	v_cvt_pk_fp8_f32 v14, v6, v8
	s_waitcnt lgkmcnt(5)
	v_mul_f32_e32 v6, 0x42000000, v16
	s_waitcnt lgkmcnt(4)
	v_mul_f32_e32 v8, 0x42000000, v18
	v_mov_b32_e32 v15, v3
	v_cvt_pk_fp8_f32 v15, v6, v8
	v_mul_f32_e32 v7, 0x42000000, v7
	v_mul_f32_e32 v8, 0x42000000, v9
	v_mov_b32_e32 v6, v3
	v_cvt_pk_fp8_f32 v6, v7, v8
	s_waitcnt lgkmcnt(3)
	v_mul_f32_e32 v10, 0x42000000, v10
	s_waitcnt lgkmcnt(2)
	v_mul_f32_e32 v12, 0x42000000, v12
	v_cvt_pk_fp8_f32 v14, v10, v12 op_sel:[0,0,1]
	s_waitcnt lgkmcnt(1)
	v_mul_f32_e32 v10, 0x42000000, v20
	s_waitcnt lgkmcnt(0)
	v_mul_f32_e32 v12, 0x42000000, v22
	v_cvt_pk_fp8_f32 v15, v10, v12 op_sel:[0,0,1]
	v_mul_f32_e32 v9, 0x42000000, v11
	v_mul_f32_e32 v10, 0x42000000, v13
	v_cvt_pk_fp8_f32 v6, v9, v10 op_sel:[0,0,1]
	v_mul_f32_e32 v8, 0x42000000, v17
	v_mul_f32_e32 v9, 0x42000000, v19
	v_mov_b32_e32 v7, v3
	v_cvt_pk_fp8_f32 v7, v8, v9
	v_add_u32_e32 v24, s8, v24
	v_mul_f32_e32 v10, 0x42000000, v21
	v_mul_f32_e32 v11, 0x42000000, v23
	v_cvt_pk_fp8_f32 v7, v10, v11 op_sel:[0,0,1]
	v_add_u32_e32 v8, 8, v24
	v_ashrrev_i32_e32 v9, 31, v8
	v_lshlrev_b64 v[8:9], 10, v[8:9]
	v_lshl_add_u64 v[8:9], v[4:5], 0, v[8:9]
	global_store_dwordx2 v[8:9], v[6:7], off
	ds_read2_b32 v[6:7], v2 offset0:16 offset1:24
	ds_read2_b32 v[8:9], v2 offset0:49 offset1:57
	ds_read2_b32 v[16:17], v2 offset0:148 offset1:156
	ds_read2_b32 v[18:19], v2 offset0:181 offset1:189
	v_ashrrev_i32_e32 v25, 31, v24
	v_lshlrev_b64 v[26:27], 10, v[24:25]
	v_lshl_add_u64 v[26:27], v[4:5], 0, v[26:27]
	ds_read2_b32 v[10:11], v2 offset0:82 offset1:90
	ds_read2_b32 v[12:13], v2 offset0:115 offset1:123
	global_store_dwordx2 v[26:27], v[14:15], off
	s_waitcnt lgkmcnt(5)
	v_mul_f32_e32 v6, 0x42000000, v6
	s_waitcnt lgkmcnt(4)
	v_mul_f32_e32 v8, 0x42000000, v8
	v_mov_b32_e32 v14, v3
	ds_read2_b32 v[20:21], v2 offset0:214 offset1:222
	ds_read2_b32 v[22:23], v2 offset0:247 offset1:255
	v_cvt_pk_fp8_f32 v14, v6, v8
	s_waitcnt lgkmcnt(5)
	v_mul_f32_e32 v6, 0x42000000, v16
	s_waitcnt lgkmcnt(4)
	v_mul_f32_e32 v8, 0x42000000, v18
	v_mov_b32_e32 v15, v3
	v_cvt_pk_fp8_f32 v15, v6, v8
	s_waitcnt lgkmcnt(3)
	v_mul_f32_e32 v10, 0x42000000, v10
	s_waitcnt lgkmcnt(2)
	v_mul_f32_e32 v12, 0x42000000, v12
	v_cvt_pk_fp8_f32 v14, v10, v12 op_sel:[0,0,1]
	s_waitcnt lgkmcnt(1)
	v_mul_f32_e32 v10, 0x42000000, v20
	s_waitcnt lgkmcnt(0)
	v_mul_f32_e32 v2, 0x42000000, v22
	v_cvt_pk_fp8_f32 v15, v10, v2 op_sel:[0,0,1]
	v_mul_f32_e32 v2, 0x42000000, v7
	v_mul_f32_e32 v7, 0x42000000, v9
	v_mov_b32_e32 v6, v3
	v_cvt_pk_fp8_f32 v6, v2, v7
	v_mul_f32_e32 v8, 0x42000000, v11
	v_mul_f32_e32 v9, 0x42000000, v13
	v_mul_f32_e32 v2, 0x42000000, v17
	v_cvt_pk_fp8_f32 v6, v8, v9 op_sel:[0,0,1]
	v_mul_f32_e32 v8, 0x42000000, v19
	v_mov_b32_e32 v7, v3
	v_cvt_pk_fp8_f32 v7, v2, v8
	v_mul_f32_e32 v9, 0x42000000, v21
	v_mul_f32_e32 v10, 0x42000000, v23
	v_add_u32_e32 v26, 16, v24
	v_cvt_pk_fp8_f32 v7, v9, v10 op_sel:[0,0,1]
	v_add_u32_e32 v8, 24, v24
	v_ashrrev_i32_e32 v27, 31, v26
	v_ashrrev_i32_e32 v9, 31, v8
	v_lshlrev_b64 v[26:27], 10, v[26:27]
	v_lshlrev_b64 v[8:9], 10, v[8:9]
	v_lshl_add_u64 v[26:27], v[4:5], 0, v[26:27]
	v_lshl_add_u64 v[4:5], v[4:5], 0, v[8:9]
	global_store_dwordx2 v[26:27], v[14:15], off
	global_store_dwordx2 v[4:5], v[6:7], off
	s_waitcnt lgkmcnt(0)
	s_mov_b64 s[16:17], 0
.LBB0_1593:
	s_andn2_b64 vcc, exec, s[16:17]
	s_cbranch_vccnz .LBB0_1589
	s_lshl_b32 s8, s90, 25
	s_add_i32 s8, s8, 0x2b00000
	s_and_b64 s[14:15], s[14:15], exec
	s_cselect_b32 s8, 0x3bb00000, s8
	s_add_u32 s8, s52, s8
	s_addc_u32 s33, s53, 0
	s_ashr_i32 s14, s91, 10
	s_bfe_u32 s80, s87, 0x10009
	s_and_b32 s81, s88, 0x3e0
	s_cmp_eq_u32 s80, 0
	s_movk_i32 s15, 0xc8
	s_cselect_b32 s15, s15, 0xd0
	s_add_u32 s16, s0, s15
	s_addc_u32 s17, s1, 0
	s_load_dwordx2 s[16:17], s[16:17], 0x0
	s_lshl_b32 s15, s90, 4
	s_add_i32 s76, s14, s15
	s_ashr_i32 s77, s76, 31
	s_lshl_b64 s[76:77], s[76:77], 22
	s_waitcnt lgkmcnt(0)
	s_add_u32 s76, s16, s76
	s_addc_u32 s17, s17, s77
	s_ashr_i32 s15, s14, 31
	s_lshl_b64 s[14:15], s[14:15], 21
	s_add_u32 s14, s8, s14
	s_addc_u32 s15, s33, s15
	s_lshl_b32 s8, s88, 1
	s_and_b32 s8, s8, 0x700
	s_lshl_b32 s33, s80, 7
	s_or_b32 s8, s8, s33
	s_and_b32 s33, s88, 0x60
	v_mov_b32_e32 v8, v1
	s_and_b32 s16, s89, 0x3c0
	s_or_b32 s8, s8, s33
	s_lshl_b32 s33, s81, 2
	v_ashrrev_i32_e32 v9, 5, v8
	v_add_u32_e32 v4, s16, v9
	s_add_u32 s76, s76, s33
	v_lshlrev_b32_e32 v2, 2, v8
	s_addc_u32 s77, s17, 0
	v_and_b32_e32 v2, 0x7c, v2
	v_ashrrev_i32_e32 v5, 31, v4
	v_lshl_add_u64 v[6:7], s[76:77], 0, v[2:3]
	v_lshlrev_b64 v[4:5], 12, v[4:5]
	v_lshl_add_u64 v[4:5], v[6:7], 0, v[4:5]
	v_add_co_u32_e32 v6, vcc, s26, v4
	global_load_dword v10, v[4:5], off nt
	s_nop 0
	v_addc_co_u32_e32 v7, vcc, 0, v5, vcc
	global_load_dword v11, v[6:7], off nt
	v_add_co_u32_e32 v6, vcc, s27, v4
	s_add_u32 s14, s14, s16
	s_nop 0
	v_addc_co_u32_e32 v7, vcc, 0, v5, vcc
	global_load_dword v12, v[6:7], off nt
	v_add_co_u32_e32 v6, vcc, s3, v4
	s_addc_u32 s15, s15, 0
	s_nop 0
	v_addc_co_u32_e32 v7, vcc, 0, v5, vcc
	global_load_dword v13, v[6:7], off nt
	v_add_co_u32_e32 v6, vcc, s28, v4
	s_nop 1
	v_addc_co_u32_e32 v7, vcc, 0, v5, vcc
	global_load_dword v14, v[6:7], off nt
	v_add_co_u32_e32 v6, vcc, s29, v4
	s_nop 1
	v_addc_co_u32_e32 v7, vcc, 0, v5, vcc
	global_load_dword v15, v[6:7], off nt
	v_add_co_u32_e32 v6, vcc, s18, v4
	s_nop 1
	v_addc_co_u32_e32 v7, vcc, 0, v5, vcc
	global_load_dword v16, v[6:7], off nt
	v_add_co_u32_e32 v6, vcc, s30, v4
	s_nop 1
	v_addc_co_u32_e32 v7, vcc, 0, v5, vcc
	global_load_dword v17, v[6:7], off nt
	v_add_co_u32_e32 v6, vcc, s24, v4
	s_nop 1
	v_addc_co_u32_e32 v7, vcc, 0, v5, vcc
	global_load_dword v18, v[6:7], off nt
	v_add_co_u32_e32 v6, vcc, s31, v4
	s_nop 1
	v_addc_co_u32_e32 v7, vcc, 0, v5, vcc
	global_load_dword v19, v[6:7], off nt
	v_add_co_u32_e32 v6, vcc, s34, v4
	s_nop 1
	v_addc_co_u32_e32 v7, vcc, 0, v5, vcc
	global_load_dword v20, v[6:7], off nt
	v_add_co_u32_e32 v6, vcc, s35, v4
	s_nop 1
	v_addc_co_u32_e32 v7, vcc, 0, v5, vcc
	global_load_dword v21, v[6:7], off nt
	v_add_co_u32_e32 v6, vcc, s36, v4
	s_nop 1
	v_addc_co_u32_e32 v7, vcc, 0, v5, vcc
	global_load_dword v22, v[6:7], off nt
	v_add_co_u32_e32 v6, vcc, s37, v4
	s_nop 1
	v_addc_co_u32_e32 v7, vcc, 0, v5, vcc
	global_load_dword v23, v[6:7], off nt
	v_add_co_u32_e32 v6, vcc, s38, v4
	s_nop 1
	v_addc_co_u32_e32 v7, vcc, 0, v5, vcc
	global_load_dword v24, v[6:7], off nt
	v_add_co_u32_e32 v6, vcc, s39, v4
	s_nop 1
	v_addc_co_u32_e32 v7, vcc, 0, v5, vcc
	global_load_dword v25, v[6:7], off nt
	v_add_co_u32_e32 v6, vcc, s41, v4
	s_nop 1
	v_addc_co_u32_e32 v7, vcc, 0, v5, vcc
	global_load_dword v26, v[6:7], off nt
	v_add_co_u32_e32 v6, vcc, s42, v4
	s_nop 1
	v_addc_co_u32_e32 v7, vcc, 0, v5, vcc
	global_load_dword v27, v[6:7], off nt
	v_add_co_u32_e32 v6, vcc, s43, v4
	s_nop 1
	v_addc_co_u32_e32 v7, vcc, 0, v5, vcc
	global_load_dword v28, v[6:7], off nt
	v_add_co_u32_e32 v6, vcc, s45, v4
	s_nop 1
	v_addc_co_u32_e32 v7, vcc, 0, v5, vcc
	global_load_dword v29, v[6:7], off nt
	v_add_co_u32_e32 v6, vcc, s46, v4
	s_nop 1
	v_addc_co_u32_e32 v7, vcc, 0, v5, vcc
	global_load_dword v30, v[6:7], off nt
	v_add_co_u32_e32 v6, vcc, s47, v4
	s_nop 1
	v_addc_co_u32_e32 v7, vcc, 0, v5, vcc
	global_load_dword v31, v[6:7], off nt
	v_add_co_u32_e32 v6, vcc, s49, v4
	s_nop 1
	v_addc_co_u32_e32 v7, vcc, 0, v5, vcc
	global_load_dword v32, v[6:7], off nt
	v_add_co_u32_e32 v6, vcc, s57, v4
	s_nop 1
	v_addc_co_u32_e32 v7, vcc, 0, v5, vcc
	global_load_dword v33, v[6:7], off nt
	v_add_co_u32_e32 v6, vcc, s58, v4
	s_nop 1
	v_addc_co_u32_e32 v7, vcc, 0, v5, vcc
	global_load_dword v34, v[6:7], off nt
	v_add_co_u32_e32 v6, vcc, s59, v4
	s_nop 1
	v_addc_co_u32_e32 v7, vcc, 0, v5, vcc
	global_load_dword v35, v[6:7], off nt
	v_add_co_u32_e32 v6, vcc, s72, v4
	s_nop 1
	v_addc_co_u32_e32 v7, vcc, 0, v5, vcc
	global_load_dword v36, v[6:7], off nt
	v_add_co_u32_e32 v6, vcc, s73, v4
	s_nop 1
	v_addc_co_u32_e32 v7, vcc, 0, v5, vcc
	global_load_dword v37, v[6:7], off nt
	v_add_co_u32_e32 v6, vcc, s78, v4
	s_nop 1
	v_addc_co_u32_e32 v7, vcc, 0, v5, vcc
	global_load_dword v38, v[6:7], off nt
	v_add_co_u32_e32 v6, vcc, s79, v4
	s_nop 1
	v_addc_co_u32_e32 v7, vcc, 0, v5, vcc
	global_load_dword v39, v[6:7], off nt
	v_add_co_u32_e32 v6, vcc, s84, v4
	s_nop 1
	v_addc_co_u32_e32 v7, vcc, 0, v5, vcc
	v_add_co_u32_e32 v4, vcc, s85, v4
	global_load_dword v6, v[6:7], off nt
	s_nop 0
	v_addc_co_u32_e32 v5, vcc, 0, v5, vcc
	global_load_dword v4, v[4:5], off nt
	v_mul_lo_u32 v5, v9, s86
	v_add3_u32 v2, s25, v2, v5
	v_add_u32_e32 v5, 0x400, v2
	s_waitcnt vmcnt(30)
	ds_write2_b32 v2, v10, v11 offset1:66
	s_waitcnt vmcnt(28)
	ds_write2_b32 v2, v12, v13 offset0:132 offset1:198
	s_waitcnt vmcnt(26)
	ds_write2_b32 v5, v14, v15 offset0:8 offset1:74
	s_waitcnt vmcnt(24)
	ds_write2_b32 v5, v16, v17 offset0:140 offset1:206
	v_add_u32_e32 v5, 0x800, v2
	s_waitcnt vmcnt(22)
	ds_write2_b32 v5, v18, v19 offset0:16 offset1:82
	s_waitcnt vmcnt(20)
	ds_write2_b32 v5, v20, v21 offset0:148 offset1:214
	v_add_u32_e32 v5, 0xc00, v2
	s_waitcnt vmcnt(18)
	ds_write2_b32 v5, v22, v23 offset0:24 offset1:90
	s_waitcnt vmcnt(16)
	ds_write2_b32 v5, v24, v25 offset0:156 offset1:222
	v_add_u32_e32 v5, 0x1000, v2
	s_waitcnt vmcnt(14)
	ds_write2_b32 v5, v26, v27 offset0:32 offset1:98
	s_waitcnt vmcnt(12)
	ds_write2_b32 v5, v28, v29 offset0:164 offset1:230
	v_add_u32_e32 v5, 0x1400, v2
	s_waitcnt vmcnt(10)
	ds_write2_b32 v5, v30, v31 offset0:40 offset1:106
	s_waitcnt vmcnt(8)
	ds_write2_b32 v5, v32, v33 offset0:172 offset1:238
	v_add_u32_e32 v5, 0x1800, v2
	v_add_u32_e32 v2, 0x1c00, v2
	s_waitcnt vmcnt(6)
	ds_write2_b32 v5, v34, v35 offset0:48 offset1:114
	s_waitcnt vmcnt(4)
	ds_write2_b32 v5, v36, v37 offset0:180 offset1:246
	s_waitcnt vmcnt(2)
	ds_write2_b32 v2, v38, v39 offset0:56 offset1:122
	s_waitcnt vmcnt(0)
	ds_write2_b32 v2, v6, v4 offset0:188 offset1:254
	v_lshlrev_b32_e32 v2, 3, v8
	v_ashrrev_i32_e32 v24, 3, v8
	v_and_b32_e32 v2, 56, v2
	s_waitcnt lgkmcnt(0)
	v_mul_u32_u24_e32 v6, 0x84, v2
	v_lshl_add_u64 v[4:5], s[14:15], 0, v[2:3]
	v_lshlrev_b32_e32 v2, 2, v24
	v_add3_u32 v2, s25, v6, v2
	ds_read2_b32 v[6:7], v2 offset1:8
	ds_read2_b32 v[8:9], v2 offset0:33 offset1:41
	ds_read2_b32 v[16:17], v2 offset0:132 offset1:140
	ds_read2_b32 v[18:19], v2 offset0:165 offset1:173
	ds_read2_b32 v[10:11], v2 offset0:66 offset1:74
	ds_read2_b32 v[12:13], v2 offset0:99 offset1:107
	s_waitcnt lgkmcnt(5)
	v_mul_f32_e32 v6, 0x42000000, v6
	s_waitcnt lgkmcnt(4)
	v_mul_f32_e32 v8, 0x42000000, v8
	v_mov_b32_e32 v14, v3
	ds_read2_b32 v[20:21], v2 offset0:198 offset1:206
	ds_read2_b32 v[22:23], v2 offset0:231 offset1:239
	v_cvt_pk_fp8_f32 v14, v6, v8
	s_waitcnt lgkmcnt(5)
	v_mul_f32_e32 v6, 0x42000000, v16
	s_waitcnt lgkmcnt(4)
	v_mul_f32_e32 v8, 0x42000000, v18
	v_mov_b32_e32 v15, v3
	v_cvt_pk_fp8_f32 v15, v6, v8
	v_mul_f32_e32 v7, 0x42000000, v7
	v_mul_f32_e32 v8, 0x42000000, v9
	v_mov_b32_e32 v6, v3
	v_cvt_pk_fp8_f32 v6, v7, v8
	s_waitcnt lgkmcnt(3)
	v_mul_f32_e32 v10, 0x42000000, v10
	s_waitcnt lgkmcnt(2)
	v_mul_f32_e32 v12, 0x42000000, v12
	v_cvt_pk_fp8_f32 v14, v10, v12 op_sel:[0,0,1]
	s_waitcnt lgkmcnt(1)
	v_mul_f32_e32 v10, 0x42000000, v20
	s_waitcnt lgkmcnt(0)
	v_mul_f32_e32 v12, 0x42000000, v22
	v_cvt_pk_fp8_f32 v15, v10, v12 op_sel:[0,0,1]
	v_mul_f32_e32 v9, 0x42000000, v11
	v_mul_f32_e32 v10, 0x42000000, v13
	v_cvt_pk_fp8_f32 v6, v9, v10 op_sel:[0,0,1]
	v_mul_f32_e32 v8, 0x42000000, v17
	v_mul_f32_e32 v9, 0x42000000, v19
	v_mov_b32_e32 v7, v3
	v_cvt_pk_fp8_f32 v7, v8, v9
	v_add_u32_e32 v24, s8, v24
	v_mul_f32_e32 v10, 0x42000000, v21
	v_mul_f32_e32 v11, 0x42000000, v23
	v_cvt_pk_fp8_f32 v7, v10, v11 op_sel:[0,0,1]
	v_add_u32_e32 v8, 8, v24
	v_ashrrev_i32_e32 v9, 31, v8
	v_lshlrev_b64 v[8:9], 10, v[8:9]
	v_lshl_add_u64 v[8:9], v[4:5], 0, v[8:9]
	global_store_dwordx2 v[8:9], v[6:7], off
	ds_read2_b32 v[6:7], v2 offset0:16 offset1:24
	ds_read2_b32 v[8:9], v2 offset0:49 offset1:57
	ds_read2_b32 v[16:17], v2 offset0:148 offset1:156
	ds_read2_b32 v[18:19], v2 offset0:181 offset1:189
	v_ashrrev_i32_e32 v25, 31, v24
	v_lshlrev_b64 v[26:27], 10, v[24:25]
	v_lshl_add_u64 v[26:27], v[4:5], 0, v[26:27]
	ds_read2_b32 v[10:11], v2 offset0:82 offset1:90
	ds_read2_b32 v[12:13], v2 offset0:115 offset1:123
	global_store_dwordx2 v[26:27], v[14:15], off
	s_waitcnt lgkmcnt(5)
	v_mul_f32_e32 v6, 0x42000000, v6
	s_waitcnt lgkmcnt(4)
	v_mul_f32_e32 v8, 0x42000000, v8
	v_mov_b32_e32 v14, v3
	ds_read2_b32 v[20:21], v2 offset0:214 offset1:222
	ds_read2_b32 v[22:23], v2 offset0:247 offset1:255
	v_cvt_pk_fp8_f32 v14, v6, v8
	s_waitcnt lgkmcnt(5)
	v_mul_f32_e32 v6, 0x42000000, v16
	s_waitcnt lgkmcnt(4)
	v_mul_f32_e32 v8, 0x42000000, v18
	v_mov_b32_e32 v15, v3
	v_cvt_pk_fp8_f32 v15, v6, v8
	s_waitcnt lgkmcnt(3)
	v_mul_f32_e32 v10, 0x42000000, v10
	s_waitcnt lgkmcnt(2)
	v_mul_f32_e32 v12, 0x42000000, v12
	v_cvt_pk_fp8_f32 v14, v10, v12 op_sel:[0,0,1]
	s_waitcnt lgkmcnt(1)
	v_mul_f32_e32 v10, 0x42000000, v20
	s_waitcnt lgkmcnt(0)
	v_mul_f32_e32 v2, 0x42000000, v22
	v_cvt_pk_fp8_f32 v15, v10, v2 op_sel:[0,0,1]
	v_mul_f32_e32 v2, 0x42000000, v7
	v_mul_f32_e32 v7, 0x42000000, v9
	v_mov_b32_e32 v6, v3
	v_cvt_pk_fp8_f32 v6, v2, v7
	v_mul_f32_e32 v8, 0x42000000, v11
	v_mul_f32_e32 v9, 0x42000000, v13
	v_mul_f32_e32 v2, 0x42000000, v17
	v_cvt_pk_fp8_f32 v6, v8, v9 op_sel:[0,0,1]
	v_mul_f32_e32 v8, 0x42000000, v19
	v_mov_b32_e32 v7, v3
	v_cvt_pk_fp8_f32 v7, v2, v8
	v_mul_f32_e32 v9, 0x42000000, v21
	v_mul_f32_e32 v10, 0x42000000, v23
	v_add_u32_e32 v26, 16, v24
	v_cvt_pk_fp8_f32 v7, v9, v10 op_sel:[0,0,1]
	v_add_u32_e32 v8, 24, v24
	v_ashrrev_i32_e32 v27, 31, v26
	v_ashrrev_i32_e32 v9, 31, v8
	v_lshlrev_b64 v[26:27], 10, v[26:27]
	v_lshlrev_b64 v[8:9], 10, v[8:9]
	v_lshl_add_u64 v[26:27], v[4:5], 0, v[26:27]
	v_lshl_add_u64 v[4:5], v[4:5], 0, v[8:9]
	global_store_dwordx2 v[26:27], v[14:15], off
	global_store_dwordx2 v[4:5], v[6:7], off
	s_waitcnt lgkmcnt(0)
	s_branch .LBB0_1589

.LBB0_1891:
	s_cmpk_gt_i32 s3, 0x5fff
	s_cselect_b64 s[8:9], -1, 0
	s_cmp_gt_i32 s3, 0xbfff
	s_cselect_b64 s[6:7], -1, 0
	v_cndmask_b32_e64 v2, 0, 1, s[6:7]
	s_cmp_lg_u64 s[8:9], 0
	v_readfirstlane_b32 s4, v2
	s_addc_u32 s51, s4, 0
	s_mul_i32 s4, s51, 0xffffa000
	s_add_i32 s57, s3, s4
	s_cmpk_gt_i32 s57, 0x3fff
	s_mov_b64 s[8:9], -1
	s_cbranch_scc0 .LBB0_1893
	s_lshl_b32 s4, s51, 24
	s_add_i32 s4, s4, 0x6b00000
	s_and_b64 s[8:9], s[6:7], exec
	s_cselect_b32 s4, 0x3db00000, s4
	s_add_u32 s33, s52, s4
	s_load_dwordx2 s[8:9], s[0:1], 0xd8
	s_addc_u32 s76, s53, 0
	s_add_i32 s4, s57, 0xffffc000
	s_lshr_b32 s58, s4, 9
	s_lshl_b32 s4, s51, 4
	s_add_i32 s4, s58, s4
	s_lshl_b64 s[72:73], s[4:5], 22
	s_waitcnt lgkmcnt(0)
	s_add_u32 s72, s8, s72
	s_mov_b32 s59, s5
	s_addc_u32 s73, s9, s73
	s_lshl_b64 s[58:59], s[58:59], 20
	s_add_u32 s9, s33, s58
	s_addc_u32 s8, s76, s59
	s_and_b32 s4, s13, 0x3e0
	v_mov_b32_e32 v22, v1
	s_and_b32 s58, s12, 0x3c0
	s_lshl_b32 s33, s4, 2
	v_ashrrev_i32_e32 v23, 5, v22
	v_add_u32_e32 v4, s58, v23
	s_add_u32 s72, s72, s33
	v_lshlrev_b32_e32 v2, 2, v22
	s_addc_u32 s73, s73, 0
	v_and_b32_e32 v2, 0x7c, v2
	v_ashrrev_i32_e32 v5, 31, v4
	v_lshl_add_u64 v[6:7], s[72:73], 0, v[2:3]
	v_lshlrev_b64 v[4:5], 12, v[4:5]
	v_lshl_add_u64 v[4:5], v[6:7], 0, v[4:5]
	v_add_co_u32_e32 v6, vcc, s14, v4
	s_add_u32 s58, s9, s58
	s_nop 0
	v_addc_co_u32_e32 v7, vcc, 0, v5, vcc
	v_add_co_u32_e32 v8, vcc, s15, v4
	s_addc_u32 s59, s8, 0
	s_nop 0
	v_addc_co_u32_e32 v9, vcc, 0, v5, vcc
	v_add_co_u32_e32 v10, vcc, s16, v4
	s_mov_b64 s[8:9], 0
	s_nop 0
	v_addc_co_u32_e32 v11, vcc, 0, v5, vcc
	v_add_co_u32_e32 v12, vcc, s17, v4
	s_nop 1
	v_addc_co_u32_e32 v13, vcc, 0, v5, vcc
	v_add_co_u32_e32 v14, vcc, s18, v4
	s_nop 1
	v_addc_co_u32_e32 v15, vcc, 0, v5, vcc
	v_add_co_u32_e32 v16, vcc, s19, v4
	s_nop 1
	v_addc_co_u32_e32 v17, vcc, 0, v5, vcc
	v_add_co_u32_e32 v18, vcc, s20, v4
	s_nop 1
	v_addc_co_u32_e32 v19, vcc, 0, v5, vcc
	global_load_dword v24, v[4:5], off nt
	global_load_dword v25, v[6:7], off nt
	global_load_dword v26, v[8:9], off nt
	global_load_dword v27, v[10:11], off nt
	global_load_dword v28, v[12:13], off nt
	global_load_dword v29, v[14:15], off nt
	global_load_dword v30, v[16:17], off nt
	global_load_dword v31, v[18:19], off nt
	v_add_co_u32_e32 v6, vcc, s10, v4
	s_nop 1
	v_addc_co_u32_e32 v7, vcc, 0, v5, vcc
	v_add_co_u32_e32 v8, vcc, s21, v4
	s_nop 1
	v_addc_co_u32_e32 v9, vcc, 0, v5, vcc
	v_add_co_u32_e32 v10, vcc, s22, v4
	s_nop 1
	v_addc_co_u32_e32 v11, vcc, 0, v5, vcc
	v_add_co_u32_e32 v12, vcc, s23, v4
	s_nop 1
	v_addc_co_u32_e32 v13, vcc, 0, v5, vcc
	v_add_co_u32_e32 v14, vcc, s24, v4
	s_nop 1
	v_addc_co_u32_e32 v15, vcc, 0, v5, vcc
	v_add_co_u32_e32 v16, vcc, s25, v4
	s_nop 1
	v_addc_co_u32_e32 v17, vcc, 0, v5, vcc
	v_add_co_u32_e32 v18, vcc, s26, v4
	s_nop 1
	v_addc_co_u32_e32 v19, vcc, 0, v5, vcc
	v_add_co_u32_e32 v20, vcc, s27, v4
	s_nop 1
	v_addc_co_u32_e32 v21, vcc, 0, v5, vcc
	global_load_dword v32, v[6:7], off nt
	global_load_dword v33, v[8:9], off nt
	global_load_dword v34, v[10:11], off nt
	global_load_dword v35, v[12:13], off nt
	global_load_dword v36, v[14:15], off nt
	global_load_dword v37, v[16:17], off nt
	global_load_dword v38, v[18:19], off nt
	global_load_dword v39, v[20:21], off nt
	v_add_co_u32_e32 v6, vcc, s28, v4
	s_nop 1
	v_addc_co_u32_e32 v7, vcc, 0, v5, vcc
	v_add_co_u32_e32 v8, vcc, s29, v4
	s_nop 1
	v_addc_co_u32_e32 v9, vcc, 0, v5, vcc
	v_add_co_u32_e32 v10, vcc, s30, v4
	s_nop 1
	v_addc_co_u32_e32 v11, vcc, 0, v5, vcc
	v_add_co_u32_e32 v12, vcc, s31, v4
	s_nop 1
	v_addc_co_u32_e32 v13, vcc, 0, v5, vcc
	v_add_co_u32_e32 v14, vcc, s34, v4
	s_nop 1
	v_addc_co_u32_e32 v15, vcc, 0, v5, vcc
	v_add_co_u32_e32 v16, vcc, s35, v4
	s_nop 1
	v_addc_co_u32_e32 v17, vcc, 0, v5, vcc
	v_add_co_u32_e32 v18, vcc, s36, v4
	s_nop 1
	v_addc_co_u32_e32 v19, vcc, 0, v5, vcc
	v_add_co_u32_e32 v20, vcc, s37, v4
	s_nop 1
	v_addc_co_u32_e32 v21, vcc, 0, v5, vcc
	global_load_dword v40, v[6:7], off nt
	global_load_dword v41, v[8:9], off nt
	global_load_dword v42, v[10:11], off nt
	global_load_dword v43, v[12:13], off nt
	global_load_dword v44, v[14:15], off nt
	global_load_dword v45, v[16:17], off nt
	global_load_dword v46, v[18:19], off nt
	s_nop 0
	global_load_dword v20, v[20:21], off nt
	v_add_co_u32_e32 v6, vcc, s38, v4
	s_nop 1
	v_addc_co_u32_e32 v7, vcc, 0, v5, vcc
	v_add_co_u32_e32 v8, vcc, s39, v4
	s_nop 1
	v_addc_co_u32_e32 v9, vcc, 0, v5, vcc
	v_add_co_u32_e32 v10, vcc, s41, v4
	s_nop 1
	v_addc_co_u32_e32 v11, vcc, 0, v5, vcc
	v_add_co_u32_e32 v12, vcc, s42, v4
	s_nop 1
	v_addc_co_u32_e32 v13, vcc, 0, v5, vcc
	v_add_co_u32_e32 v14, vcc, s43, v4
	s_nop 1
	v_addc_co_u32_e32 v15, vcc, 0, v5, vcc
	v_add_co_u32_e32 v16, vcc, s45, v4
	s_nop 1
	v_addc_co_u32_e32 v17, vcc, 0, v5, vcc
	v_add_co_u32_e32 v18, vcc, s46, v4
	s_nop 1
	v_addc_co_u32_e32 v19, vcc, 0, v5, vcc
	v_add_co_u32_e32 v4, vcc, s47, v4
	s_nop 1
	v_addc_co_u32_e32 v5, vcc, 0, v5, vcc
	global_load_dword v6, v[6:7], off nt
	s_nop 0
	global_load_dword v7, v[8:9], off nt
	s_nop 0
	global_load_dword v8, v[10:11], off nt
	global_load_dword v9, v[12:13], off nt
	s_nop 0
	global_load_dword v10, v[14:15], off nt
	global_load_dword v11, v[16:17], off nt
	global_load_dword v12, v[18:19], off nt
	s_nop 0
	global_load_dword v4, v[4:5], off nt
	v_mul_lo_u32 v5, v23, s49
	v_add3_u32 v2, s11, v2, v5
	v_add_u32_e32 v5, 0x400, v2
	s_waitcnt vmcnt(30)
	ds_write2_b32 v2, v24, v25 offset1:66
	s_waitcnt vmcnt(28)
	ds_write2_b32 v2, v26, v27 offset0:132 offset1:198
	s_waitcnt vmcnt(26)
	ds_write2_b32 v5, v28, v29 offset0:8 offset1:74
	s_waitcnt vmcnt(24)
	ds_write2_b32 v5, v30, v31 offset0:140 offset1:206
	v_add_u32_e32 v5, 0x800, v2
	s_waitcnt vmcnt(22)
	ds_write2_b32 v5, v32, v33 offset0:16 offset1:82
	s_waitcnt vmcnt(20)
	ds_write2_b32 v5, v34, v35 offset0:148 offset1:214
	v_add_u32_e32 v5, 0xc00, v2
	s_waitcnt vmcnt(18)
	ds_write2_b32 v5, v36, v37 offset0:24 offset1:90
	s_waitcnt vmcnt(16)
	ds_write2_b32 v5, v38, v39 offset0:156 offset1:222
	v_add_u32_e32 v5, 0x1000, v2
	s_waitcnt vmcnt(14)
	ds_write2_b32 v5, v40, v41 offset0:32 offset1:98
	s_waitcnt vmcnt(12)
	ds_write2_b32 v5, v42, v43 offset0:164 offset1:230
	v_add_u32_e32 v5, 0x1400, v2
	s_waitcnt vmcnt(10)
	ds_write2_b32 v5, v44, v45 offset0:40 offset1:106
	s_waitcnt vmcnt(8)
	ds_write2_b32 v5, v46, v20 offset0:172 offset1:238
	v_add_u32_e32 v5, 0x1800, v2
	v_add_u32_e32 v2, 0x1c00, v2
	s_waitcnt vmcnt(6)
	ds_write2_b32 v5, v6, v7 offset0:48 offset1:114
	s_waitcnt vmcnt(4)
	ds_write2_b32 v5, v8, v9 offset0:180 offset1:246
	s_waitcnt vmcnt(2)
	ds_write2_b32 v2, v10, v11 offset0:56 offset1:122
	s_waitcnt vmcnt(0)
	ds_write2_b32 v2, v12, v4 offset0:188 offset1:254
	v_lshlrev_b32_e32 v2, 3, v22
	v_ashrrev_i32_e32 v24, 3, v22
	v_and_b32_e32 v2, 56, v2
	s_waitcnt lgkmcnt(0)
	v_mul_u32_u24_e32 v4, 0x84, v2
	v_lshlrev_b32_e32 v5, 2, v24
	v_add3_u32 v28, s11, v4, v5
	ds_read2_b32 v[4:5], v28 offset1:8
	ds_read2_b32 v[6:7], v28 offset0:33 offset1:41
	ds_read2_b32 v[8:9], v28 offset0:66 offset1:74
	ds_read2_b32 v[12:13], v28 offset0:99 offset1:107
	ds_read2_b32 v[14:15], v28 offset0:132 offset1:140
	ds_read2_b32 v[16:17], v28 offset0:165 offset1:173
	v_lshl_add_u64 v[10:11], s[58:59], 0, v[2:3]
	s_waitcnt lgkmcnt(5)
	v_mul_f32_e32 v2, 0x42000000, v4
	s_waitcnt lgkmcnt(4)
	v_mul_f32_e32 v4, 0x42000000, v6
	v_mov_b32_e32 v18, v3
	ds_read2_b32 v[20:21], v28 offset0:198 offset1:206
	ds_read2_b32 v[22:23], v28 offset0:231 offset1:239
	v_cvt_pk_fp8_f32 v18, v2, v4
	s_waitcnt lgkmcnt(3)
	v_mul_f32_e32 v2, 0x42000000, v14
	s_waitcnt lgkmcnt(2)
	v_mul_f32_e32 v4, 0x42000000, v16
	v_mov_b32_e32 v19, v3
	v_cvt_pk_fp8_f32 v19, v2, v4
	s_waitcnt lgkmcnt(1)
	v_mul_f32_e32 v2, 0x42000000, v20
	s_waitcnt lgkmcnt(0)
	v_mul_f32_e32 v4, 0x42000000, v22
	v_mul_f32_e32 v6, 0x42000000, v8
	v_mul_f32_e32 v8, 0x42000000, v12
	v_cvt_pk_fp8_f32 v19, v2, v4 op_sel:[0,0,1]
	v_mul_f32_e32 v2, 0x42000000, v5
	v_mul_f32_e32 v5, 0x42000000, v7
	v_mov_b32_e32 v4, v3
	v_cvt_pk_fp8_f32 v18, v6, v8 op_sel:[0,0,1]
	v_cvt_pk_fp8_f32 v4, v2, v5
	v_mul_f32_e32 v2, 0x42000000, v15
	v_mul_f32_e32 v8, 0x42000000, v17
	v_mov_b32_e32 v5, v3
	v_cvt_pk_fp8_f32 v5, v2, v8
	v_mul_f32_e32 v6, 0x42000000, v9
	v_mul_f32_e32 v7, 0x42000000, v13
	v_add_u32_e32 v24, s4, v24
	v_cvt_pk_fp8_f32 v4, v6, v7 op_sel:[0,0,1]
	v_mul_f32_e32 v2, 0x42000000, v21
	v_mul_f32_e32 v6, 0x42000000, v23
	v_ashrrev_i32_e32 v25, 31, v24
	v_cvt_pk_fp8_f32 v5, v2, v6 op_sel:[0,0,1]
	v_add_u32_e32 v6, 8, v24
	v_lshlrev_b64 v[26:27], 10, v[24:25]
	v_ashrrev_i32_e32 v7, 31, v6
	v_lshl_add_u64 v[26:27], v[10:11], 0, v[26:27]
	v_lshlrev_b64 v[6:7], 10, v[6:7]
	global_store_dwordx2 v[26:27], v[18:19], off
	v_lshl_add_u64 v[6:7], v[10:11], 0, v[6:7]
	ds_read2_b32 v[8:9], v28 offset0:16 offset1:24
	ds_read2_b32 v[12:13], v28 offset0:49 offset1:57
	ds_read2_b32 v[14:15], v28 offset0:82 offset1:90
	global_store_dwordx2 v[6:7], v[4:5], off
	ds_read2_b32 v[4:5], v28 offset0:115 offset1:123
	ds_read2_b32 v[6:7], v28 offset0:148 offset1:156
	ds_read2_b32 v[16:17], v28 offset0:181 offset1:189
	s_waitcnt lgkmcnt(5)
	v_mul_f32_e32 v2, 0x42000000, v8
	s_waitcnt lgkmcnt(4)
	v_mul_f32_e32 v8, 0x42000000, v12
	v_mov_b32_e32 v18, v3
	ds_read2_b32 v[20:21], v28 offset0:214 offset1:222
	ds_read2_b32 v[22:23], v28 offset0:247 offset1:255
	v_cvt_pk_fp8_f32 v18, v2, v8
	s_waitcnt lgkmcnt(3)
	v_mul_f32_e32 v2, 0x42000000, v6
	s_waitcnt lgkmcnt(2)
	v_mul_f32_e32 v6, 0x42000000, v16
	v_mov_b32_e32 v19, v3
	v_cvt_pk_fp8_f32 v19, v2, v6
	v_mul_f32_e32 v12, 0x42000000, v14
	v_mul_f32_e32 v4, 0x42000000, v4
	v_cvt_pk_fp8_f32 v18, v12, v4 op_sel:[0,0,1]
	s_waitcnt lgkmcnt(1)
	v_mul_f32_e32 v2, 0x42000000, v20
	s_waitcnt lgkmcnt(0)
	v_mul_f32_e32 v4, 0x42000000, v22
	v_cvt_pk_fp8_f32 v19, v2, v4 op_sel:[0,0,1]
	v_mul_f32_e32 v2, 0x42000000, v9
	v_mul_f32_e32 v6, 0x42000000, v13
	v_mov_b32_e32 v4, v3
	v_mul_f32_e32 v9, 0x42000000, v5
	v_cvt_pk_fp8_f32 v4, v2, v6
	v_mul_f32_e32 v2, 0x42000000, v7
	v_mul_f32_e32 v6, 0x42000000, v17
	v_mov_b32_e32 v5, v3
	v_cvt_pk_fp8_f32 v5, v2, v6
	v_mul_f32_e32 v8, 0x42000000, v15
	v_mul_f32_e32 v2, 0x42000000, v21
	v_mul_f32_e32 v6, 0x42000000, v23
	v_add_u32_e32 v26, 16, v24
	v_cvt_pk_fp8_f32 v4, v8, v9 op_sel:[0,0,1]
	v_cvt_pk_fp8_f32 v5, v2, v6 op_sel:[0,0,1]
	v_add_u32_e32 v6, 24, v24
	v_ashrrev_i32_e32 v27, 31, v26
	v_ashrrev_i32_e32 v7, 31, v6
	v_lshlrev_b64 v[26:27], 10, v[26:27]
	v_lshlrev_b64 v[6:7], 10, v[6:7]
	v_lshl_add_u64 v[26:27], v[10:11], 0, v[26:27]
	v_lshl_add_u64 v[6:7], v[10:11], 0, v[6:7]
	global_store_dwordx2 v[26:27], v[18:19], off
	global_store_dwordx2 v[6:7], v[4:5], off
	s_waitcnt lgkmcnt(0)
.LBB0_1893:
	s_andn2_b64 vcc, exec, s[8:9]
	s_cbranch_vccnz .LBB0_1890
	s_lshl_b32 s4, s51, 25
	s_add_i32 s4, s4, 0x2b00000
	s_and_b64 s[6:7], s[6:7], exec
	s_cselect_b32 s4, 0x3bb00000, s4
	s_add_u32 s4, s52, s4
	s_addc_u32 s33, s53, 0
	s_ashr_i32 s6, s57, 10
	s_bfe_u32 s57, s3, 0x10009
	s_and_b32 s72, s13, 0x3e0
	s_cmp_eq_u32 s57, 0
	s_cselect_b32 s7, s50, 0xd0
	s_add_u32 s8, s0, s7
	s_addc_u32 s9, s1, 0
	s_load_dwordx2 s[8:9], s[8:9], 0x0
	s_lshl_b32 s7, s51, 4
	s_add_i32 s58, s6, s7
	s_ashr_i32 s59, s58, 31
	s_lshl_b64 s[58:59], s[58:59], 22
	s_waitcnt lgkmcnt(0)
	s_add_u32 s51, s8, s58
	s_addc_u32 s59, s9, s59
	s_ashr_i32 s7, s6, 31
	s_lshl_b64 s[8:9], s[6:7], 21
	s_add_u32 s7, s4, s8
	s_addc_u32 s6, s33, s9
	s_lshl_b32 s4, s13, 1
	s_and_b32 s4, s4, 0x700
	s_lshl_b32 s9, s57, 7
	s_or_b32 s4, s4, s9
	s_and_b32 s9, s13, 0x60
	v_mov_b32_e32 v22, v1
	s_and_b32 s8, s12, 0x3c0
	s_or_b32 s4, s4, s9
	s_lshl_b32 s9, s72, 2
	v_ashrrev_i32_e32 v23, 5, v22
	v_add_u32_e32 v4, s8, v23
	s_add_u32 s58, s51, s9
	v_lshlrev_b32_e32 v2, 2, v22
	s_addc_u32 s59, s59, 0
	v_and_b32_e32 v2, 0x7c, v2
	v_ashrrev_i32_e32 v5, 31, v4
	v_lshl_add_u64 v[6:7], s[58:59], 0, v[2:3]
	v_lshlrev_b64 v[4:5], 12, v[4:5]
	v_lshl_add_u64 v[4:5], v[6:7], 0, v[4:5]
	v_add_co_u32_e32 v6, vcc, s14, v4
	s_add_u32 s8, s7, s8
	s_nop 0
	v_addc_co_u32_e32 v7, vcc, 0, v5, vcc
	v_add_co_u32_e32 v8, vcc, s15, v4
	s_addc_u32 s9, s6, 0
	s_nop 0
	v_addc_co_u32_e32 v9, vcc, 0, v5, vcc
	v_add_co_u32_e32 v10, vcc, s16, v4
	s_nop 1
	v_addc_co_u32_e32 v11, vcc, 0, v5, vcc
	v_add_co_u32_e32 v12, vcc, s17, v4
	s_nop 1
	v_addc_co_u32_e32 v13, vcc, 0, v5, vcc
	v_add_co_u32_e32 v14, vcc, s18, v4
	s_nop 1
	v_addc_co_u32_e32 v15, vcc, 0, v5, vcc
	v_add_co_u32_e32 v16, vcc, s19, v4
	s_nop 1
	v_addc_co_u32_e32 v17, vcc, 0, v5, vcc
	v_add_co_u32_e32 v18, vcc, s20, v4
	s_nop 1
	v_addc_co_u32_e32 v19, vcc, 0, v5, vcc
	global_load_dword v24, v[4:5], off nt
	global_load_dword v25, v[6:7], off nt
	global_load_dword v26, v[8:9], off nt
	global_load_dword v27, v[10:11], off nt
	global_load_dword v28, v[12:13], off nt
	global_load_dword v29, v[14:15], off nt
	global_load_dword v30, v[16:17], off nt
	global_load_dword v31, v[18:19], off nt
	v_add_co_u32_e32 v6, vcc, s10, v4
	s_nop 1
	v_addc_co_u32_e32 v7, vcc, 0, v5, vcc
	v_add_co_u32_e32 v8, vcc, s21, v4
	s_nop 1
	v_addc_co_u32_e32 v9, vcc, 0, v5, vcc
	v_add_co_u32_e32 v10, vcc, s22, v4
	s_nop 1
	v_addc_co_u32_e32 v11, vcc, 0, v5, vcc
	v_add_co_u32_e32 v12, vcc, s23, v4
	s_nop 1
	v_addc_co_u32_e32 v13, vcc, 0, v5, vcc
	v_add_co_u32_e32 v14, vcc, s24, v4
	s_nop 1
	v_addc_co_u32_e32 v15, vcc, 0, v5, vcc
	v_add_co_u32_e32 v16, vcc, s25, v4
	s_nop 1
	v_addc_co_u32_e32 v17, vcc, 0, v5, vcc
	v_add_co_u32_e32 v18, vcc, s26, v4
	s_nop 1
	v_addc_co_u32_e32 v19, vcc, 0, v5, vcc
	v_add_co_u32_e32 v20, vcc, s27, v4
	s_nop 1
	v_addc_co_u32_e32 v21, vcc, 0, v5, vcc
	global_load_dword v32, v[6:7], off nt
	global_load_dword v33, v[8:9], off nt
	global_load_dword v34, v[10:11], off nt
	global_load_dword v35, v[12:13], off nt
	global_load_dword v36, v[14:15], off nt
	global_load_dword v37, v[16:17], off nt
	global_load_dword v38, v[18:19], off nt
	global_load_dword v39, v[20:21], off nt
	v_add_co_u32_e32 v6, vcc, s28, v4
	s_nop 1
	v_addc_co_u32_e32 v7, vcc, 0, v5, vcc
	v_add_co_u32_e32 v8, vcc, s29, v4
	s_nop 1
	v_addc_co_u32_e32 v9, vcc, 0, v5, vcc
	v_add_co_u32_e32 v10, vcc, s30, v4
	s_nop 1
	v_addc_co_u32_e32 v11, vcc, 0, v5, vcc
	v_add_co_u32_e32 v12, vcc, s31, v4
	s_nop 1
	v_addc_co_u32_e32 v13, vcc, 0, v5, vcc
	v_add_co_u32_e32 v14, vcc, s34, v4
	s_nop 1
	v_addc_co_u32_e32 v15, vcc, 0, v5, vcc
	v_add_co_u32_e32 v16, vcc, s35, v4
	s_nop 1
	v_addc_co_u32_e32 v17, vcc, 0, v5, vcc
	v_add_co_u32_e32 v18, vcc, s36, v4
	s_nop 1
	v_addc_co_u32_e32 v19, vcc, 0, v5, vcc
	v_add_co_u32_e32 v20, vcc, s37, v4
	s_nop 1
	v_addc_co_u32_e32 v21, vcc, 0, v5, vcc
	global_load_dword v40, v[6:7], off nt
	global_load_dword v41, v[8:9], off nt
	global_load_dword v42, v[10:11], off nt
	global_load_dword v43, v[12:13], off nt
	global_load_dword v44, v[14:15], off nt
	global_load_dword v45, v[16:17], off nt
	global_load_dword v46, v[18:19], off nt
	s_nop 0
	global_load_dword v20, v[20:21], off nt
	v_add_co_u32_e32 v6, vcc, s38, v4
	s_nop 1
	v_addc_co_u32_e32 v7, vcc, 0, v5, vcc
	v_add_co_u32_e32 v8, vcc, s39, v4
	s_nop 1
	v_addc_co_u32_e32 v9, vcc, 0, v5, vcc
	v_add_co_u32_e32 v10, vcc, s41, v4
	s_nop 1
	v_addc_co_u32_e32 v11, vcc, 0, v5, vcc
	v_add_co_u32_e32 v12, vcc, s42, v4
	s_nop 1
	v_addc_co_u32_e32 v13, vcc, 0, v5, vcc
	v_add_co_u32_e32 v14, vcc, s43, v4
	s_nop 1
	v_addc_co_u32_e32 v15, vcc, 0, v5, vcc
	v_add_co_u32_e32 v16, vcc, s45, v4
	s_nop 1
	v_addc_co_u32_e32 v17, vcc, 0, v5, vcc
	v_add_co_u32_e32 v18, vcc, s46, v4
	s_nop 1
	v_addc_co_u32_e32 v19, vcc, 0, v5, vcc
	v_add_co_u32_e32 v4, vcc, s47, v4
	s_nop 1
	v_addc_co_u32_e32 v5, vcc, 0, v5, vcc
	global_load_dword v6, v[6:7], off nt
	s_nop 0
	global_load_dword v7, v[8:9], off nt
	s_nop 0
	global_load_dword v8, v[10:11], off nt
	global_load_dword v9, v[12:13], off nt
	s_nop 0
	global_load_dword v10, v[14:15], off nt
	global_load_dword v11, v[16:17], off nt
	global_load_dword v12, v[18:19], off nt
	s_nop 0
	global_load_dword v4, v[4:5], off nt
	v_mul_lo_u32 v5, v23, s49
	v_add3_u32 v2, s11, v2, v5
	v_add_u32_e32 v5, 0x400, v2
	s_waitcnt vmcnt(30)
	ds_write2_b32 v2, v24, v25 offset1:66
	s_waitcnt vmcnt(28)
	ds_write2_b32 v2, v26, v27 offset0:132 offset1:198
	s_waitcnt vmcnt(26)
	ds_write2_b32 v5, v28, v29 offset0:8 offset1:74
	s_waitcnt vmcnt(24)
	ds_write2_b32 v5, v30, v31 offset0:140 offset1:206
	v_add_u32_e32 v5, 0x800, v2
	s_waitcnt vmcnt(22)
	ds_write2_b32 v5, v32, v33 offset0:16 offset1:82
	s_waitcnt vmcnt(20)
	ds_write2_b32 v5, v34, v35 offset0:148 offset1:214
	v_add_u32_e32 v5, 0xc00, v2
	s_waitcnt vmcnt(18)
	ds_write2_b32 v5, v36, v37 offset0:24 offset1:90
	s_waitcnt vmcnt(16)
	ds_write2_b32 v5, v38, v39 offset0:156 offset1:222
	v_add_u32_e32 v5, 0x1000, v2
	s_waitcnt vmcnt(14)
	ds_write2_b32 v5, v40, v41 offset0:32 offset1:98
	s_waitcnt vmcnt(12)
	ds_write2_b32 v5, v42, v43 offset0:164 offset1:230
	v_add_u32_e32 v5, 0x1400, v2
	s_waitcnt vmcnt(10)
	ds_write2_b32 v5, v44, v45 offset0:40 offset1:106
	s_waitcnt vmcnt(8)
	ds_write2_b32 v5, v46, v20 offset0:172 offset1:238
	v_add_u32_e32 v5, 0x1800, v2
	v_add_u32_e32 v2, 0x1c00, v2
	s_waitcnt vmcnt(6)
	ds_write2_b32 v5, v6, v7 offset0:48 offset1:114
	s_waitcnt vmcnt(4)
	ds_write2_b32 v5, v8, v9 offset0:180 offset1:246
	s_waitcnt vmcnt(2)
	ds_write2_b32 v2, v10, v11 offset0:56 offset1:122
	s_waitcnt vmcnt(0)
	ds_write2_b32 v2, v12, v4 offset0:188 offset1:254
	v_lshlrev_b32_e32 v2, 3, v22
	v_ashrrev_i32_e32 v24, 3, v22
	v_and_b32_e32 v2, 56, v2
	s_waitcnt lgkmcnt(0)
	v_mul_u32_u24_e32 v4, 0x84, v2
	v_lshlrev_b32_e32 v5, 2, v24
	v_add3_u32 v28, s11, v4, v5
	ds_read2_b32 v[4:5], v28 offset1:8
	ds_read2_b32 v[6:7], v28 offset0:33 offset1:41
	ds_read2_b32 v[8:9], v28 offset0:66 offset1:74
	ds_read2_b32 v[12:13], v28 offset0:99 offset1:107
	ds_read2_b32 v[14:15], v28 offset0:132 offset1:140
	ds_read2_b32 v[16:17], v28 offset0:165 offset1:173
	v_lshl_add_u64 v[10:11], s[8:9], 0, v[2:3]
	s_waitcnt lgkmcnt(5)
	v_mul_f32_e32 v2, 0x42000000, v4
	s_waitcnt lgkmcnt(4)
	v_mul_f32_e32 v4, 0x42000000, v6
	v_mov_b32_e32 v18, v3
	ds_read2_b32 v[20:21], v28 offset0:198 offset1:206
	ds_read2_b32 v[22:23], v28 offset0:231 offset1:239
	v_cvt_pk_fp8_f32 v18, v2, v4
	s_waitcnt lgkmcnt(3)
	v_mul_f32_e32 v2, 0x42000000, v14
	s_waitcnt lgkmcnt(2)
	v_mul_f32_e32 v4, 0x42000000, v16
	v_mov_b32_e32 v19, v3
	v_cvt_pk_fp8_f32 v19, v2, v4
	s_waitcnt lgkmcnt(1)
	v_mul_f32_e32 v2, 0x42000000, v20
	s_waitcnt lgkmcnt(0)
	v_mul_f32_e32 v4, 0x42000000, v22
	v_mul_f32_e32 v6, 0x42000000, v8
	v_mul_f32_e32 v8, 0x42000000, v12
	v_cvt_pk_fp8_f32 v19, v2, v4 op_sel:[0,0,1]
	v_mul_f32_e32 v2, 0x42000000, v5
	v_mul_f32_e32 v5, 0x42000000, v7
	v_mov_b32_e32 v4, v3
	v_cvt_pk_fp8_f32 v18, v6, v8 op_sel:[0,0,1]
	v_cvt_pk_fp8_f32 v4, v2, v5
	v_mul_f32_e32 v2, 0x42000000, v15
	v_mul_f32_e32 v8, 0x42000000, v17
	v_mov_b32_e32 v5, v3
	v_cvt_pk_fp8_f32 v5, v2, v8
	v_mul_f32_e32 v6, 0x42000000, v9
	v_mul_f32_e32 v7, 0x42000000, v13
	v_add_u32_e32 v24, s4, v24
	v_cvt_pk_fp8_f32 v4, v6, v7 op_sel:[0,0,1]
	v_mul_f32_e32 v2, 0x42000000, v21
	v_mul_f32_e32 v6, 0x42000000, v23
	v_ashrrev_i32_e32 v25, 31, v24
	v_cvt_pk_fp8_f32 v5, v2, v6 op_sel:[0,0,1]
	v_add_u32_e32 v6, 8, v24
	v_lshlrev_b64 v[26:27], 10, v[24:25]
	v_ashrrev_i32_e32 v7, 31, v6
	v_lshl_add_u64 v[26:27], v[10:11], 0, v[26:27]
	v_lshlrev_b64 v[6:7], 10, v[6:7]
	global_store_dwordx2 v[26:27], v[18:19], off
	v_lshl_add_u64 v[6:7], v[10:11], 0, v[6:7]
	ds_read2_b32 v[8:9], v28 offset0:16 offset1:24
	ds_read2_b32 v[12:13], v28 offset0:49 offset1:57
	ds_read2_b32 v[14:15], v28 offset0:82 offset1:90
	global_store_dwordx2 v[6:7], v[4:5], off
	ds_read2_b32 v[4:5], v28 offset0:115 offset1:123
	ds_read2_b32 v[6:7], v28 offset0:148 offset1:156
	ds_read2_b32 v[16:17], v28 offset0:181 offset1:189
	s_waitcnt lgkmcnt(5)
	v_mul_f32_e32 v2, 0x42000000, v8
	s_waitcnt lgkmcnt(4)
	v_mul_f32_e32 v8, 0x42000000, v12
	v_mov_b32_e32 v18, v3
	ds_read2_b32 v[20:21], v28 offset0:214 offset1:222
	ds_read2_b32 v[22:23], v28 offset0:247 offset1:255
	v_cvt_pk_fp8_f32 v18, v2, v8
	s_waitcnt lgkmcnt(3)
	v_mul_f32_e32 v2, 0x42000000, v6
	s_waitcnt lgkmcnt(2)
	v_mul_f32_e32 v6, 0x42000000, v16
	v_mov_b32_e32 v19, v3
	v_cvt_pk_fp8_f32 v19, v2, v6
	v_mul_f32_e32 v12, 0x42000000, v14
	v_mul_f32_e32 v4, 0x42000000, v4
	v_cvt_pk_fp8_f32 v18, v12, v4 op_sel:[0,0,1]
	s_waitcnt lgkmcnt(1)
	v_mul_f32_e32 v2, 0x42000000, v20
	s_waitcnt lgkmcnt(0)
	v_mul_f32_e32 v4, 0x42000000, v22
	v_cvt_pk_fp8_f32 v19, v2, v4 op_sel:[0,0,1]
	v_mul_f32_e32 v2, 0x42000000, v9
	v_mul_f32_e32 v6, 0x42000000, v13
	v_mov_b32_e32 v4, v3
	v_mul_f32_e32 v9, 0x42000000, v5
	v_cvt_pk_fp8_f32 v4, v2, v6
	v_mul_f32_e32 v2, 0x42000000, v7
	v_mul_f32_e32 v6, 0x42000000, v17
	v_mov_b32_e32 v5, v3
	v_cvt_pk_fp8_f32 v5, v2, v6
	v_mul_f32_e32 v8, 0x42000000, v15
	v_mul_f32_e32 v2, 0x42000000, v21
	v_mul_f32_e32 v6, 0x42000000, v23
	v_add_u32_e32 v26, 16, v24
	v_cvt_pk_fp8_f32 v4, v8, v9 op_sel:[0,0,1]
	v_cvt_pk_fp8_f32 v5, v2, v6 op_sel:[0,0,1]
	v_add_u32_e32 v6, 24, v24
	v_ashrrev_i32_e32 v27, 31, v26
	v_ashrrev_i32_e32 v7, 31, v6
	v_lshlrev_b64 v[26:27], 10, v[26:27]
	v_lshlrev_b64 v[6:7], 10, v[6:7]
	v_lshl_add_u64 v[26:27], v[10:11], 0, v[26:27]
	v_lshl_add_u64 v[6:7], v[10:11], 0, v[6:7]
	global_store_dwordx2 v[26:27], v[18:19], off
	global_store_dwordx2 v[6:7], v[4:5], off
	s_waitcnt lgkmcnt(0)
	s_branch .LBB0_1890

.LBB0_2359:
	s_cmp_ge_u32 s87, s18
	s_cbranch_scc1 .LBB0_2358
	s_cmpk_gt_i32 s87, 0x5fff
	s_cselect_b64 s[14:15], -1, 0
	s_cmp_gt_i32 s87, 0xbfff
	v_cndmask_b32_e64 v2, 0, 1, s[14:15]
	s_cselect_b64 s[14:15], -1, 0
	s_cmp_gt_i32 s87, 0x11fff
	v_cndmask_b32_e64 v4, 0, 1, s[14:15]
	s_cselect_b64 s[14:15], -1, 0
	v_readfirstlane_b32 s8, v2
	v_readfirstlane_b32 s16, v4
	s_cmp_lg_u64 s[14:15], 0
	s_addc_u32 s90, s8, s16
	s_mul_i32 s8, s90, 0xffffa000
	s_add_i32 s91, s87, s8
	s_cmp_lg_u32 s90, 3
	s_cselect_b32 s92, s90, 0
	s_cmp_eq_u32 s92, 2
	s_cselect_b64 s[14:15], -1, 0
	s_cmpk_gt_i32 s91, 0x3fff
	s_mov_b64 s[16:17], -1
	s_cbranch_scc0 .LBB0_2362
	s_lshl_b32 s8, s92, 24
	s_add_i32 s8, s8, 0x6b00000
	s_and_b64 s[16:17], s[14:15], exec
	s_cselect_b32 s8, 0x3db00000, s8
	s_add_u32 s33, s52, s8
	s_load_dwordx2 s[76:77], s[0:1], 0xd8
	s_addc_u32 s93, s53, 0
	s_add_i32 s8, s91, 0xffffc000
	s_lshr_b32 s16, s8, 9
	s_lshl_b32 s8, s90, 4
	s_add_i32 s8, s16, s8
	s_lshl_b64 s[80:81], s[8:9], 22
	s_waitcnt lgkmcnt(0)
	s_add_u32 s76, s76, s80
	s_mov_b32 s17, s9
	s_addc_u32 s77, s77, s81
	s_lshl_b64 s[16:17], s[16:17], 20
	s_add_u32 s16, s33, s16
	s_addc_u32 s17, s93, s17
	s_and_b32 s8, s88, 0x3e0
	v_mov_b32_e32 v8, v1
	s_and_b32 s93, s89, 0x3c0
	s_lshl_b32 s33, s8, 2
	v_ashrrev_i32_e32 v9, 5, v8
	v_add_u32_e32 v4, s93, v9
	s_add_u32 s76, s76, s33
	v_lshlrev_b32_e32 v2, 2, v8
	s_addc_u32 s77, s77, 0
	v_and_b32_e32 v2, 0x7c, v2
	v_ashrrev_i32_e32 v5, 31, v4
	v_lshl_add_u64 v[6:7], s[76:77], 0, v[2:3]
	v_lshlrev_b64 v[4:5], 12, v[4:5]
	v_lshl_add_u64 v[4:5], v[6:7], 0, v[4:5]
	v_add_co_u32_e32 v6, vcc, s26, v4
	global_load_dword v10, v[4:5], off nt
	s_nop 0
	v_addc_co_u32_e32 v7, vcc, 0, v5, vcc
	global_load_dword v11, v[6:7], off nt
	v_add_co_u32_e32 v6, vcc, s27, v4
	s_add_u32 s16, s16, s93
	s_nop 0
	v_addc_co_u32_e32 v7, vcc, 0, v5, vcc
	global_load_dword v12, v[6:7], off nt
	v_add_co_u32_e32 v6, vcc, s28, v4
	s_addc_u32 s17, s17, 0
	s_nop 0
	v_addc_co_u32_e32 v7, vcc, 0, v5, vcc
	global_load_dword v13, v[6:7], off nt
	v_add_co_u32_e32 v6, vcc, s29, v4
	s_nop 1
	v_addc_co_u32_e32 v7, vcc, 0, v5, vcc
	global_load_dword v14, v[6:7], off nt
	v_add_co_u32_e32 v6, vcc, s30, v4
	s_nop 1
	v_addc_co_u32_e32 v7, vcc, 0, v5, vcc
	global_load_dword v15, v[6:7], off nt
	v_add_co_u32_e32 v6, vcc, s3, v4
	s_nop 1
	v_addc_co_u32_e32 v7, vcc, 0, v5, vcc
	global_load_dword v16, v[6:7], off nt
	v_add_co_u32_e32 v6, vcc, s31, v4
	s_nop 1
	v_addc_co_u32_e32 v7, vcc, 0, v5, vcc
	global_load_dword v17, v[6:7], off nt
	v_add_co_u32_e32 v6, vcc, s24, v4
	s_nop 1
	v_addc_co_u32_e32 v7, vcc, 0, v5, vcc
	global_load_dword v18, v[6:7], off nt
	v_add_co_u32_e32 v6, vcc, s20, v4
	s_nop 1
	v_addc_co_u32_e32 v7, vcc, 0, v5, vcc
	global_load_dword v19, v[6:7], off nt
	v_add_co_u32_e32 v6, vcc, s34, v4
	s_nop 1
	v_addc_co_u32_e32 v7, vcc, 0, v5, vcc
	global_load_dword v20, v[6:7], off nt
	v_add_co_u32_e32 v6, vcc, s35, v4
	s_nop 1
	v_addc_co_u32_e32 v7, vcc, 0, v5, vcc
	global_load_dword v21, v[6:7], off nt
	v_add_co_u32_e32 v6, vcc, s36, v4
	s_nop 1
	v_addc_co_u32_e32 v7, vcc, 0, v5, vcc
	global_load_dword v22, v[6:7], off nt
	v_add_co_u32_e32 v6, vcc, s37, v4
	s_nop 1
	v_addc_co_u32_e32 v7, vcc, 0, v5, vcc
	global_load_dword v23, v[6:7], off nt
	v_add_co_u32_e32 v6, vcc, s38, v4
	s_nop 1
	v_addc_co_u32_e32 v7, vcc, 0, v5, vcc
	global_load_dword v24, v[6:7], off nt
	v_add_co_u32_e32 v6, vcc, s39, v4
	s_nop 1
	v_addc_co_u32_e32 v7, vcc, 0, v5, vcc
	global_load_dword v25, v[6:7], off nt
	v_add_co_u32_e32 v6, vcc, s41, v4
	s_nop 1
	v_addc_co_u32_e32 v7, vcc, 0, v5, vcc
	global_load_dword v26, v[6:7], off nt
	v_add_co_u32_e32 v6, vcc, s42, v4
	s_nop 1
	v_addc_co_u32_e32 v7, vcc, 0, v5, vcc
	global_load_dword v27, v[6:7], off nt
	v_add_co_u32_e32 v6, vcc, s43, v4
	s_nop 1
	v_addc_co_u32_e32 v7, vcc, 0, v5, vcc
	global_load_dword v28, v[6:7], off nt
	v_add_co_u32_e32 v6, vcc, s45, v4
	s_nop 1
	v_addc_co_u32_e32 v7, vcc, 0, v5, vcc
	global_load_dword v29, v[6:7], off nt
	v_add_co_u32_e32 v6, vcc, s46, v4
	s_nop 1
	v_addc_co_u32_e32 v7, vcc, 0, v5, vcc
	global_load_dword v30, v[6:7], off nt
	v_add_co_u32_e32 v6, vcc, s47, v4
	s_nop 1
	v_addc_co_u32_e32 v7, vcc, 0, v5, vcc
	global_load_dword v31, v[6:7], off nt
	v_add_co_u32_e32 v6, vcc, s49, v4
	s_nop 1
	v_addc_co_u32_e32 v7, vcc, 0, v5, vcc
	global_load_dword v32, v[6:7], off nt
	v_add_co_u32_e32 v6, vcc, s57, v4
	s_nop 1
	v_addc_co_u32_e32 v7, vcc, 0, v5, vcc
	global_load_dword v33, v[6:7], off nt
	v_add_co_u32_e32 v6, vcc, s58, v4
	s_nop 1
	v_addc_co_u32_e32 v7, vcc, 0, v5, vcc
	global_load_dword v34, v[6:7], off nt
	v_add_co_u32_e32 v6, vcc, s59, v4
	s_nop 1
	v_addc_co_u32_e32 v7, vcc, 0, v5, vcc
	global_load_dword v35, v[6:7], off nt
	v_add_co_u32_e32 v6, vcc, s72, v4
	s_nop 1
	v_addc_co_u32_e32 v7, vcc, 0, v5, vcc
	global_load_dword v36, v[6:7], off nt
	v_add_co_u32_e32 v6, vcc, s73, v4
	s_nop 1
	v_addc_co_u32_e32 v7, vcc, 0, v5, vcc
	global_load_dword v37, v[6:7], off nt
	v_add_co_u32_e32 v6, vcc, s78, v4
	s_nop 1
	v_addc_co_u32_e32 v7, vcc, 0, v5, vcc
	global_load_dword v38, v[6:7], off nt
	v_add_co_u32_e32 v6, vcc, s79, v4
	s_nop 1
	v_addc_co_u32_e32 v7, vcc, 0, v5, vcc
	global_load_dword v39, v[6:7], off nt
	v_add_co_u32_e32 v6, vcc, s84, v4
	s_nop 1
	v_addc_co_u32_e32 v7, vcc, 0, v5, vcc
	v_add_co_u32_e32 v4, vcc, s85, v4
	global_load_dword v6, v[6:7], off nt
	s_nop 0
	v_addc_co_u32_e32 v5, vcc, 0, v5, vcc
	global_load_dword v4, v[4:5], off nt
	v_mul_lo_u32 v5, v9, s86
	v_add3_u32 v2, s25, v2, v5
	v_add_u32_e32 v5, 0x400, v2
	s_waitcnt vmcnt(30)
	ds_write2_b32 v2, v10, v11 offset1:66
	s_waitcnt vmcnt(28)
	ds_write2_b32 v2, v12, v13 offset0:132 offset1:198
	s_waitcnt vmcnt(26)
	ds_write2_b32 v5, v14, v15 offset0:8 offset1:74
	s_waitcnt vmcnt(24)
	ds_write2_b32 v5, v16, v17 offset0:140 offset1:206
	v_add_u32_e32 v5, 0x800, v2
	s_waitcnt vmcnt(22)
	ds_write2_b32 v5, v18, v19 offset0:16 offset1:82
	s_waitcnt vmcnt(20)
	ds_write2_b32 v5, v20, v21 offset0:148 offset1:214
	v_add_u32_e32 v5, 0xc00, v2
	s_waitcnt vmcnt(18)
	ds_write2_b32 v5, v22, v23 offset0:24 offset1:90
	s_waitcnt vmcnt(16)
	ds_write2_b32 v5, v24, v25 offset0:156 offset1:222
	v_add_u32_e32 v5, 0x1000, v2
	s_waitcnt vmcnt(14)
	ds_write2_b32 v5, v26, v27 offset0:32 offset1:98
	s_waitcnt vmcnt(12)
	ds_write2_b32 v5, v28, v29 offset0:164 offset1:230
	v_add_u32_e32 v5, 0x1400, v2
	s_waitcnt vmcnt(10)
	ds_write2_b32 v5, v30, v31 offset0:40 offset1:106
	s_waitcnt vmcnt(8)
	ds_write2_b32 v5, v32, v33 offset0:172 offset1:238
	v_add_u32_e32 v5, 0x1800, v2
	v_add_u32_e32 v2, 0x1c00, v2
	s_waitcnt vmcnt(6)
	ds_write2_b32 v5, v34, v35 offset0:48 offset1:114
	s_waitcnt vmcnt(4)
	ds_write2_b32 v5, v36, v37 offset0:180 offset1:246
	s_waitcnt vmcnt(2)
	ds_write2_b32 v2, v38, v39 offset0:56 offset1:122
	s_waitcnt vmcnt(0)
	ds_write2_b32 v2, v6, v4 offset0:188 offset1:254
	v_lshlrev_b32_e32 v2, 3, v8
	v_ashrrev_i32_e32 v24, 3, v8
	v_and_b32_e32 v2, 56, v2
	s_waitcnt lgkmcnt(0)
	v_mul_u32_u24_e32 v6, 0x84, v2
	v_lshl_add_u64 v[4:5], s[16:17], 0, v[2:3]
	v_lshlrev_b32_e32 v2, 2, v24
	v_add3_u32 v2, s25, v6, v2
	ds_read2_b32 v[6:7], v2 offset1:8
	ds_read2_b32 v[8:9], v2 offset0:33 offset1:41
	ds_read2_b32 v[16:17], v2 offset0:132 offset1:140
	ds_read2_b32 v[18:19], v2 offset0:165 offset1:173
	ds_read2_b32 v[10:11], v2 offset0:66 offset1:74
	ds_read2_b32 v[12:13], v2 offset0:99 offset1:107
	s_waitcnt lgkmcnt(5)
	v_mul_f32_e32 v6, 0x42000000, v6
	s_waitcnt lgkmcnt(4)
	v_mul_f32_e32 v8, 0x42000000, v8
	v_mov_b32_e32 v14, v3
	ds_read2_b32 v[20:21], v2 offset0:198 offset1:206
	ds_read2_b32 v[22:23], v2 offset0:231 offset1:239
	v_cvt_pk_fp8_f32 v14, v6, v8
	s_waitcnt lgkmcnt(5)
	v_mul_f32_e32 v6, 0x42000000, v16
	s_waitcnt lgkmcnt(4)
	v_mul_f32_e32 v8, 0x42000000, v18
	v_mov_b32_e32 v15, v3
	v_cvt_pk_fp8_f32 v15, v6, v8
	v_mul_f32_e32 v7, 0x42000000, v7
	v_mul_f32_e32 v8, 0x42000000, v9
	v_mov_b32_e32 v6, v3
	v_cvt_pk_fp8_f32 v6, v7, v8
	s_waitcnt lgkmcnt(3)
	v_mul_f32_e32 v10, 0x42000000, v10
	s_waitcnt lgkmcnt(2)
	v_mul_f32_e32 v12, 0x42000000, v12
	v_cvt_pk_fp8_f32 v14, v10, v12 op_sel:[0,0,1]
	s_waitcnt lgkmcnt(1)
	v_mul_f32_e32 v10, 0x42000000, v20
	s_waitcnt lgkmcnt(0)
	v_mul_f32_e32 v12, 0x42000000, v22
	v_cvt_pk_fp8_f32 v15, v10, v12 op_sel:[0,0,1]
	v_mul_f32_e32 v9, 0x42000000, v11
	v_mul_f32_e32 v10, 0x42000000, v13
	v_cvt_pk_fp8_f32 v6, v9, v10 op_sel:[0,0,1]
	v_mul_f32_e32 v8, 0x42000000, v17
	v_mul_f32_e32 v9, 0x42000000, v19
	v_mov_b32_e32 v7, v3
	v_cvt_pk_fp8_f32 v7, v8, v9
	v_add_u32_e32 v24, s8, v24
	v_mul_f32_e32 v10, 0x42000000, v21
	v_mul_f32_e32 v11, 0x42000000, v23
	v_cvt_pk_fp8_f32 v7, v10, v11 op_sel:[0,0,1]
	v_add_u32_e32 v8, 8, v24
	v_ashrrev_i32_e32 v9, 31, v8
	v_lshlrev_b64 v[8:9], 10, v[8:9]
	v_lshl_add_u64 v[8:9], v[4:5], 0, v[8:9]
	global_store_dwordx2 v[8:9], v[6:7], off
	ds_read2_b32 v[6:7], v2 offset0:16 offset1:24
	ds_read2_b32 v[8:9], v2 offset0:49 offset1:57
	ds_read2_b32 v[16:17], v2 offset0:148 offset1:156
	ds_read2_b32 v[18:19], v2 offset0:181 offset1:189
	v_ashrrev_i32_e32 v25, 31, v24
	v_lshlrev_b64 v[26:27], 10, v[24:25]
	v_lshl_add_u64 v[26:27], v[4:5], 0, v[26:27]
	ds_read2_b32 v[10:11], v2 offset0:82 offset1:90
	ds_read2_b32 v[12:13], v2 offset0:115 offset1:123
	global_store_dwordx2 v[26:27], v[14:15], off
	s_waitcnt lgkmcnt(5)
	v_mul_f32_e32 v6, 0x42000000, v6
	s_waitcnt lgkmcnt(4)
	v_mul_f32_e32 v8, 0x42000000, v8
	v_mov_b32_e32 v14, v3
	ds_read2_b32 v[20:21], v2 offset0:214 offset1:222
	ds_read2_b32 v[22:23], v2 offset0:247 offset1:255
	v_cvt_pk_fp8_f32 v14, v6, v8
	s_waitcnt lgkmcnt(5)
	v_mul_f32_e32 v6, 0x42000000, v16
	s_waitcnt lgkmcnt(4)
	v_mul_f32_e32 v8, 0x42000000, v18
	v_mov_b32_e32 v15, v3
	v_cvt_pk_fp8_f32 v15, v6, v8
	s_waitcnt lgkmcnt(3)
	v_mul_f32_e32 v10, 0x42000000, v10
	s_waitcnt lgkmcnt(2)
	v_mul_f32_e32 v12, 0x42000000, v12
	v_cvt_pk_fp8_f32 v14, v10, v12 op_sel:[0,0,1]
	s_waitcnt lgkmcnt(1)
	v_mul_f32_e32 v10, 0x42000000, v20
	s_waitcnt lgkmcnt(0)
	v_mul_f32_e32 v2, 0x42000000, v22
	v_cvt_pk_fp8_f32 v15, v10, v2 op_sel:[0,0,1]
	v_mul_f32_e32 v2, 0x42000000, v7
	v_mul_f32_e32 v7, 0x42000000, v9
	v_mov_b32_e32 v6, v3
	v_cvt_pk_fp8_f32 v6, v2, v7
	v_mul_f32_e32 v8, 0x42000000, v11
	v_mul_f32_e32 v9, 0x42000000, v13
	v_mul_f32_e32 v2, 0x42000000, v17
	v_cvt_pk_fp8_f32 v6, v8, v9 op_sel:[0,0,1]
	v_mul_f32_e32 v8, 0x42000000, v19
	v_mov_b32_e32 v7, v3
	v_cvt_pk_fp8_f32 v7, v2, v8
	v_mul_f32_e32 v9, 0x42000000, v21
	v_mul_f32_e32 v10, 0x42000000, v23
	v_add_u32_e32 v26, 16, v24
	v_cvt_pk_fp8_f32 v7, v9, v10 op_sel:[0,0,1]
	v_add_u32_e32 v8, 24, v24
	v_ashrrev_i32_e32 v27, 31, v26
	v_ashrrev_i32_e32 v9, 31, v8
	v_lshlrev_b64 v[26:27], 10, v[26:27]
	v_lshlrev_b64 v[8:9], 10, v[8:9]
	v_lshl_add_u64 v[26:27], v[4:5], 0, v[26:27]
	v_lshl_add_u64 v[4:5], v[4:5], 0, v[8:9]
	global_store_dwordx2 v[26:27], v[14:15], off
	global_store_dwordx2 v[4:5], v[6:7], off
	s_waitcnt lgkmcnt(0)
	s_mov_b64 s[16:17], 0
.LBB0_2362:
	s_andn2_b64 vcc, exec, s[16:17]
	s_cbranch_vccnz .LBB0_2358
	s_lshl_b32 s8, s92, 25
	s_add_i32 s8, s8, 0x2b00000
	s_and_b64 s[14:15], s[14:15], exec
	s_cselect_b32 s8, 0x3bb00000, s8
	s_add_u32 s8, s52, s8
	s_addc_u32 s33, s53, 0
	s_ashr_i32 s14, s91, 10
	s_bfe_u32 s80, s87, 0x10009
	s_and_b32 s81, s88, 0x3e0
	s_cmp_eq_u32 s80, 0
	s_movk_i32 s15, 0xc8
	s_cselect_b32 s15, s15, 0xd0
	s_add_u32 s16, s0, s15
	s_addc_u32 s17, s1, 0
	s_load_dwordx2 s[16:17], s[16:17], 0x0
	s_lshl_b32 s15, s90, 4
	s_add_i32 s76, s14, s15
	s_ashr_i32 s77, s76, 31
	s_lshl_b64 s[76:77], s[76:77], 22
	s_waitcnt lgkmcnt(0)
	s_add_u32 s76, s16, s76
	s_addc_u32 s17, s17, s77
	s_ashr_i32 s15, s14, 31
	s_lshl_b64 s[14:15], s[14:15], 21
	s_add_u32 s14, s8, s14
	s_addc_u32 s15, s33, s15
	s_lshl_b32 s8, s88, 1
	s_and_b32 s8, s8, 0x700
	s_lshl_b32 s33, s80, 7
	s_or_b32 s8, s8, s33
	s_and_b32 s33, s88, 0x60
	v_mov_b32_e32 v8, v1
	s_and_b32 s16, s89, 0x3c0
	s_or_b32 s8, s8, s33
	s_lshl_b32 s33, s81, 2
	v_ashrrev_i32_e32 v9, 5, v8
	v_add_u32_e32 v4, s16, v9
	s_add_u32 s76, s76, s33
	v_lshlrev_b32_e32 v2, 2, v8
	s_addc_u32 s77, s17, 0
	v_and_b32_e32 v2, 0x7c, v2
	v_ashrrev_i32_e32 v5, 31, v4
	v_lshl_add_u64 v[6:7], s[76:77], 0, v[2:3]
	v_lshlrev_b64 v[4:5], 12, v[4:5]
	v_lshl_add_u64 v[4:5], v[6:7], 0, v[4:5]
	v_add_co_u32_e32 v6, vcc, s26, v4
	global_load_dword v10, v[4:5], off nt
	s_nop 0
	v_addc_co_u32_e32 v7, vcc, 0, v5, vcc
	global_load_dword v11, v[6:7], off nt
	v_add_co_u32_e32 v6, vcc, s27, v4
	s_add_u32 s14, s14, s16
	s_nop 0
	v_addc_co_u32_e32 v7, vcc, 0, v5, vcc
	global_load_dword v12, v[6:7], off nt
	v_add_co_u32_e32 v6, vcc, s28, v4
	s_addc_u32 s15, s15, 0
	s_nop 0
	v_addc_co_u32_e32 v7, vcc, 0, v5, vcc
	global_load_dword v13, v[6:7], off nt
	v_add_co_u32_e32 v6, vcc, s29, v4
	s_nop 1
	v_addc_co_u32_e32 v7, vcc, 0, v5, vcc
	global_load_dword v14, v[6:7], off nt
	v_add_co_u32_e32 v6, vcc, s30, v4
	s_nop 1
	v_addc_co_u32_e32 v7, vcc, 0, v5, vcc
	global_load_dword v15, v[6:7], off nt
	v_add_co_u32_e32 v6, vcc, s3, v4
	s_nop 1
	v_addc_co_u32_e32 v7, vcc, 0, v5, vcc
	global_load_dword v16, v[6:7], off nt
	v_add_co_u32_e32 v6, vcc, s31, v4
	s_nop 1
	v_addc_co_u32_e32 v7, vcc, 0, v5, vcc
	global_load_dword v17, v[6:7], off nt
	v_add_co_u32_e32 v6, vcc, s24, v4
	s_nop 1
	v_addc_co_u32_e32 v7, vcc, 0, v5, vcc
	global_load_dword v18, v[6:7], off nt
	v_add_co_u32_e32 v6, vcc, s20, v4
	s_nop 1
	v_addc_co_u32_e32 v7, vcc, 0, v5, vcc
	global_load_dword v19, v[6:7], off nt
	v_add_co_u32_e32 v6, vcc, s34, v4
	s_nop 1
	v_addc_co_u32_e32 v7, vcc, 0, v5, vcc
	global_load_dword v20, v[6:7], off nt
	v_add_co_u32_e32 v6, vcc, s35, v4
	s_nop 1
	v_addc_co_u32_e32 v7, vcc, 0, v5, vcc
	global_load_dword v21, v[6:7], off nt
	v_add_co_u32_e32 v6, vcc, s36, v4
	s_nop 1
	v_addc_co_u32_e32 v7, vcc, 0, v5, vcc
	global_load_dword v22, v[6:7], off nt
	v_add_co_u32_e32 v6, vcc, s37, v4
	s_nop 1
	v_addc_co_u32_e32 v7, vcc, 0, v5, vcc
	global_load_dword v23, v[6:7], off nt
	v_add_co_u32_e32 v6, vcc, s38, v4
	s_nop 1
	v_addc_co_u32_e32 v7, vcc, 0, v5, vcc
	global_load_dword v24, v[6:7], off nt
	v_add_co_u32_e32 v6, vcc, s39, v4
	s_nop 1
	v_addc_co_u32_e32 v7, vcc, 0, v5, vcc
	global_load_dword v25, v[6:7], off nt
	v_add_co_u32_e32 v6, vcc, s41, v4
	s_nop 1
	v_addc_co_u32_e32 v7, vcc, 0, v5, vcc
	global_load_dword v26, v[6:7], off nt
	v_add_co_u32_e32 v6, vcc, s42, v4
	s_nop 1
	v_addc_co_u32_e32 v7, vcc, 0, v5, vcc
	global_load_dword v27, v[6:7], off nt
	v_add_co_u32_e32 v6, vcc, s43, v4
	s_nop 1
	v_addc_co_u32_e32 v7, vcc, 0, v5, vcc
	global_load_dword v28, v[6:7], off nt
	v_add_co_u32_e32 v6, vcc, s45, v4
	s_nop 1
	v_addc_co_u32_e32 v7, vcc, 0, v5, vcc
	global_load_dword v29, v[6:7], off nt
	v_add_co_u32_e32 v6, vcc, s46, v4
	s_nop 1
	v_addc_co_u32_e32 v7, vcc, 0, v5, vcc
	global_load_dword v30, v[6:7], off nt
	v_add_co_u32_e32 v6, vcc, s47, v4
	s_nop 1
	v_addc_co_u32_e32 v7, vcc, 0, v5, vcc
	global_load_dword v31, v[6:7], off nt
	v_add_co_u32_e32 v6, vcc, s49, v4
	s_nop 1
	v_addc_co_u32_e32 v7, vcc, 0, v5, vcc
	global_load_dword v32, v[6:7], off nt
	v_add_co_u32_e32 v6, vcc, s57, v4
	s_nop 1
	v_addc_co_u32_e32 v7, vcc, 0, v5, vcc
	global_load_dword v33, v[6:7], off nt
	v_add_co_u32_e32 v6, vcc, s58, v4
	s_nop 1
	v_addc_co_u32_e32 v7, vcc, 0, v5, vcc
	global_load_dword v34, v[6:7], off nt
	v_add_co_u32_e32 v6, vcc, s59, v4
	s_nop 1
	v_addc_co_u32_e32 v7, vcc, 0, v5, vcc
	global_load_dword v35, v[6:7], off nt
	v_add_co_u32_e32 v6, vcc, s72, v4
	s_nop 1
	v_addc_co_u32_e32 v7, vcc, 0, v5, vcc
	global_load_dword v36, v[6:7], off nt
	v_add_co_u32_e32 v6, vcc, s73, v4
	s_nop 1
	v_addc_co_u32_e32 v7, vcc, 0, v5, vcc
	global_load_dword v37, v[6:7], off nt
	v_add_co_u32_e32 v6, vcc, s78, v4
	s_nop 1
	v_addc_co_u32_e32 v7, vcc, 0, v5, vcc
	global_load_dword v38, v[6:7], off nt
	v_add_co_u32_e32 v6, vcc, s79, v4
	s_nop 1
	v_addc_co_u32_e32 v7, vcc, 0, v5, vcc
	global_load_dword v39, v[6:7], off nt
	v_add_co_u32_e32 v6, vcc, s84, v4
	s_nop 1
	v_addc_co_u32_e32 v7, vcc, 0, v5, vcc
	v_add_co_u32_e32 v4, vcc, s85, v4
	global_load_dword v6, v[6:7], off nt
	s_nop 0
	v_addc_co_u32_e32 v5, vcc, 0, v5, vcc
	global_load_dword v4, v[4:5], off nt
	v_mul_lo_u32 v5, v9, s86
	v_add3_u32 v2, s25, v2, v5
	v_add_u32_e32 v5, 0x400, v2
	s_waitcnt vmcnt(30)
	ds_write2_b32 v2, v10, v11 offset1:66
	s_waitcnt vmcnt(28)
	ds_write2_b32 v2, v12, v13 offset0:132 offset1:198
	s_waitcnt vmcnt(26)
	ds_write2_b32 v5, v14, v15 offset0:8 offset1:74
	s_waitcnt vmcnt(24)
	ds_write2_b32 v5, v16, v17 offset0:140 offset1:206
	v_add_u32_e32 v5, 0x800, v2
	s_waitcnt vmcnt(22)
	ds_write2_b32 v5, v18, v19 offset0:16 offset1:82
	s_waitcnt vmcnt(20)
	ds_write2_b32 v5, v20, v21 offset0:148 offset1:214
	v_add_u32_e32 v5, 0xc00, v2
	s_waitcnt vmcnt(18)
	ds_write2_b32 v5, v22, v23 offset0:24 offset1:90
	s_waitcnt vmcnt(16)
	ds_write2_b32 v5, v24, v25 offset0:156 offset1:222
	v_add_u32_e32 v5, 0x1000, v2
	s_waitcnt vmcnt(14)
	ds_write2_b32 v5, v26, v27 offset0:32 offset1:98
	s_waitcnt vmcnt(12)
	ds_write2_b32 v5, v28, v29 offset0:164 offset1:230
	v_add_u32_e32 v5, 0x1400, v2
	s_waitcnt vmcnt(10)
	ds_write2_b32 v5, v30, v31 offset0:40 offset1:106
	s_waitcnt vmcnt(8)
	ds_write2_b32 v5, v32, v33 offset0:172 offset1:238
	v_add_u32_e32 v5, 0x1800, v2
	v_add_u32_e32 v2, 0x1c00, v2
	s_waitcnt vmcnt(6)
	ds_write2_b32 v5, v34, v35 offset0:48 offset1:114
	s_waitcnt vmcnt(4)
	ds_write2_b32 v5, v36, v37 offset0:180 offset1:246
	s_waitcnt vmcnt(2)
	ds_write2_b32 v2, v38, v39 offset0:56 offset1:122
	s_waitcnt vmcnt(0)
	ds_write2_b32 v2, v6, v4 offset0:188 offset1:254
	v_lshlrev_b32_e32 v2, 3, v8
	v_ashrrev_i32_e32 v24, 3, v8
	v_and_b32_e32 v2, 56, v2
	s_waitcnt lgkmcnt(0)
	v_mul_u32_u24_e32 v6, 0x84, v2
	v_lshl_add_u64 v[4:5], s[14:15], 0, v[2:3]
	v_lshlrev_b32_e32 v2, 2, v24
	v_add3_u32 v2, s25, v6, v2
	ds_read2_b32 v[6:7], v2 offset1:8
	ds_read2_b32 v[8:9], v2 offset0:33 offset1:41
	ds_read2_b32 v[16:17], v2 offset0:132 offset1:140
	ds_read2_b32 v[18:19], v2 offset0:165 offset1:173
	ds_read2_b32 v[10:11], v2 offset0:66 offset1:74
	ds_read2_b32 v[12:13], v2 offset0:99 offset1:107
	s_waitcnt lgkmcnt(5)
	v_mul_f32_e32 v6, 0x42000000, v6
	s_waitcnt lgkmcnt(4)
	v_mul_f32_e32 v8, 0x42000000, v8
	v_mov_b32_e32 v14, v3
	ds_read2_b32 v[20:21], v2 offset0:198 offset1:206
	ds_read2_b32 v[22:23], v2 offset0:231 offset1:239
	v_cvt_pk_fp8_f32 v14, v6, v8
	s_waitcnt lgkmcnt(5)
	v_mul_f32_e32 v6, 0x42000000, v16
	s_waitcnt lgkmcnt(4)
	v_mul_f32_e32 v8, 0x42000000, v18
	v_mov_b32_e32 v15, v3
	v_cvt_pk_fp8_f32 v15, v6, v8
	v_mul_f32_e32 v7, 0x42000000, v7
	v_mul_f32_e32 v8, 0x42000000, v9
	v_mov_b32_e32 v6, v3
	v_cvt_pk_fp8_f32 v6, v7, v8
	s_waitcnt lgkmcnt(3)
	v_mul_f32_e32 v10, 0x42000000, v10
	s_waitcnt lgkmcnt(2)
	v_mul_f32_e32 v12, 0x42000000, v12
	v_cvt_pk_fp8_f32 v14, v10, v12 op_sel:[0,0,1]
	s_waitcnt lgkmcnt(1)
	v_mul_f32_e32 v10, 0x42000000, v20
	s_waitcnt lgkmcnt(0)
	v_mul_f32_e32 v12, 0x42000000, v22
	v_cvt_pk_fp8_f32 v15, v10, v12 op_sel:[0,0,1]
	v_mul_f32_e32 v9, 0x42000000, v11
	v_mul_f32_e32 v10, 0x42000000, v13
	v_cvt_pk_fp8_f32 v6, v9, v10 op_sel:[0,0,1]
	v_mul_f32_e32 v8, 0x42000000, v17
	v_mul_f32_e32 v9, 0x42000000, v19
	v_mov_b32_e32 v7, v3
	v_cvt_pk_fp8_f32 v7, v8, v9
	v_add_u32_e32 v24, s8, v24
	v_mul_f32_e32 v10, 0x42000000, v21
	v_mul_f32_e32 v11, 0x42000000, v23
	v_cvt_pk_fp8_f32 v7, v10, v11 op_sel:[0,0,1]
	v_add_u32_e32 v8, 8, v24
	v_ashrrev_i32_e32 v9, 31, v8
	v_lshlrev_b64 v[8:9], 10, v[8:9]
	v_lshl_add_u64 v[8:9], v[4:5], 0, v[8:9]
	global_store_dwordx2 v[8:9], v[6:7], off
	ds_read2_b32 v[6:7], v2 offset0:16 offset1:24
	ds_read2_b32 v[8:9], v2 offset0:49 offset1:57
	ds_read2_b32 v[16:17], v2 offset0:148 offset1:156
	ds_read2_b32 v[18:19], v2 offset0:181 offset1:189
	v_ashrrev_i32_e32 v25, 31, v24
	v_lshlrev_b64 v[26:27], 10, v[24:25]
	v_lshl_add_u64 v[26:27], v[4:5], 0, v[26:27]
	ds_read2_b32 v[10:11], v2 offset0:82 offset1:90
	ds_read2_b32 v[12:13], v2 offset0:115 offset1:123
	global_store_dwordx2 v[26:27], v[14:15], off
	s_waitcnt lgkmcnt(5)
	v_mul_f32_e32 v6, 0x42000000, v6
	s_waitcnt lgkmcnt(4)
	v_mul_f32_e32 v8, 0x42000000, v8
	v_mov_b32_e32 v14, v3
	ds_read2_b32 v[20:21], v2 offset0:214 offset1:222
	ds_read2_b32 v[22:23], v2 offset0:247 offset1:255
	v_cvt_pk_fp8_f32 v14, v6, v8
	s_waitcnt lgkmcnt(5)
	v_mul_f32_e32 v6, 0x42000000, v16
	s_waitcnt lgkmcnt(4)
	v_mul_f32_e32 v8, 0x42000000, v18
	v_mov_b32_e32 v15, v3
	v_cvt_pk_fp8_f32 v15, v6, v8
	s_waitcnt lgkmcnt(3)
	v_mul_f32_e32 v10, 0x42000000, v10
	s_waitcnt lgkmcnt(2)
	v_mul_f32_e32 v12, 0x42000000, v12
	v_cvt_pk_fp8_f32 v14, v10, v12 op_sel:[0,0,1]
	s_waitcnt lgkmcnt(1)
	v_mul_f32_e32 v10, 0x42000000, v20
	s_waitcnt lgkmcnt(0)
	v_mul_f32_e32 v2, 0x42000000, v22
	v_cvt_pk_fp8_f32 v15, v10, v2 op_sel:[0,0,1]
	v_mul_f32_e32 v2, 0x42000000, v7
	v_mul_f32_e32 v7, 0x42000000, v9
	v_mov_b32_e32 v6, v3
	v_cvt_pk_fp8_f32 v6, v2, v7
	v_mul_f32_e32 v8, 0x42000000, v11
	v_mul_f32_e32 v9, 0x42000000, v13
	v_mul_f32_e32 v2, 0x42000000, v17
	v_cvt_pk_fp8_f32 v6, v8, v9 op_sel:[0,0,1]
	v_mul_f32_e32 v8, 0x42000000, v19
	v_mov_b32_e32 v7, v3
	v_cvt_pk_fp8_f32 v7, v2, v8
	v_mul_f32_e32 v9, 0x42000000, v21
	v_mul_f32_e32 v10, 0x42000000, v23
	v_add_u32_e32 v26, 16, v24
	v_cvt_pk_fp8_f32 v7, v9, v10 op_sel:[0,0,1]
	v_add_u32_e32 v8, 24, v24
	v_ashrrev_i32_e32 v27, 31, v26
	v_ashrrev_i32_e32 v9, 31, v8
	v_lshlrev_b64 v[26:27], 10, v[26:27]
	v_lshlrev_b64 v[8:9], 10, v[8:9]
	v_lshl_add_u64 v[26:27], v[4:5], 0, v[26:27]
	v_lshl_add_u64 v[4:5], v[4:5], 0, v[8:9]
	global_store_dwordx2 v[26:27], v[14:15], off
	global_store_dwordx2 v[4:5], v[6:7], off
	s_waitcnt lgkmcnt(0)
	s_branch .LBB0_2358

.LBB0_3035:
	s_cmp_ge_u32 s81, s20
	s_cbranch_scc1 .LBB0_3034
	s_cmpk_gt_i32 s81, 0x5fff
	s_cselect_b64 s[14:15], -1, 0
	s_cmp_gt_i32 s81, 0xbfff
	v_cndmask_b32_e64 v2, 0, 1, s[14:15]
	s_cselect_b64 s[14:15], -1, 0
	s_cmp_gt_i32 s81, 0x11fff
	v_cndmask_b32_e64 v4, 0, 1, s[14:15]
	s_cselect_b64 s[14:15], -1, 0
	v_readfirstlane_b32 s10, v2
	v_readfirstlane_b32 s16, v4
	s_cmp_lg_u64 s[14:15], 0
	s_addc_u32 s84, s10, s16
	s_mul_i32 s10, s84, 0xffffa000
	s_add_i32 s85, s81, s10
	s_cmp_lg_u32 s84, 3
	s_cselect_b32 s86, s84, 0
	s_cmp_eq_u32 s86, 2
	s_cselect_b64 s[14:15], -1, 0
	s_cmpk_gt_i32 s85, 0x3fff
	s_mov_b64 s[16:17], -1
	s_cbranch_scc0 .LBB0_3038
	s_lshl_b32 s10, s86, 24
	s_add_i32 s10, s10, 0x6b00000
	s_and_b64 s[16:17], s[14:15], exec
	s_cselect_b32 s10, 0x3db00000, s10
	s_add_u32 s33, s52, s10
	s_load_dwordx2 s[16:17], s[0:1], 0xd8
	s_addc_u32 s87, s53, 0
	s_add_i32 s10, s85, 0xffffc000
	s_lshr_b32 s88, s10, 9
	s_lshl_b32 s10, s84, 4
	s_add_i32 s10, s88, s10
	s_lshl_b64 s[90:91], s[10:11], 22
	s_waitcnt lgkmcnt(0)
	s_add_u32 s90, s16, s90
	s_mov_b32 s89, s11
	s_addc_u32 s91, s17, s91
	s_lshl_b64 s[88:89], s[88:89], 20
	s_add_u32 s17, s33, s88
	s_addc_u32 s16, s87, s89
	s_and_b32 s10, s82, 0x3e0
	v_mov_b32_e32 v22, v1
	s_and_b32 s87, s83, 0x3c0
	s_lshl_b32 s33, s10, 2
	v_ashrrev_i32_e32 v23, 5, v22
	v_add_u32_e32 v4, s87, v23
	s_add_u32 s88, s90, s33
	v_lshlrev_b32_e32 v2, 2, v22
	s_addc_u32 s89, s91, 0
	v_and_b32_e32 v2, 0x7c, v2
	v_ashrrev_i32_e32 v5, 31, v4
	v_lshl_add_u64 v[6:7], s[88:89], 0, v[2:3]
	v_lshlrev_b64 v[4:5], 12, v[4:5]
	v_lshl_add_u64 v[4:5], v[6:7], 0, v[4:5]
	v_add_co_u32_e32 v6, vcc, s26, v4
	s_add_u32 s88, s17, s87
	s_nop 0
	v_addc_co_u32_e32 v7, vcc, 0, v5, vcc
	v_add_co_u32_e32 v8, vcc, s27, v4
	s_addc_u32 s89, s16, 0
	s_nop 0
	v_addc_co_u32_e32 v9, vcc, 0, v5, vcc
	v_add_co_u32_e32 v10, vcc, s28, v4
	s_mov_b64 s[16:17], 0
	s_nop 0
	v_addc_co_u32_e32 v11, vcc, 0, v5, vcc
	v_add_co_u32_e32 v12, vcc, s29, v4
	s_nop 1
	v_addc_co_u32_e32 v13, vcc, 0, v5, vcc
	v_add_co_u32_e32 v14, vcc, s30, v4
	s_nop 1
	v_addc_co_u32_e32 v15, vcc, 0, v5, vcc
	v_add_co_u32_e32 v16, vcc, s31, v4
	s_nop 1
	v_addc_co_u32_e32 v17, vcc, 0, v5, vcc
	v_add_co_u32_e32 v18, vcc, s34, v4
	s_nop 1
	v_addc_co_u32_e32 v19, vcc, 0, v5, vcc
	global_load_dword v24, v[4:5], off nt
	global_load_dword v25, v[6:7], off nt
	global_load_dword v26, v[8:9], off nt
	global_load_dword v27, v[10:11], off nt
	global_load_dword v28, v[12:13], off nt
	global_load_dword v29, v[14:15], off nt
	global_load_dword v30, v[16:17], off nt
	global_load_dword v31, v[18:19], off nt
	v_add_co_u32_e32 v6, vcc, s24, v4
	s_nop 1
	v_addc_co_u32_e32 v7, vcc, 0, v5, vcc
	v_add_co_u32_e32 v8, vcc, s3, v4
	s_nop 1
	v_addc_co_u32_e32 v9, vcc, 0, v5, vcc
	v_add_co_u32_e32 v10, vcc, s35, v4
	s_nop 1
	v_addc_co_u32_e32 v11, vcc, 0, v5, vcc
	v_add_co_u32_e32 v12, vcc, s36, v4
	s_nop 1
	v_addc_co_u32_e32 v13, vcc, 0, v5, vcc
	v_add_co_u32_e32 v14, vcc, s19, v4
	s_nop 1
	v_addc_co_u32_e32 v15, vcc, 0, v5, vcc
	v_add_co_u32_e32 v16, vcc, s37, v4
	s_nop 1
	v_addc_co_u32_e32 v17, vcc, 0, v5, vcc
	v_add_co_u32_e32 v18, vcc, s38, v4
	s_nop 1
	v_addc_co_u32_e32 v19, vcc, 0, v5, vcc
	v_add_co_u32_e32 v20, vcc, s39, v4
	s_nop 1
	v_addc_co_u32_e32 v21, vcc, 0, v5, vcc
	global_load_dword v32, v[6:7], off nt
	global_load_dword v33, v[8:9], off nt
	global_load_dword v34, v[10:11], off nt
	global_load_dword v35, v[12:13], off nt
	global_load_dword v36, v[14:15], off nt
	global_load_dword v37, v[16:17], off nt
	global_load_dword v38, v[18:19], off nt
	global_load_dword v39, v[20:21], off nt
	v_add_co_u32_e32 v6, vcc, s41, v4
	s_nop 1
	v_addc_co_u32_e32 v7, vcc, 0, v5, vcc
	v_add_co_u32_e32 v8, vcc, s42, v4
	s_nop 1
	v_addc_co_u32_e32 v9, vcc, 0, v5, vcc
	v_add_co_u32_e32 v10, vcc, s43, v4
	s_nop 1
	v_addc_co_u32_e32 v11, vcc, 0, v5, vcc
	v_add_co_u32_e32 v12, vcc, s45, v4
	s_nop 1
	v_addc_co_u32_e32 v13, vcc, 0, v5, vcc
	v_add_co_u32_e32 v14, vcc, s46, v4
	s_nop 1
	v_addc_co_u32_e32 v15, vcc, 0, v5, vcc
	v_add_co_u32_e32 v16, vcc, s47, v4
	s_nop 1
	v_addc_co_u32_e32 v17, vcc, 0, v5, vcc
	v_add_co_u32_e32 v18, vcc, s50, v4
	s_nop 1
	v_addc_co_u32_e32 v19, vcc, 0, v5, vcc
	v_add_co_u32_e32 v20, vcc, s51, v4
	s_nop 1
	v_addc_co_u32_e32 v21, vcc, 0, v5, vcc
	global_load_dword v40, v[6:7], off nt
	global_load_dword v41, v[8:9], off nt
	global_load_dword v42, v[10:11], off nt
	global_load_dword v43, v[12:13], off nt
	global_load_dword v44, v[14:15], off nt
	global_load_dword v45, v[16:17], off nt
	global_load_dword v46, v[18:19], off nt
	s_nop 0
	global_load_dword v20, v[20:21], off nt
	v_add_co_u32_e32 v6, vcc, s57, v4
	s_nop 1
	v_addc_co_u32_e32 v7, vcc, 0, v5, vcc
	v_add_co_u32_e32 v8, vcc, s58, v4
	s_nop 1
	v_addc_co_u32_e32 v9, vcc, 0, v5, vcc
	v_add_co_u32_e32 v10, vcc, s59, v4
	s_nop 1
	v_addc_co_u32_e32 v11, vcc, 0, v5, vcc
	v_add_co_u32_e32 v12, vcc, s72, v4
	s_nop 1
	v_addc_co_u32_e32 v13, vcc, 0, v5, vcc
	v_add_co_u32_e32 v14, vcc, s73, v4
	s_nop 1
	v_addc_co_u32_e32 v15, vcc, 0, v5, vcc
	v_add_co_u32_e32 v16, vcc, s76, v4
	s_nop 1
	v_addc_co_u32_e32 v17, vcc, 0, v5, vcc
	v_add_co_u32_e32 v18, vcc, s77, v4
	s_nop 1
	v_addc_co_u32_e32 v19, vcc, 0, v5, vcc
	v_add_co_u32_e32 v4, vcc, s78, v4
	s_nop 1
	v_addc_co_u32_e32 v5, vcc, 0, v5, vcc
	global_load_dword v6, v[6:7], off nt
	s_nop 0
	global_load_dword v7, v[8:9], off nt
	s_nop 0
	global_load_dword v8, v[10:11], off nt
	global_load_dword v9, v[12:13], off nt
	s_nop 0
	global_load_dword v10, v[14:15], off nt
	global_load_dword v11, v[16:17], off nt
	global_load_dword v12, v[18:19], off nt
	s_nop 0
	global_load_dword v4, v[4:5], off nt
	v_mul_lo_u32 v5, v23, s79
	v_add3_u32 v2, s25, v2, v5
	v_add_u32_e32 v5, 0x400, v2
	s_waitcnt vmcnt(30)
	ds_write2_b32 v2, v24, v25 offset1:66
	s_waitcnt vmcnt(28)
	ds_write2_b32 v2, v26, v27 offset0:132 offset1:198
	s_waitcnt vmcnt(26)
	ds_write2_b32 v5, v28, v29 offset0:8 offset1:74
	s_waitcnt vmcnt(24)
	ds_write2_b32 v5, v30, v31 offset0:140 offset1:206
	v_add_u32_e32 v5, 0x800, v2
	s_waitcnt vmcnt(22)
	ds_write2_b32 v5, v32, v33 offset0:16 offset1:82
	s_waitcnt vmcnt(20)
	ds_write2_b32 v5, v34, v35 offset0:148 offset1:214
	v_add_u32_e32 v5, 0xc00, v2
	s_waitcnt vmcnt(18)
	ds_write2_b32 v5, v36, v37 offset0:24 offset1:90
	s_waitcnt vmcnt(16)
	ds_write2_b32 v5, v38, v39 offset0:156 offset1:222
	v_add_u32_e32 v5, 0x1000, v2
	s_waitcnt vmcnt(14)
	ds_write2_b32 v5, v40, v41 offset0:32 offset1:98
	s_waitcnt vmcnt(12)
	ds_write2_b32 v5, v42, v43 offset0:164 offset1:230
	v_add_u32_e32 v5, 0x1400, v2
	s_waitcnt vmcnt(10)
	ds_write2_b32 v5, v44, v45 offset0:40 offset1:106
	s_waitcnt vmcnt(8)
	ds_write2_b32 v5, v46, v20 offset0:172 offset1:238
	v_add_u32_e32 v5, 0x1800, v2
	v_add_u32_e32 v2, 0x1c00, v2
	s_waitcnt vmcnt(6)
	ds_write2_b32 v5, v6, v7 offset0:48 offset1:114
	s_waitcnt vmcnt(4)
	ds_write2_b32 v5, v8, v9 offset0:180 offset1:246
	s_waitcnt vmcnt(2)
	ds_write2_b32 v2, v10, v11 offset0:56 offset1:122
	s_waitcnt vmcnt(0)
	ds_write2_b32 v2, v12, v4 offset0:188 offset1:254
	v_lshlrev_b32_e32 v2, 3, v22
	v_ashrrev_i32_e32 v24, 3, v22
	v_and_b32_e32 v2, 56, v2
	s_waitcnt lgkmcnt(0)
	v_mul_u32_u24_e32 v4, 0x84, v2
	v_lshlrev_b32_e32 v5, 2, v24
	v_add3_u32 v28, s25, v4, v5
	ds_read2_b32 v[4:5], v28 offset1:8
	ds_read2_b32 v[6:7], v28 offset0:33 offset1:41
	ds_read2_b32 v[8:9], v28 offset0:66 offset1:74
	ds_read2_b32 v[12:13], v28 offset0:99 offset1:107
	ds_read2_b32 v[14:15], v28 offset0:132 offset1:140
	ds_read2_b32 v[16:17], v28 offset0:165 offset1:173
	v_lshl_add_u64 v[10:11], s[88:89], 0, v[2:3]
	s_waitcnt lgkmcnt(5)
	v_mul_f32_e32 v2, 0x42000000, v4
	s_waitcnt lgkmcnt(4)
	v_mul_f32_e32 v4, 0x42000000, v6
	v_mov_b32_e32 v18, v3
	ds_read2_b32 v[20:21], v28 offset0:198 offset1:206
	ds_read2_b32 v[22:23], v28 offset0:231 offset1:239
	v_cvt_pk_fp8_f32 v18, v2, v4
	s_waitcnt lgkmcnt(3)
	v_mul_f32_e32 v2, 0x42000000, v14
	s_waitcnt lgkmcnt(2)
	v_mul_f32_e32 v4, 0x42000000, v16
	v_mov_b32_e32 v19, v3
	v_cvt_pk_fp8_f32 v19, v2, v4
	s_waitcnt lgkmcnt(1)
	v_mul_f32_e32 v2, 0x42000000, v20
	s_waitcnt lgkmcnt(0)
	v_mul_f32_e32 v4, 0x42000000, v22
	v_mul_f32_e32 v6, 0x42000000, v8
	v_mul_f32_e32 v8, 0x42000000, v12
	v_cvt_pk_fp8_f32 v19, v2, v4 op_sel:[0,0,1]
	v_mul_f32_e32 v2, 0x42000000, v5
	v_mul_f32_e32 v5, 0x42000000, v7
	v_mov_b32_e32 v4, v3
	v_cvt_pk_fp8_f32 v18, v6, v8 op_sel:[0,0,1]
	v_cvt_pk_fp8_f32 v4, v2, v5
	v_mul_f32_e32 v2, 0x42000000, v15
	v_mul_f32_e32 v8, 0x42000000, v17
	v_mov_b32_e32 v5, v3
	v_cvt_pk_fp8_f32 v5, v2, v8
	v_mul_f32_e32 v6, 0x42000000, v9
	v_mul_f32_e32 v7, 0x42000000, v13
	v_add_u32_e32 v24, s10, v24
	v_cvt_pk_fp8_f32 v4, v6, v7 op_sel:[0,0,1]
	v_mul_f32_e32 v2, 0x42000000, v21
	v_mul_f32_e32 v6, 0x42000000, v23
	v_ashrrev_i32_e32 v25, 31, v24
	v_cvt_pk_fp8_f32 v5, v2, v6 op_sel:[0,0,1]
	v_add_u32_e32 v6, 8, v24
	v_lshlrev_b64 v[26:27], 10, v[24:25]
	v_ashrrev_i32_e32 v7, 31, v6
	v_lshl_add_u64 v[26:27], v[10:11], 0, v[26:27]
	v_lshlrev_b64 v[6:7], 10, v[6:7]
	global_store_dwordx2 v[26:27], v[18:19], off
	v_lshl_add_u64 v[6:7], v[10:11], 0, v[6:7]
	ds_read2_b32 v[8:9], v28 offset0:16 offset1:24
	ds_read2_b32 v[12:13], v28 offset0:49 offset1:57
	ds_read2_b32 v[14:15], v28 offset0:82 offset1:90
	global_store_dwordx2 v[6:7], v[4:5], off
	ds_read2_b32 v[4:5], v28 offset0:115 offset1:123
	ds_read2_b32 v[6:7], v28 offset0:148 offset1:156
	ds_read2_b32 v[16:17], v28 offset0:181 offset1:189
	s_waitcnt lgkmcnt(5)
	v_mul_f32_e32 v2, 0x42000000, v8
	s_waitcnt lgkmcnt(4)
	v_mul_f32_e32 v8, 0x42000000, v12
	v_mov_b32_e32 v18, v3
	ds_read2_b32 v[20:21], v28 offset0:214 offset1:222
	ds_read2_b32 v[22:23], v28 offset0:247 offset1:255
	v_cvt_pk_fp8_f32 v18, v2, v8
	s_waitcnt lgkmcnt(3)
	v_mul_f32_e32 v2, 0x42000000, v6
	s_waitcnt lgkmcnt(2)
	v_mul_f32_e32 v6, 0x42000000, v16
	v_mov_b32_e32 v19, v3
	v_cvt_pk_fp8_f32 v19, v2, v6
	v_mul_f32_e32 v12, 0x42000000, v14
	v_mul_f32_e32 v4, 0x42000000, v4
	v_cvt_pk_fp8_f32 v18, v12, v4 op_sel:[0,0,1]
	s_waitcnt lgkmcnt(1)
	v_mul_f32_e32 v2, 0x42000000, v20
	s_waitcnt lgkmcnt(0)
	v_mul_f32_e32 v4, 0x42000000, v22
	v_cvt_pk_fp8_f32 v19, v2, v4 op_sel:[0,0,1]
	v_mul_f32_e32 v2, 0x42000000, v9
	v_mul_f32_e32 v6, 0x42000000, v13
	v_mov_b32_e32 v4, v3
	v_mul_f32_e32 v9, 0x42000000, v5
	v_cvt_pk_fp8_f32 v4, v2, v6
	v_mul_f32_e32 v2, 0x42000000, v7
	v_mul_f32_e32 v6, 0x42000000, v17
	v_mov_b32_e32 v5, v3
	v_cvt_pk_fp8_f32 v5, v2, v6
	v_mul_f32_e32 v8, 0x42000000, v15
	v_mul_f32_e32 v2, 0x42000000, v21
	v_mul_f32_e32 v6, 0x42000000, v23
	v_add_u32_e32 v26, 16, v24
	v_cvt_pk_fp8_f32 v4, v8, v9 op_sel:[0,0,1]
	v_cvt_pk_fp8_f32 v5, v2, v6 op_sel:[0,0,1]
	v_add_u32_e32 v6, 24, v24
	v_ashrrev_i32_e32 v27, 31, v26
	v_ashrrev_i32_e32 v7, 31, v6
	v_lshlrev_b64 v[26:27], 10, v[26:27]
	v_lshlrev_b64 v[6:7], 10, v[6:7]
	v_lshl_add_u64 v[26:27], v[10:11], 0, v[26:27]
	v_lshl_add_u64 v[6:7], v[10:11], 0, v[6:7]
	global_store_dwordx2 v[26:27], v[18:19], off
	global_store_dwordx2 v[6:7], v[4:5], off
	s_waitcnt lgkmcnt(0)
.LBB0_3038:
	s_andn2_b64 vcc, exec, s[16:17]
	s_cbranch_vccnz .LBB0_3034
	s_lshl_b32 s10, s86, 25
	s_add_i32 s10, s10, 0x2b00000
	s_and_b64 s[14:15], s[14:15], exec
	s_cselect_b32 s10, 0x3bb00000, s10
	s_add_u32 s10, s52, s10
	s_addc_u32 s33, s53, 0
	s_ashr_i32 s14, s85, 10
	s_bfe_u32 s86, s81, 0x10009
	s_and_b32 s87, s82, 0x3e0
	s_cmp_eq_u32 s86, 0
	s_cselect_b32 s15, s80, 0xd0
	s_add_u32 s16, s0, s15
	s_addc_u32 s17, s1, 0
	s_load_dwordx2 s[16:17], s[16:17], 0x0
	s_lshl_b32 s15, s84, 4
	s_add_i32 s84, s14, s15
	s_ashr_i32 s85, s84, 31
	s_lshl_b64 s[84:85], s[84:85], 22
	s_waitcnt lgkmcnt(0)
	s_add_u32 s84, s16, s84
	s_addc_u32 s85, s17, s85
	s_ashr_i32 s15, s14, 31
	s_lshl_b64 s[16:17], s[14:15], 21
	s_add_u32 s15, s10, s16
	s_addc_u32 s14, s33, s17
	s_lshl_b32 s10, s82, 1
	s_and_b32 s10, s10, 0x700
	s_lshl_b32 s17, s86, 7
	s_or_b32 s10, s10, s17
	s_and_b32 s17, s82, 0x60
	v_mov_b32_e32 v22, v1
	s_and_b32 s16, s83, 0x3c0
	s_or_b32 s10, s10, s17
	s_lshl_b32 s17, s87, 2
	v_ashrrev_i32_e32 v23, 5, v22
	v_add_u32_e32 v4, s16, v23
	s_add_u32 s84, s84, s17
	v_lshlrev_b32_e32 v2, 2, v22
	s_addc_u32 s85, s85, 0
	v_and_b32_e32 v2, 0x7c, v2
	v_ashrrev_i32_e32 v5, 31, v4
	v_lshl_add_u64 v[6:7], s[84:85], 0, v[2:3]
	v_lshlrev_b64 v[4:5], 12, v[4:5]
	v_lshl_add_u64 v[4:5], v[6:7], 0, v[4:5]
	v_add_co_u32_e32 v6, vcc, s26, v4
	s_add_u32 s16, s15, s16
	s_nop 0
	v_addc_co_u32_e32 v7, vcc, 0, v5, vcc
	v_add_co_u32_e32 v8, vcc, s27, v4
	s_addc_u32 s17, s14, 0
	s_nop 0
	v_addc_co_u32_e32 v9, vcc, 0, v5, vcc
	v_add_co_u32_e32 v10, vcc, s28, v4
	s_nop 1
	v_addc_co_u32_e32 v11, vcc, 0, v5, vcc
	v_add_co_u32_e32 v12, vcc, s29, v4
	s_nop 1
	v_addc_co_u32_e32 v13, vcc, 0, v5, vcc
	v_add_co_u32_e32 v14, vcc, s30, v4
	s_nop 1
	v_addc_co_u32_e32 v15, vcc, 0, v5, vcc
	v_add_co_u32_e32 v16, vcc, s31, v4
	s_nop 1
	v_addc_co_u32_e32 v17, vcc, 0, v5, vcc
	v_add_co_u32_e32 v18, vcc, s34, v4
	s_nop 1
	v_addc_co_u32_e32 v19, vcc, 0, v5, vcc
	global_load_dword v24, v[4:5], off nt
	global_load_dword v25, v[6:7], off nt
	global_load_dword v26, v[8:9], off nt
	global_load_dword v27, v[10:11], off nt
	global_load_dword v28, v[12:13], off nt
	global_load_dword v29, v[14:15], off nt
	global_load_dword v30, v[16:17], off nt
	global_load_dword v31, v[18:19], off nt
	v_add_co_u32_e32 v6, vcc, s24, v4
	s_nop 1
	v_addc_co_u32_e32 v7, vcc, 0, v5, vcc
	v_add_co_u32_e32 v8, vcc, s3, v4
	s_nop 1
	v_addc_co_u32_e32 v9, vcc, 0, v5, vcc
	v_add_co_u32_e32 v10, vcc, s35, v4
	s_nop 1
	v_addc_co_u32_e32 v11, vcc, 0, v5, vcc
	v_add_co_u32_e32 v12, vcc, s36, v4
	s_nop 1
	v_addc_co_u32_e32 v13, vcc, 0, v5, vcc
	v_add_co_u32_e32 v14, vcc, s19, v4
	s_nop 1
	v_addc_co_u32_e32 v15, vcc, 0, v5, vcc
	v_add_co_u32_e32 v16, vcc, s37, v4
	s_nop 1
	v_addc_co_u32_e32 v17, vcc, 0, v5, vcc
	v_add_co_u32_e32 v18, vcc, s38, v4
	s_nop 1
	v_addc_co_u32_e32 v19, vcc, 0, v5, vcc
	v_add_co_u32_e32 v20, vcc, s39, v4
	s_nop 1
	v_addc_co_u32_e32 v21, vcc, 0, v5, vcc
	global_load_dword v32, v[6:7], off nt
	global_load_dword v33, v[8:9], off nt
	global_load_dword v34, v[10:11], off nt
	global_load_dword v35, v[12:13], off nt
	global_load_dword v36, v[14:15], off nt
	global_load_dword v37, v[16:17], off nt
	global_load_dword v38, v[18:19], off nt
	global_load_dword v39, v[20:21], off nt
	v_add_co_u32_e32 v6, vcc, s41, v4
	s_nop 1
	v_addc_co_u32_e32 v7, vcc, 0, v5, vcc
	v_add_co_u32_e32 v8, vcc, s42, v4
	s_nop 1
	v_addc_co_u32_e32 v9, vcc, 0, v5, vcc
	v_add_co_u32_e32 v10, vcc, s43, v4
	s_nop 1
	v_addc_co_u32_e32 v11, vcc, 0, v5, vcc
	v_add_co_u32_e32 v12, vcc, s45, v4
	s_nop 1
	v_addc_co_u32_e32 v13, vcc, 0, v5, vcc
	v_add_co_u32_e32 v14, vcc, s46, v4
	s_nop 1
	v_addc_co_u32_e32 v15, vcc, 0, v5, vcc
	v_add_co_u32_e32 v16, vcc, s47, v4
	s_nop 1
	v_addc_co_u32_e32 v17, vcc, 0, v5, vcc
	v_add_co_u32_e32 v18, vcc, s50, v4
	s_nop 1
	v_addc_co_u32_e32 v19, vcc, 0, v5, vcc
	v_add_co_u32_e32 v20, vcc, s51, v4
	s_nop 1
	v_addc_co_u32_e32 v21, vcc, 0, v5, vcc
	global_load_dword v40, v[6:7], off nt
	global_load_dword v41, v[8:9], off nt
	global_load_dword v42, v[10:11], off nt
	global_load_dword v43, v[12:13], off nt
	global_load_dword v44, v[14:15], off nt
	global_load_dword v45, v[16:17], off nt
	global_load_dword v46, v[18:19], off nt
	s_nop 0
	global_load_dword v20, v[20:21], off nt
	v_add_co_u32_e32 v6, vcc, s57, v4
	s_nop 1
	v_addc_co_u32_e32 v7, vcc, 0, v5, vcc
	v_add_co_u32_e32 v8, vcc, s58, v4
	s_nop 1
	v_addc_co_u32_e32 v9, vcc, 0, v5, vcc
	v_add_co_u32_e32 v10, vcc, s59, v4
	s_nop 1
	v_addc_co_u32_e32 v11, vcc, 0, v5, vcc
	v_add_co_u32_e32 v12, vcc, s72, v4
	s_nop 1
	v_addc_co_u32_e32 v13, vcc, 0, v5, vcc
	v_add_co_u32_e32 v14, vcc, s73, v4
	s_nop 1
	v_addc_co_u32_e32 v15, vcc, 0, v5, vcc
	v_add_co_u32_e32 v16, vcc, s76, v4
	s_nop 1
	v_addc_co_u32_e32 v17, vcc, 0, v5, vcc
	v_add_co_u32_e32 v18, vcc, s77, v4
	s_nop 1
	v_addc_co_u32_e32 v19, vcc, 0, v5, vcc
	v_add_co_u32_e32 v4, vcc, s78, v4
	s_nop 1
	v_addc_co_u32_e32 v5, vcc, 0, v5, vcc
	global_load_dword v6, v[6:7], off nt
	s_nop 0
	global_load_dword v7, v[8:9], off nt
	s_nop 0
	global_load_dword v8, v[10:11], off nt
	global_load_dword v9, v[12:13], off nt
	s_nop 0
	global_load_dword v10, v[14:15], off nt
	global_load_dword v11, v[16:17], off nt
	global_load_dword v12, v[18:19], off nt
	s_nop 0
	global_load_dword v4, v[4:5], off nt
	v_mul_lo_u32 v5, v23, s79
	v_add3_u32 v2, s25, v2, v5
	v_add_u32_e32 v5, 0x400, v2
	s_waitcnt vmcnt(30)
	ds_write2_b32 v2, v24, v25 offset1:66
	s_waitcnt vmcnt(28)
	ds_write2_b32 v2, v26, v27 offset0:132 offset1:198
	s_waitcnt vmcnt(26)
	ds_write2_b32 v5, v28, v29 offset0:8 offset1:74
	s_waitcnt vmcnt(24)
	ds_write2_b32 v5, v30, v31 offset0:140 offset1:206
	v_add_u32_e32 v5, 0x800, v2
	s_waitcnt vmcnt(22)
	ds_write2_b32 v5, v32, v33 offset0:16 offset1:82
	s_waitcnt vmcnt(20)
	ds_write2_b32 v5, v34, v35 offset0:148 offset1:214
	v_add_u32_e32 v5, 0xc00, v2
	s_waitcnt vmcnt(18)
	ds_write2_b32 v5, v36, v37 offset0:24 offset1:90
	s_waitcnt vmcnt(16)
	ds_write2_b32 v5, v38, v39 offset0:156 offset1:222
	v_add_u32_e32 v5, 0x1000, v2
	s_waitcnt vmcnt(14)
	ds_write2_b32 v5, v40, v41 offset0:32 offset1:98
	s_waitcnt vmcnt(12)
	ds_write2_b32 v5, v42, v43 offset0:164 offset1:230
	v_add_u32_e32 v5, 0x1400, v2
	s_waitcnt vmcnt(10)
	ds_write2_b32 v5, v44, v45 offset0:40 offset1:106
	s_waitcnt vmcnt(8)
	ds_write2_b32 v5, v46, v20 offset0:172 offset1:238
	v_add_u32_e32 v5, 0x1800, v2
	v_add_u32_e32 v2, 0x1c00, v2
	s_waitcnt vmcnt(6)
	ds_write2_b32 v5, v6, v7 offset0:48 offset1:114
	s_waitcnt vmcnt(4)
	ds_write2_b32 v5, v8, v9 offset0:180 offset1:246
	s_waitcnt vmcnt(2)
	ds_write2_b32 v2, v10, v11 offset0:56 offset1:122
	s_waitcnt vmcnt(0)
	ds_write2_b32 v2, v12, v4 offset0:188 offset1:254
	v_lshlrev_b32_e32 v2, 3, v22
	v_ashrrev_i32_e32 v24, 3, v22
	v_and_b32_e32 v2, 56, v2
	s_waitcnt lgkmcnt(0)
	v_mul_u32_u24_e32 v4, 0x84, v2
	v_lshlrev_b32_e32 v5, 2, v24
	v_add3_u32 v28, s25, v4, v5
	ds_read2_b32 v[4:5], v28 offset1:8
	ds_read2_b32 v[6:7], v28 offset0:33 offset1:41
	ds_read2_b32 v[8:9], v28 offset0:66 offset1:74
	ds_read2_b32 v[12:13], v28 offset0:99 offset1:107
	ds_read2_b32 v[14:15], v28 offset0:132 offset1:140
	ds_read2_b32 v[16:17], v28 offset0:165 offset1:173
	v_lshl_add_u64 v[10:11], s[16:17], 0, v[2:3]
	s_waitcnt lgkmcnt(5)
	v_mul_f32_e32 v2, 0x42000000, v4
	s_waitcnt lgkmcnt(4)
	v_mul_f32_e32 v4, 0x42000000, v6
	v_mov_b32_e32 v18, v3
	ds_read2_b32 v[20:21], v28 offset0:198 offset1:206
	ds_read2_b32 v[22:23], v28 offset0:231 offset1:239
	v_cvt_pk_fp8_f32 v18, v2, v4
	s_waitcnt lgkmcnt(3)
	v_mul_f32_e32 v2, 0x42000000, v14
	s_waitcnt lgkmcnt(2)
	v_mul_f32_e32 v4, 0x42000000, v16
	v_mov_b32_e32 v19, v3
	v_cvt_pk_fp8_f32 v19, v2, v4
	s_waitcnt lgkmcnt(1)
	v_mul_f32_e32 v2, 0x42000000, v20
	s_waitcnt lgkmcnt(0)
	v_mul_f32_e32 v4, 0x42000000, v22
	v_mul_f32_e32 v6, 0x42000000, v8
	v_mul_f32_e32 v8, 0x42000000, v12
	v_cvt_pk_fp8_f32 v19, v2, v4 op_sel:[0,0,1]
	v_mul_f32_e32 v2, 0x42000000, v5
	v_mul_f32_e32 v5, 0x42000000, v7
	v_mov_b32_e32 v4, v3
	v_cvt_pk_fp8_f32 v18, v6, v8 op_sel:[0,0,1]
	v_cvt_pk_fp8_f32 v4, v2, v5
	v_mul_f32_e32 v2, 0x42000000, v15
	v_mul_f32_e32 v8, 0x42000000, v17
	v_mov_b32_e32 v5, v3
	v_cvt_pk_fp8_f32 v5, v2, v8
	v_mul_f32_e32 v6, 0x42000000, v9
	v_mul_f32_e32 v7, 0x42000000, v13
	v_add_u32_e32 v24, s10, v24
	v_cvt_pk_fp8_f32 v4, v6, v7 op_sel:[0,0,1]
	v_mul_f32_e32 v2, 0x42000000, v21
	v_mul_f32_e32 v6, 0x42000000, v23
	v_ashrrev_i32_e32 v25, 31, v24
	v_cvt_pk_fp8_f32 v5, v2, v6 op_sel:[0,0,1]
	v_add_u32_e32 v6, 8, v24
	v_lshlrev_b64 v[26:27], 10, v[24:25]
	v_ashrrev_i32_e32 v7, 31, v6
	v_lshl_add_u64 v[26:27], v[10:11], 0, v[26:27]
	v_lshlrev_b64 v[6:7], 10, v[6:7]
	global_store_dwordx2 v[26:27], v[18:19], off
	v_lshl_add_u64 v[6:7], v[10:11], 0, v[6:7]
	ds_read2_b32 v[8:9], v28 offset0:16 offset1:24
	ds_read2_b32 v[12:13], v28 offset0:49 offset1:57
	ds_read2_b32 v[14:15], v28 offset0:82 offset1:90
	global_store_dwordx2 v[6:7], v[4:5], off
	ds_read2_b32 v[4:5], v28 offset0:115 offset1:123
	ds_read2_b32 v[6:7], v28 offset0:148 offset1:156
	ds_read2_b32 v[16:17], v28 offset0:181 offset1:189
	s_waitcnt lgkmcnt(5)
	v_mul_f32_e32 v2, 0x42000000, v8
	s_waitcnt lgkmcnt(4)
	v_mul_f32_e32 v8, 0x42000000, v12
	v_mov_b32_e32 v18, v3
	ds_read2_b32 v[20:21], v28 offset0:214 offset1:222
	ds_read2_b32 v[22:23], v28 offset0:247 offset1:255
	v_cvt_pk_fp8_f32 v18, v2, v8
	s_waitcnt lgkmcnt(3)
	v_mul_f32_e32 v2, 0x42000000, v6
	s_waitcnt lgkmcnt(2)
	v_mul_f32_e32 v6, 0x42000000, v16
	v_mov_b32_e32 v19, v3
	v_cvt_pk_fp8_f32 v19, v2, v6
	v_mul_f32_e32 v12, 0x42000000, v14
	v_mul_f32_e32 v4, 0x42000000, v4
	v_cvt_pk_fp8_f32 v18, v12, v4 op_sel:[0,0,1]
	s_waitcnt lgkmcnt(1)
	v_mul_f32_e32 v2, 0x42000000, v20
	s_waitcnt lgkmcnt(0)
	v_mul_f32_e32 v4, 0x42000000, v22
	v_cvt_pk_fp8_f32 v19, v2, v4 op_sel:[0,0,1]
	v_mul_f32_e32 v2, 0x42000000, v9
	v_mul_f32_e32 v6, 0x42000000, v13
	v_mov_b32_e32 v4, v3
	v_mul_f32_e32 v9, 0x42000000, v5
	v_cvt_pk_fp8_f32 v4, v2, v6
	v_mul_f32_e32 v2, 0x42000000, v7
	v_mul_f32_e32 v6, 0x42000000, v17
	v_mov_b32_e32 v5, v3
	v_cvt_pk_fp8_f32 v5, v2, v6
	v_mul_f32_e32 v8, 0x42000000, v15
	v_mul_f32_e32 v2, 0x42000000, v21
	v_mul_f32_e32 v6, 0x42000000, v23
	v_add_u32_e32 v26, 16, v24
	v_cvt_pk_fp8_f32 v4, v8, v9 op_sel:[0,0,1]
	v_cvt_pk_fp8_f32 v5, v2, v6 op_sel:[0,0,1]
	v_add_u32_e32 v6, 24, v24
	v_ashrrev_i32_e32 v27, 31, v26
	v_ashrrev_i32_e32 v7, 31, v6
	v_lshlrev_b64 v[26:27], 10, v[26:27]
	v_lshlrev_b64 v[6:7], 10, v[6:7]
	v_lshl_add_u64 v[26:27], v[10:11], 0, v[26:27]
	v_lshl_add_u64 v[6:7], v[10:11], 0, v[6:7]
	global_store_dwordx2 v[26:27], v[18:19], off
	global_store_dwordx2 v[6:7], v[4:5], off
	s_waitcnt lgkmcnt(0)
	s_branch .LBB0_3034
